# v95 + K-loop load-segment leading SALU (DMA bases, first M0 write) issued in the previous MFMA segment's shadow
# baseline (speedup 1.0000x reference)
.LBB0_266:
	s_xor_b64 s[2:3], s[2:3], -1
	s_mov_b32 s34, s74
	s_add_i32 s74, s74, 1
	s_cmp_lt_u32 s34, 5
	s_mov_b64 s[4:5], s[10:11]
	s_mov_b32 s10, s75
	s_cselect_b64 s[14:15], -1, 0
	s_add_i32 s75, s74, s16
	s_mov_b64 s[12:13], s[8:9]
	s_and_b64 s[8:9], s[14:15], exec
	s_cselect_b32 s8, s75, s10
	s_cselect_b32 s10, s6, s6
	s_ashr_i32 s11, s10, 31
	s_lshl_b64 s[10:11], s[10:11], 19
	s_add_u32 s10, s80, s10
	s_addc_u32 s11, s81, s11
	s_and_b64 s[44:45], s[14:15], exec
	s_cselect_b32 s44, s11, s5
	s_cselect_b32 s45, s10, s4
	s_ashr_i32 s9, s8, 31
	s_lshl_b64 s[8:9], s[8:9], 19
	v_readlane_b32 s47, v255, 14
	s_add_u32 s8, s47, s8
	v_readlane_b32 s47, v255, 15
	s_addc_u32 s9, s47, s9
	s_and_b64 s[14:15], s[14:15], exec
	s_cselect_b32 s47, s9, s13
	s_cselect_b32 s55, s8, s12
	s_add_u32 s4, s4, 0x40080
	s_addc_u32 s5, s5, 0
	s_add_u32 s78, s12, 0x100
	s_addc_u32 s79, s13, 0
	s_mov_b32 s85, -2
	s_waitcnt lgkmcnt(0)
	s_add_i32 s86, 0, 0x10000
	v_add_u32_e32 v0, s86, v150
	v_add_u32_e32 v189, 0x10000, v150
	ds_read_b128 v[142:145], v0
	ds_read_b128 v[146:149], v0 offset:1024
	ds_read_b128 v[152:155], v0 offset:2048
	ds_read_b128 v[156:159], v0 offset:3072
	s_add_u32 s12, s4, 0xfffc0080
	s_addc_u32 s13, s5, -1
	s_cmp_eq_u32 s85, 12
	s_cselect_b32 s15, s44, s13
	s_cselect_b32 s14, s45, s12
	s_cselect_b32 s13, s47, s79
	s_cselect_b32 s12, s55, s78
	s_add_i32 m0, s7, 0xc000
	ds_read_b128 v[160:163], v151
	ds_read_b128 v[164:167], v151 offset:1024
	ds_read_b128 v[168:171], v151 offset:2048
	ds_read_b128 v[172:175], v151 offset:3072
	ds_read_b128 v[176:179], v151 offset:4096
	ds_read_b128 v[180:183], v151 offset:5120
	ds_read_b128 v[184:187], v151 offset:6144
	global_load_lds_dwordx4 v138, s[4:5]
	s_add_i32 m0, s7, 0xe000
	ds_read_b128 v[190:193], v151 offset:7168
	global_load_lds_dwordx4 v140, s[4:5]
	s_waitcnt lgkmcnt(8)
	s_barrier
	s_waitcnt lgkmcnt(0)
	v_mfma_f32_16x16x32_bf16 v[126:129], v[142:145], v[160:163], 0
	v_mfma_f32_16x16x32_bf16 v[122:125], v[152:155], v[160:163], 0
	v_mfma_f32_16x16x32_bf16 v[110:113], v[142:145], v[168:171], 0
	v_mfma_f32_16x16x32_bf16 v[106:109], v[152:155], v[168:171], 0
	v_mfma_f32_16x16x32_bf16 v[94:97], v[142:145], v[176:179], 0
	v_mfma_f32_16x16x32_bf16 v[90:93], v[152:155], v[176:179], 0
	v_mfma_f32_16x16x32_bf16 v[78:81], v[142:145], v[184:187], 0
	v_mfma_f32_16x16x32_bf16 v[74:77], v[152:155], v[184:187], 0
	v_mfma_f32_16x16x32_bf16 v[126:129], v[146:149], v[164:167], v[126:129]
	s_add_i32 m0, s22, 0x10000
	v_mfma_f32_16x16x32_bf16 v[122:125], v[156:159], v[164:167], v[122:125]
	v_mfma_f32_16x16x32_bf16 v[110:113], v[146:149], v[172:175], v[110:113]
	v_mfma_f32_16x16x32_bf16 v[106:109], v[156:159], v[172:175], v[106:109]
	v_mfma_f32_16x16x32_bf16 v[94:97], v[146:149], v[180:183], v[94:97]
	v_mfma_f32_16x16x32_bf16 v[90:93], v[156:159], v[180:183], v[90:93]
	v_mfma_f32_16x16x32_bf16 v[78:81], v[146:149], v[190:193], v[78:81]
	v_mfma_f32_16x16x32_bf16 v[74:77], v[156:159], v[190:193], v[74:77]
	s_barrier
	ds_read_b128 v[194:197], v189 offset:16384
	ds_read_b128 v[198:201], v189 offset:17408
	ds_read_b128 v[202:205], v189 offset:18432
	global_load_lds_dwordx4 v134, s[12:13]
	s_add_i32 m0, s22, 0x12000
	ds_read_b128 v[206:209], v189 offset:19456
	global_load_lds_dwordx4 v130, s[12:13]
	s_barrier
	s_waitcnt lgkmcnt(0)
	v_mfma_f32_16x16x32_bf16 v[118:121], v[194:197], v[160:163], 0
	v_mfma_f32_16x16x32_bf16 v[114:117], v[202:205], v[160:163], 0
	v_mfma_f32_16x16x32_bf16 v[102:105], v[194:197], v[168:171], 0
	v_mfma_f32_16x16x32_bf16 v[98:101], v[202:205], v[168:171], 0
	v_mfma_f32_16x16x32_bf16 v[86:89], v[194:197], v[176:179], 0
	v_mfma_f32_16x16x32_bf16 v[82:85], v[202:205], v[176:179], 0
	v_mfma_f32_16x16x32_bf16 v[70:73], v[194:197], v[184:187], 0
	v_mfma_f32_16x16x32_bf16 v[66:69], v[202:205], v[184:187], 0
	v_mfma_f32_16x16x32_bf16 v[118:121], v[198:201], v[164:167], v[118:121]
	v_mfma_f32_16x16x32_bf16 v[114:117], v[206:209], v[164:167], v[114:117]
	v_mfma_f32_16x16x32_bf16 v[102:105], v[198:201], v[172:175], v[102:105]
	v_mfma_f32_16x16x32_bf16 v[98:101], v[206:209], v[172:175], v[98:101]
	v_mfma_f32_16x16x32_bf16 v[86:89], v[198:201], v[180:183], v[86:89]
	v_mfma_f32_16x16x32_bf16 v[82:85], v[206:209], v[180:183], v[82:85]
	v_mfma_f32_16x16x32_bf16 v[70:73], v[198:201], v[190:193], v[70:73]
	v_mfma_f32_16x16x32_bf16 v[66:69], v[206:209], v[190:193], v[66:69]
	s_mov_b32 m0, s7
	s_mov_b64 s[100:101], s[14:15]
	s_barrier
	ds_read_b128 v[160:163], v151 offset:16384
	ds_read_b128 v[164:167], v151 offset:17408
	ds_read_b128 v[168:171], v151 offset:18432
	ds_read_b128 v[172:175], v151 offset:19456
	ds_read_b128 v[176:179], v151 offset:20480
	ds_read_b128 v[180:183], v151 offset:21504
	ds_read_b128 v[184:187], v151 offset:22528
	global_load_lds_dwordx4 v136, s[100:101]
	s_mov_b32 m0, s23
	ds_read_b128 v[190:193], v151 offset:23552
	global_load_lds_dwordx4 v132, s[100:101]
	s_waitcnt vmcnt(10)
	s_barrier
	s_waitcnt lgkmcnt(0)
	v_mfma_f32_16x16x32_bf16 v[62:65], v[142:145], v[160:163], 0
	v_mfma_f32_16x16x32_bf16 v[58:61], v[152:155], v[160:163], 0
	v_mfma_f32_16x16x32_bf16 v[46:49], v[142:145], v[168:171], 0
	v_mfma_f32_16x16x32_bf16 v[42:45], v[152:155], v[168:171], 0
	v_mfma_f32_16x16x32_bf16 v[30:33], v[142:145], v[176:179], 0
	v_mfma_f32_16x16x32_bf16 v[26:29], v[152:155], v[176:179], 0
	v_mfma_f32_16x16x32_bf16 v[14:17], v[142:145], v[184:187], 0
	v_mfma_f32_16x16x32_bf16 v[10:13], v[152:155], v[184:187], 0
	v_mfma_f32_16x16x32_bf16 v[62:65], v[146:149], v[164:167], v[62:65]
	s_add_u32 s86, s12, 0x40000
	s_addc_u32 s87, s13, 0
	v_mfma_f32_16x16x32_bf16 v[58:61], v[156:159], v[164:167], v[58:61]
	s_add_i32 m0, s22, 0x14000
	v_mfma_f32_16x16x32_bf16 v[46:49], v[146:149], v[172:175], v[46:49]
	v_mfma_f32_16x16x32_bf16 v[42:45], v[156:159], v[172:175], v[42:45]
	v_mfma_f32_16x16x32_bf16 v[30:33], v[146:149], v[180:183], v[30:33]
	v_mfma_f32_16x16x32_bf16 v[26:29], v[156:159], v[180:183], v[26:29]
	v_mfma_f32_16x16x32_bf16 v[14:17], v[146:149], v[190:193], v[14:17]
	v_mfma_f32_16x16x32_bf16 v[10:13], v[156:159], v[190:193], v[10:13]
	s_barrier
	s_nop 0
	global_load_lds_dwordx4 v134, s[86:87]
	s_add_i32 m0, s22, 0x16000
	s_nop 0
	global_load_lds_dwordx4 v130, s[86:87]
	ds_read_b128 v[142:145], v189 offset:32768
	ds_read_b128 v[146:149], v189 offset:33792
	ds_read_b128 v[152:155], v189 offset:34816
	ds_read_b128 v[156:159], v189 offset:35840
	s_waitcnt vmcnt(6)
	s_barrier
	v_mfma_f32_16x16x32_bf16 v[54:57], v[194:197], v[160:163], 0
	v_mfma_f32_16x16x32_bf16 v[50:53], v[202:205], v[160:163], 0
	v_mfma_f32_16x16x32_bf16 v[38:41], v[194:197], v[168:171], 0
	v_mfma_f32_16x16x32_bf16 v[34:37], v[202:205], v[168:171], 0
	v_mfma_f32_16x16x32_bf16 v[22:25], v[194:197], v[176:179], 0
	v_mfma_f32_16x16x32_bf16 v[18:21], v[202:205], v[176:179], 0
	v_mfma_f32_16x16x32_bf16 v[6:9], v[194:197], v[184:187], 0
	v_mfma_f32_16x16x32_bf16 v[2:5], v[202:205], v[184:187], 0
	v_mfma_f32_16x16x32_bf16 v[54:57], v[198:201], v[164:167], v[54:57]
	s_add_u32 s14, s14, 0x40000
	s_addc_u32 s15, s15, 0
	v_mfma_f32_16x16x32_bf16 v[50:53], v[206:209], v[164:167], v[50:53]
	s_mov_b32 m0, s28
	v_mfma_f32_16x16x32_bf16 v[38:41], v[198:201], v[172:175], v[38:41]
	v_mfma_f32_16x16x32_bf16 v[34:37], v[206:209], v[172:175], v[34:37]
	v_mfma_f32_16x16x32_bf16 v[22:25], v[198:201], v[180:183], v[22:25]
	v_mfma_f32_16x16x32_bf16 v[18:21], v[206:209], v[180:183], v[18:21]
	v_mfma_f32_16x16x32_bf16 v[6:9], v[198:201], v[190:193], v[6:9]
	v_mfma_f32_16x16x32_bf16 v[2:5], v[206:209], v[190:193], v[2:5]
	s_barrier
	ds_read_b128 v[160:163], v151 offset:32768
	ds_read_b128 v[164:167], v151 offset:33792
	ds_read_b128 v[168:171], v151 offset:34816
	ds_read_b128 v[172:175], v151 offset:35840
	ds_read_b128 v[176:179], v151 offset:36864
	ds_read_b128 v[180:183], v151 offset:37888
	ds_read_b128 v[184:187], v151 offset:38912
	global_load_lds_dwordx4 v136, s[14:15]
	s_mov_b32 m0, s29
	ds_read_b128 v[190:193], v151 offset:39936
	global_load_lds_dwordx4 v132, s[14:15]
	s_waitcnt lgkmcnt(8)
	s_barrier
	s_waitcnt lgkmcnt(0)
	v_mfma_f32_16x16x32_bf16 v[126:129], v[142:145], v[160:163], v[126:129]
	v_mfma_f32_16x16x32_bf16 v[122:125], v[152:155], v[160:163], v[122:125]
	v_mfma_f32_16x16x32_bf16 v[110:113], v[142:145], v[168:171], v[110:113]
	v_mfma_f32_16x16x32_bf16 v[106:109], v[152:155], v[168:171], v[106:109]
	v_mfma_f32_16x16x32_bf16 v[94:97], v[142:145], v[176:179], v[94:97]
	v_mfma_f32_16x16x32_bf16 v[90:93], v[152:155], v[176:179], v[90:93]
	v_mfma_f32_16x16x32_bf16 v[78:81], v[142:145], v[184:187], v[78:81]
	v_mfma_f32_16x16x32_bf16 v[74:77], v[152:155], v[184:187], v[74:77]
	v_mfma_f32_16x16x32_bf16 v[126:129], v[146:149], v[164:167], v[126:129]
	s_add_i32 m0, s22, 0x18000
	v_mfma_f32_16x16x32_bf16 v[122:125], v[156:159], v[164:167], v[122:125]
	v_mfma_f32_16x16x32_bf16 v[110:113], v[146:149], v[172:175], v[110:113]
	v_mfma_f32_16x16x32_bf16 v[106:109], v[156:159], v[172:175], v[106:109]
	v_mfma_f32_16x16x32_bf16 v[94:97], v[146:149], v[180:183], v[94:97]
	v_mfma_f32_16x16x32_bf16 v[90:93], v[156:159], v[180:183], v[90:93]
	v_mfma_f32_16x16x32_bf16 v[78:81], v[146:149], v[190:193], v[78:81]
	v_mfma_f32_16x16x32_bf16 v[74:77], v[156:159], v[190:193], v[74:77]
	s_barrier
	ds_read_b128 v[194:197], v189 offset:49152
	ds_read_b128 v[198:201], v189 offset:50176
	ds_read_b128 v[202:205], v189 offset:51200
	ds_read_b128 v[206:209], v189 offset:52224
	s_add_u32 s98, s12, s40
	s_addc_u32 s99, s13, s41
	global_load_lds_dwordx4 v134, s[98:99]
	s_add_i32 m0, s22, 0x1a000
	s_nop 0
	global_load_lds_dwordx4 v130, s[98:99]
	s_barrier
	s_waitcnt lgkmcnt(0)
	v_mfma_f32_16x16x32_bf16 v[118:121], v[194:197], v[160:163], v[118:121]
	v_mfma_f32_16x16x32_bf16 v[114:117], v[202:205], v[160:163], v[114:117]
	v_mfma_f32_16x16x32_bf16 v[102:105], v[194:197], v[168:171], v[102:105]
	v_mfma_f32_16x16x32_bf16 v[98:101], v[202:205], v[168:171], v[98:101]
	v_mfma_f32_16x16x32_bf16 v[86:89], v[194:197], v[176:179], v[86:89]
	v_mfma_f32_16x16x32_bf16 v[82:85], v[202:205], v[176:179], v[82:85]
	v_mfma_f32_16x16x32_bf16 v[70:73], v[194:197], v[184:187], v[70:73]
	v_mfma_f32_16x16x32_bf16 v[66:69], v[202:205], v[184:187], v[66:69]
	v_mfma_f32_16x16x32_bf16 v[118:121], v[198:201], v[164:167], v[118:121]
	v_mfma_f32_16x16x32_bf16 v[114:117], v[206:209], v[164:167], v[114:117]
	v_mfma_f32_16x16x32_bf16 v[102:105], v[198:201], v[172:175], v[102:105]
	v_mfma_f32_16x16x32_bf16 v[98:101], v[206:209], v[172:175], v[98:101]
	v_mfma_f32_16x16x32_bf16 v[86:89], v[198:201], v[180:183], v[86:89]
	v_mfma_f32_16x16x32_bf16 v[82:85], v[206:209], v[180:183], v[82:85]
	v_mfma_f32_16x16x32_bf16 v[70:73], v[198:201], v[190:193], v[70:73]
	v_mfma_f32_16x16x32_bf16 v[66:69], v[206:209], v[190:193], v[66:69]
	s_mov_b32 m0, s38
	s_barrier
	ds_read_b128 v[160:163], v151 offset:49152
	ds_read_b128 v[164:167], v151 offset:50176
	ds_read_b128 v[168:171], v151 offset:51200
	ds_read_b128 v[172:175], v151 offset:52224
	ds_read_b128 v[176:179], v151 offset:53248
	ds_read_b128 v[180:183], v151 offset:54272
	ds_read_b128 v[184:187], v151 offset:55296
	ds_read_b128 v[190:193], v151 offset:56320
	s_add_u32 s98, s100, s40
	s_addc_u32 s99, s101, s41
	global_load_lds_dwordx4 v136, s[98:99]
	s_mov_b32 m0, s39
	s_nop 0
	global_load_lds_dwordx4 v132, s[98:99]
	s_waitcnt vmcnt(10)
	s_barrier
	s_waitcnt lgkmcnt(0)
	v_mfma_f32_16x16x32_bf16 v[62:65], v[142:145], v[160:163], v[62:65]
	v_mfma_f32_16x16x32_bf16 v[58:61], v[152:155], v[160:163], v[58:61]
	v_mfma_f32_16x16x32_bf16 v[46:49], v[142:145], v[168:171], v[46:49]
	v_mfma_f32_16x16x32_bf16 v[42:45], v[152:155], v[168:171], v[42:45]
	v_mfma_f32_16x16x32_bf16 v[30:33], v[142:145], v[176:179], v[30:33]
	v_mfma_f32_16x16x32_bf16 v[26:29], v[152:155], v[176:179], v[26:29]
	v_mfma_f32_16x16x32_bf16 v[14:17], v[142:145], v[184:187], v[14:17]
	v_mfma_f32_16x16x32_bf16 v[10:13], v[152:155], v[184:187], v[10:13]
	v_mfma_f32_16x16x32_bf16 v[62:65], v[146:149], v[164:167], v[62:65]
	s_add_u32 s12, s12, 0x40080
	s_addc_u32 s13, s13, 0
	v_mfma_f32_16x16x32_bf16 v[58:61], v[156:159], v[164:167], v[58:61]
	s_add_i32 m0, s22, 0x1c000
	v_mfma_f32_16x16x32_bf16 v[46:49], v[146:149], v[172:175], v[46:49]
	v_mfma_f32_16x16x32_bf16 v[42:45], v[156:159], v[172:175], v[42:45]
	v_mfma_f32_16x16x32_bf16 v[30:33], v[146:149], v[180:183], v[30:33]
	v_mfma_f32_16x16x32_bf16 v[26:29], v[156:159], v[180:183], v[26:29]
	v_mfma_f32_16x16x32_bf16 v[14:17], v[146:149], v[190:193], v[14:17]
	v_mfma_f32_16x16x32_bf16 v[10:13], v[156:159], v[190:193], v[10:13]
	s_barrier
	s_nop 0
	global_load_lds_dwordx4 v134, s[12:13]
	s_add_i32 m0, s22, 0x1e000
	s_nop 0
	global_load_lds_dwordx4 v130, s[12:13]
	ds_read_b128 v[142:145], v189
	ds_read_b128 v[146:149], v189 offset:1024
	ds_read_b128 v[152:155], v189 offset:2048
	ds_read_b128 v[156:159], v189 offset:3072
	s_waitcnt vmcnt(6)
	s_barrier
	v_mfma_f32_16x16x32_bf16 v[54:57], v[194:197], v[160:163], v[54:57]
	v_mfma_f32_16x16x32_bf16 v[50:53], v[202:205], v[160:163], v[50:53]
	v_mfma_f32_16x16x32_bf16 v[38:41], v[194:197], v[168:171], v[38:41]
	v_mfma_f32_16x16x32_bf16 v[34:37], v[202:205], v[168:171], v[34:37]
	v_mfma_f32_16x16x32_bf16 v[22:25], v[194:197], v[176:179], v[22:25]
	v_mfma_f32_16x16x32_bf16 v[18:21], v[202:205], v[176:179], v[18:21]
	v_mfma_f32_16x16x32_bf16 v[6:9], v[194:197], v[184:187], v[6:9]
	v_mfma_f32_16x16x32_bf16 v[2:5], v[202:205], v[184:187], v[2:5]
	v_mfma_f32_16x16x32_bf16 v[54:57], v[198:201], v[164:167], v[54:57]
	s_add_i32 s85, s85, 2
	s_add_u32 s4, s4, 0x100
	v_mfma_f32_16x16x32_bf16 v[50:53], v[206:209], v[164:167], v[50:53]
	s_addc_u32 s5, s5, 0
	s_add_u32 s78, s78, 0x100
	v_mfma_f32_16x16x32_bf16 v[38:41], v[198:201], v[172:175], v[38:41]
	s_addc_u32 s79, s79, 0
	s_add_u32 s12, s4, 0xfffc0080
	v_mfma_f32_16x16x32_bf16 v[34:37], v[206:209], v[172:175], v[34:37]
	s_addc_u32 s13, s5, -1
	s_cmp_eq_u32 s85, 12
	v_mfma_f32_16x16x32_bf16 v[22:25], v[198:201], v[180:183], v[22:25]
	s_cselect_b32 s15, s44, s13
	s_cselect_b32 s14, s45, s12
	v_mfma_f32_16x16x32_bf16 v[18:21], v[206:209], v[180:183], v[18:21]
	s_cselect_b32 s13, s47, s79
	s_cselect_b32 s12, s55, s78
	v_mfma_f32_16x16x32_bf16 v[6:9], v[198:201], v[190:193], v[6:9]
	s_cmp_gt_u32 s85, 13
	v_mfma_f32_16x16x32_bf16 v[2:5], v[206:209], v[190:193], v[2:5]
	s_barrier
	.p2align 3
.LBB0_267:
	s_add_i32 m0, s7, 0xc000
	ds_read_b128 v[160:163], v151
	ds_read_b128 v[164:167], v151 offset:1024
	ds_read_b128 v[168:171], v151 offset:2048
	ds_read_b128 v[172:175], v151 offset:3072
	ds_read_b128 v[176:179], v151 offset:4096
	ds_read_b128 v[180:183], v151 offset:5120
	ds_read_b128 v[184:187], v151 offset:6144
	global_load_lds_dwordx4 v138, s[4:5]
	s_add_i32 m0, s7, 0xe000
	ds_read_b128 v[190:193], v151 offset:7168
	global_load_lds_dwordx4 v140, s[4:5]
	s_waitcnt lgkmcnt(8)
	s_barrier
	s_waitcnt lgkmcnt(0)
	v_mfma_f32_16x16x32_bf16 v[126:129], v[142:145], v[160:163], v[126:129]
	v_mfma_f32_16x16x32_bf16 v[122:125], v[152:155], v[160:163], v[122:125]
	v_mfma_f32_16x16x32_bf16 v[110:113], v[142:145], v[168:171], v[110:113]
	v_mfma_f32_16x16x32_bf16 v[106:109], v[152:155], v[168:171], v[106:109]
	v_mfma_f32_16x16x32_bf16 v[94:97], v[142:145], v[176:179], v[94:97]
	v_mfma_f32_16x16x32_bf16 v[90:93], v[152:155], v[176:179], v[90:93]
	v_mfma_f32_16x16x32_bf16 v[78:81], v[142:145], v[184:187], v[78:81]
	v_mfma_f32_16x16x32_bf16 v[74:77], v[152:155], v[184:187], v[74:77]
	v_mfma_f32_16x16x32_bf16 v[126:129], v[146:149], v[164:167], v[126:129]
	s_add_i32 m0, s22, 0x10000
	v_mfma_f32_16x16x32_bf16 v[122:125], v[156:159], v[164:167], v[122:125]
	v_mfma_f32_16x16x32_bf16 v[110:113], v[146:149], v[172:175], v[110:113]
	v_mfma_f32_16x16x32_bf16 v[106:109], v[156:159], v[172:175], v[106:109]
	v_mfma_f32_16x16x32_bf16 v[94:97], v[146:149], v[180:183], v[94:97]
	v_mfma_f32_16x16x32_bf16 v[90:93], v[156:159], v[180:183], v[90:93]
	v_mfma_f32_16x16x32_bf16 v[78:81], v[146:149], v[190:193], v[78:81]
	v_mfma_f32_16x16x32_bf16 v[74:77], v[156:159], v[190:193], v[74:77]
	s_barrier
	ds_read_b128 v[194:197], v189 offset:16384
	ds_read_b128 v[198:201], v189 offset:17408
	ds_read_b128 v[202:205], v189 offset:18432
	global_load_lds_dwordx4 v134, s[12:13]
	s_add_i32 m0, s22, 0x12000
	ds_read_b128 v[206:209], v189 offset:19456
	global_load_lds_dwordx4 v130, s[12:13]
	s_barrier
	s_waitcnt lgkmcnt(0)
	v_mfma_f32_16x16x32_bf16 v[118:121], v[194:197], v[160:163], v[118:121]
	v_mfma_f32_16x16x32_bf16 v[114:117], v[202:205], v[160:163], v[114:117]
	v_mfma_f32_16x16x32_bf16 v[102:105], v[194:197], v[168:171], v[102:105]
	v_mfma_f32_16x16x32_bf16 v[98:101], v[202:205], v[168:171], v[98:101]
	v_mfma_f32_16x16x32_bf16 v[86:89], v[194:197], v[176:179], v[86:89]
	v_mfma_f32_16x16x32_bf16 v[82:85], v[202:205], v[176:179], v[82:85]
	v_mfma_f32_16x16x32_bf16 v[70:73], v[194:197], v[184:187], v[70:73]
	v_mfma_f32_16x16x32_bf16 v[66:69], v[202:205], v[184:187], v[66:69]
	v_mfma_f32_16x16x32_bf16 v[118:121], v[198:201], v[164:167], v[118:121]
	v_mfma_f32_16x16x32_bf16 v[114:117], v[206:209], v[164:167], v[114:117]
	v_mfma_f32_16x16x32_bf16 v[102:105], v[198:201], v[172:175], v[102:105]
	v_mfma_f32_16x16x32_bf16 v[98:101], v[206:209], v[172:175], v[98:101]
	v_mfma_f32_16x16x32_bf16 v[86:89], v[198:201], v[180:183], v[86:89]
	v_mfma_f32_16x16x32_bf16 v[82:85], v[206:209], v[180:183], v[82:85]
	v_mfma_f32_16x16x32_bf16 v[70:73], v[198:201], v[190:193], v[70:73]
	v_mfma_f32_16x16x32_bf16 v[66:69], v[206:209], v[190:193], v[66:69]
	s_mov_b32 m0, s7
	s_mov_b64 s[100:101], s[14:15]
	s_barrier
	ds_read_b128 v[160:163], v151 offset:16384
	ds_read_b128 v[164:167], v151 offset:17408
	ds_read_b128 v[168:171], v151 offset:18432
	ds_read_b128 v[172:175], v151 offset:19456
	ds_read_b128 v[176:179], v151 offset:20480
	ds_read_b128 v[180:183], v151 offset:21504
	ds_read_b128 v[184:187], v151 offset:22528
	global_load_lds_dwordx4 v136, s[100:101]
	s_mov_b32 m0, s23
	ds_read_b128 v[190:193], v151 offset:23552
	global_load_lds_dwordx4 v132, s[100:101]
	s_waitcnt vmcnt(10)
	s_barrier
	s_waitcnt lgkmcnt(0)
	v_mfma_f32_16x16x32_bf16 v[62:65], v[142:145], v[160:163], v[62:65]
	v_mfma_f32_16x16x32_bf16 v[58:61], v[152:155], v[160:163], v[58:61]
	v_mfma_f32_16x16x32_bf16 v[46:49], v[142:145], v[168:171], v[46:49]
	v_mfma_f32_16x16x32_bf16 v[42:45], v[152:155], v[168:171], v[42:45]
	v_mfma_f32_16x16x32_bf16 v[30:33], v[142:145], v[176:179], v[30:33]
	v_mfma_f32_16x16x32_bf16 v[26:29], v[152:155], v[176:179], v[26:29]
	v_mfma_f32_16x16x32_bf16 v[14:17], v[142:145], v[184:187], v[14:17]
	v_mfma_f32_16x16x32_bf16 v[10:13], v[152:155], v[184:187], v[10:13]
	v_mfma_f32_16x16x32_bf16 v[62:65], v[146:149], v[164:167], v[62:65]
	s_add_u32 s86, s12, 0x40000
	s_addc_u32 s87, s13, 0
	v_mfma_f32_16x16x32_bf16 v[58:61], v[156:159], v[164:167], v[58:61]
	s_add_i32 m0, s22, 0x14000
	v_mfma_f32_16x16x32_bf16 v[46:49], v[146:149], v[172:175], v[46:49]
	v_mfma_f32_16x16x32_bf16 v[42:45], v[156:159], v[172:175], v[42:45]
	v_mfma_f32_16x16x32_bf16 v[30:33], v[146:149], v[180:183], v[30:33]
	v_mfma_f32_16x16x32_bf16 v[26:29], v[156:159], v[180:183], v[26:29]
	v_mfma_f32_16x16x32_bf16 v[14:17], v[146:149], v[190:193], v[14:17]
	v_mfma_f32_16x16x32_bf16 v[10:13], v[156:159], v[190:193], v[10:13]
	s_barrier
	s_nop 0
	global_load_lds_dwordx4 v134, s[86:87]
	s_add_i32 m0, s22, 0x16000
	s_nop 0
	global_load_lds_dwordx4 v130, s[86:87]
	ds_read_b128 v[142:145], v189 offset:32768
	ds_read_b128 v[146:149], v189 offset:33792
	ds_read_b128 v[152:155], v189 offset:34816
	ds_read_b128 v[156:159], v189 offset:35840
	s_waitcnt vmcnt(6)
	s_barrier
	v_mfma_f32_16x16x32_bf16 v[54:57], v[194:197], v[160:163], v[54:57]
	v_mfma_f32_16x16x32_bf16 v[50:53], v[202:205], v[160:163], v[50:53]
	v_mfma_f32_16x16x32_bf16 v[38:41], v[194:197], v[168:171], v[38:41]
	v_mfma_f32_16x16x32_bf16 v[34:37], v[202:205], v[168:171], v[34:37]
	v_mfma_f32_16x16x32_bf16 v[22:25], v[194:197], v[176:179], v[22:25]
	v_mfma_f32_16x16x32_bf16 v[18:21], v[202:205], v[176:179], v[18:21]
	v_mfma_f32_16x16x32_bf16 v[6:9], v[194:197], v[184:187], v[6:9]
	v_mfma_f32_16x16x32_bf16 v[2:5], v[202:205], v[184:187], v[2:5]
	v_mfma_f32_16x16x32_bf16 v[54:57], v[198:201], v[164:167], v[54:57]
	s_add_u32 s14, s14, 0x40000
	s_addc_u32 s15, s15, 0
	v_mfma_f32_16x16x32_bf16 v[50:53], v[206:209], v[164:167], v[50:53]
	s_mov_b32 m0, s28
	v_mfma_f32_16x16x32_bf16 v[38:41], v[198:201], v[172:175], v[38:41]
	v_mfma_f32_16x16x32_bf16 v[34:37], v[206:209], v[172:175], v[34:37]
	v_mfma_f32_16x16x32_bf16 v[22:25], v[198:201], v[180:183], v[22:25]
	v_mfma_f32_16x16x32_bf16 v[18:21], v[206:209], v[180:183], v[18:21]
	v_mfma_f32_16x16x32_bf16 v[6:9], v[198:201], v[190:193], v[6:9]
	v_mfma_f32_16x16x32_bf16 v[2:5], v[206:209], v[190:193], v[2:5]
	s_barrier
	ds_read_b128 v[160:163], v151 offset:32768
	ds_read_b128 v[164:167], v151 offset:33792
	ds_read_b128 v[168:171], v151 offset:34816
	ds_read_b128 v[172:175], v151 offset:35840
	ds_read_b128 v[176:179], v151 offset:36864
	ds_read_b128 v[180:183], v151 offset:37888
	ds_read_b128 v[184:187], v151 offset:38912
	global_load_lds_dwordx4 v136, s[14:15]
	s_mov_b32 m0, s29
	ds_read_b128 v[190:193], v151 offset:39936
	global_load_lds_dwordx4 v132, s[14:15]
	s_waitcnt lgkmcnt(8)
	s_barrier
	s_waitcnt lgkmcnt(0)
	v_mfma_f32_16x16x32_bf16 v[126:129], v[142:145], v[160:163], v[126:129]
	v_mfma_f32_16x16x32_bf16 v[122:125], v[152:155], v[160:163], v[122:125]
	v_mfma_f32_16x16x32_bf16 v[110:113], v[142:145], v[168:171], v[110:113]
	v_mfma_f32_16x16x32_bf16 v[106:109], v[152:155], v[168:171], v[106:109]
	v_mfma_f32_16x16x32_bf16 v[94:97], v[142:145], v[176:179], v[94:97]
	v_mfma_f32_16x16x32_bf16 v[90:93], v[152:155], v[176:179], v[90:93]
	v_mfma_f32_16x16x32_bf16 v[78:81], v[142:145], v[184:187], v[78:81]
	v_mfma_f32_16x16x32_bf16 v[74:77], v[152:155], v[184:187], v[74:77]
	v_mfma_f32_16x16x32_bf16 v[126:129], v[146:149], v[164:167], v[126:129]
	s_add_i32 m0, s22, 0x18000
	v_mfma_f32_16x16x32_bf16 v[122:125], v[156:159], v[164:167], v[122:125]
	v_mfma_f32_16x16x32_bf16 v[110:113], v[146:149], v[172:175], v[110:113]
	v_mfma_f32_16x16x32_bf16 v[106:109], v[156:159], v[172:175], v[106:109]
	v_mfma_f32_16x16x32_bf16 v[94:97], v[146:149], v[180:183], v[94:97]
	v_mfma_f32_16x16x32_bf16 v[90:93], v[156:159], v[180:183], v[90:93]
	v_mfma_f32_16x16x32_bf16 v[78:81], v[146:149], v[190:193], v[78:81]
	v_mfma_f32_16x16x32_bf16 v[74:77], v[156:159], v[190:193], v[74:77]
	s_barrier
	ds_read_b128 v[194:197], v189 offset:49152
	ds_read_b128 v[198:201], v189 offset:50176
	ds_read_b128 v[202:205], v189 offset:51200
	ds_read_b128 v[206:209], v189 offset:52224
	s_add_u32 s98, s12, s40
	s_addc_u32 s99, s13, s41
	global_load_lds_dwordx4 v134, s[98:99]
	s_add_i32 m0, s22, 0x1a000
	s_nop 0
	global_load_lds_dwordx4 v130, s[98:99]
	s_barrier
	s_waitcnt lgkmcnt(0)
	v_mfma_f32_16x16x32_bf16 v[118:121], v[194:197], v[160:163], v[118:121]
	v_mfma_f32_16x16x32_bf16 v[114:117], v[202:205], v[160:163], v[114:117]
	v_mfma_f32_16x16x32_bf16 v[102:105], v[194:197], v[168:171], v[102:105]
	v_mfma_f32_16x16x32_bf16 v[98:101], v[202:205], v[168:171], v[98:101]
	v_mfma_f32_16x16x32_bf16 v[86:89], v[194:197], v[176:179], v[86:89]
	v_mfma_f32_16x16x32_bf16 v[82:85], v[202:205], v[176:179], v[82:85]
	v_mfma_f32_16x16x32_bf16 v[70:73], v[194:197], v[184:187], v[70:73]
	v_mfma_f32_16x16x32_bf16 v[66:69], v[202:205], v[184:187], v[66:69]
	v_mfma_f32_16x16x32_bf16 v[118:121], v[198:201], v[164:167], v[118:121]
	v_mfma_f32_16x16x32_bf16 v[114:117], v[206:209], v[164:167], v[114:117]
	v_mfma_f32_16x16x32_bf16 v[102:105], v[198:201], v[172:175], v[102:105]
	v_mfma_f32_16x16x32_bf16 v[98:101], v[206:209], v[172:175], v[98:101]
	v_mfma_f32_16x16x32_bf16 v[86:89], v[198:201], v[180:183], v[86:89]
	v_mfma_f32_16x16x32_bf16 v[82:85], v[206:209], v[180:183], v[82:85]
	v_mfma_f32_16x16x32_bf16 v[70:73], v[198:201], v[190:193], v[70:73]
	v_mfma_f32_16x16x32_bf16 v[66:69], v[206:209], v[190:193], v[66:69]
	s_mov_b32 m0, s38
	s_barrier
	ds_read_b128 v[160:163], v151 offset:49152
	ds_read_b128 v[164:167], v151 offset:50176
	ds_read_b128 v[168:171], v151 offset:51200
	ds_read_b128 v[172:175], v151 offset:52224
	ds_read_b128 v[176:179], v151 offset:53248
	ds_read_b128 v[180:183], v151 offset:54272
	ds_read_b128 v[184:187], v151 offset:55296
	ds_read_b128 v[190:193], v151 offset:56320
	s_add_u32 s98, s100, s40
	s_addc_u32 s99, s101, s41
	global_load_lds_dwordx4 v136, s[98:99]
	s_mov_b32 m0, s39
	s_nop 0
	global_load_lds_dwordx4 v132, s[98:99]
	s_waitcnt vmcnt(10)
	s_barrier
	s_waitcnt lgkmcnt(0)
	v_mfma_f32_16x16x32_bf16 v[62:65], v[142:145], v[160:163], v[62:65]
	v_mfma_f32_16x16x32_bf16 v[58:61], v[152:155], v[160:163], v[58:61]
	v_mfma_f32_16x16x32_bf16 v[46:49], v[142:145], v[168:171], v[46:49]
	v_mfma_f32_16x16x32_bf16 v[42:45], v[152:155], v[168:171], v[42:45]
	v_mfma_f32_16x16x32_bf16 v[30:33], v[142:145], v[176:179], v[30:33]
	v_mfma_f32_16x16x32_bf16 v[26:29], v[152:155], v[176:179], v[26:29]
	v_mfma_f32_16x16x32_bf16 v[14:17], v[142:145], v[184:187], v[14:17]
	v_mfma_f32_16x16x32_bf16 v[10:13], v[152:155], v[184:187], v[10:13]
	v_mfma_f32_16x16x32_bf16 v[62:65], v[146:149], v[164:167], v[62:65]
	s_add_u32 s12, s12, 0x40080
	s_addc_u32 s13, s13, 0
	v_mfma_f32_16x16x32_bf16 v[58:61], v[156:159], v[164:167], v[58:61]
	s_add_i32 m0, s22, 0x1c000
	v_mfma_f32_16x16x32_bf16 v[46:49], v[146:149], v[172:175], v[46:49]
	v_mfma_f32_16x16x32_bf16 v[42:45], v[156:159], v[172:175], v[42:45]
	v_mfma_f32_16x16x32_bf16 v[30:33], v[146:149], v[180:183], v[30:33]
	v_mfma_f32_16x16x32_bf16 v[26:29], v[156:159], v[180:183], v[26:29]
	v_mfma_f32_16x16x32_bf16 v[14:17], v[146:149], v[190:193], v[14:17]
	v_mfma_f32_16x16x32_bf16 v[10:13], v[156:159], v[190:193], v[10:13]
	s_barrier
	s_nop 0
	global_load_lds_dwordx4 v134, s[12:13]
	s_add_i32 m0, s22, 0x1e000
	s_nop 0
	global_load_lds_dwordx4 v130, s[12:13]
	ds_read_b128 v[142:145], v189
	ds_read_b128 v[146:149], v189 offset:1024
	ds_read_b128 v[152:155], v189 offset:2048
	ds_read_b128 v[156:159], v189 offset:3072
	s_waitcnt vmcnt(6)
	s_barrier
	v_mfma_f32_16x16x32_bf16 v[54:57], v[194:197], v[160:163], v[54:57]
	v_mfma_f32_16x16x32_bf16 v[50:53], v[202:205], v[160:163], v[50:53]
	v_mfma_f32_16x16x32_bf16 v[38:41], v[194:197], v[168:171], v[38:41]
	v_mfma_f32_16x16x32_bf16 v[34:37], v[202:205], v[168:171], v[34:37]
	v_mfma_f32_16x16x32_bf16 v[22:25], v[194:197], v[176:179], v[22:25]
	v_mfma_f32_16x16x32_bf16 v[18:21], v[202:205], v[176:179], v[18:21]
	v_mfma_f32_16x16x32_bf16 v[6:9], v[194:197], v[184:187], v[6:9]
	v_mfma_f32_16x16x32_bf16 v[2:5], v[202:205], v[184:187], v[2:5]
	v_mfma_f32_16x16x32_bf16 v[54:57], v[198:201], v[164:167], v[54:57]
	s_add_i32 s85, s85, 2
	s_add_u32 s4, s4, 0x100
	v_mfma_f32_16x16x32_bf16 v[50:53], v[206:209], v[164:167], v[50:53]
	s_addc_u32 s5, s5, 0
	s_add_u32 s78, s78, 0x100
	v_mfma_f32_16x16x32_bf16 v[38:41], v[198:201], v[172:175], v[38:41]
	s_addc_u32 s79, s79, 0
	s_add_u32 s12, s4, 0xfffc0080
	v_mfma_f32_16x16x32_bf16 v[34:37], v[206:209], v[172:175], v[34:37]
	s_addc_u32 s13, s5, -1
	s_cmp_eq_u32 s85, 12
	v_mfma_f32_16x16x32_bf16 v[22:25], v[198:201], v[180:183], v[22:25]
	s_cselect_b32 s15, s44, s13
	s_cselect_b32 s14, s45, s12
	v_mfma_f32_16x16x32_bf16 v[18:21], v[206:209], v[180:183], v[18:21]
	s_cselect_b32 s13, s47, s79
	s_cselect_b32 s12, s55, s78
	v_mfma_f32_16x16x32_bf16 v[6:9], v[198:201], v[190:193], v[6:9]
	s_cmp_gt_u32 s85, 13
	v_mfma_f32_16x16x32_bf16 v[2:5], v[206:209], v[190:193], v[2:5]
	s_barrier
	s_cbranch_scc0 .LBB0_267
	s_waitcnt lgkmcnt(0)
	v_mov_b32_e32 v156, v252
	s_mov_b64 s[4:5], -1
	v_and_b32_e32 v154, 63, v156
	s_andn2_b64 vcc, exec, s[2:3]
	v_lshlrev_b32_e32 v142, 2, v154
	s_cbranch_vccnz .LBB0_270
	v_lshlrev_b32_e32 v155, 2, v154
	s_mov_b64 s[4:5], 0

.LBB0_837:
	s_ashr_i32 s15, s14, 31
	s_lshl_b64 s[78:79], s[14:15], 19
	s_add_u32 s84, s36, s78
	s_addc_u32 s85, s37, s79
	s_and_b64 s[4:5], s[4:5], exec
	s_cselect_b32 s15, s85, s91
	s_cselect_b32 s23, s84, s90
	s_add_u32 s34, s90, 0x100
	s_addc_u32 s75, s91, 0
	s_mov_b32 s78, -2
	s_waitcnt lgkmcnt(0)
	s_add_i32 s79, 0, 0x10000
	v_add_u32_e32 v142, s79, v212
	v_add_u32_e32 v189, 0x10000, v212
	ds_read_b128 v[130:133], v142
	ds_read_b128 v[134:137], v142 offset:1024
	ds_read_b128 v[138:141], v142 offset:2048
	ds_read_b128 v[142:145], v142 offset:3072
	s_add_u32 s4, s88, 0x100
	s_addc_u32 s5, s89, 0
	s_cmp_eq_u32 s78, 12
	s_cselect_b32 s93, s17, s5
	s_cselect_b32 s92, s16, s4
	s_cselect_b32 s91, s15, s75
	s_cselect_b32 s90, s23, s34
	v_lshl_add_u64 v[178:179], s[88:89], 0, v[196:197]
	s_add_i32 m0, s39, 0xc000
	ds_read_b128 v[146:149], v213
	ds_read_b128 v[150:153], v213 offset:1024
	ds_read_b128 v[154:157], v213 offset:2048
	ds_read_b128 v[158:161], v213 offset:3072
	ds_read_b128 v[162:165], v213 offset:4096
	ds_read_b128 v[166:169], v213 offset:5120
	ds_read_b128 v[170:173], v213 offset:6144
	ds_read_b128 v[174:177], v213 offset:7168
	global_load_lds_dwordx4 v[178:179], off
	s_add_i32 m0, s39, 0xe000
	v_lshl_add_u64 v[178:179], s[88:89], 0, v[198:199]
	global_load_lds_dwordx4 v[178:179], off
	s_waitcnt lgkmcnt(8)
	s_barrier
	s_waitcnt lgkmcnt(0)
	v_mfma_f32_16x16x32_bf16 v[126:129], v[130:133], v[146:149], 0
	v_mfma_f32_16x16x32_bf16 v[122:125], v[138:141], v[146:149], 0
	v_mfma_f32_16x16x32_bf16 v[110:113], v[130:133], v[154:157], 0
	v_mfma_f32_16x16x32_bf16 v[106:109], v[138:141], v[154:157], 0
	v_mfma_f32_16x16x32_bf16 v[94:97], v[130:133], v[162:165], 0
	v_mfma_f32_16x16x32_bf16 v[90:93], v[138:141], v[162:165], 0
	v_mfma_f32_16x16x32_bf16 v[78:81], v[130:133], v[170:173], 0
	v_mfma_f32_16x16x32_bf16 v[74:77], v[138:141], v[170:173], 0
	v_mfma_f32_16x16x32_bf16 v[126:129], v[134:137], v[150:153], v[126:129]
	v_mfma_f32_16x16x32_bf16 v[122:125], v[142:145], v[150:153], v[122:125]
	v_mfma_f32_16x16x32_bf16 v[110:113], v[134:137], v[158:161], v[110:113]
	v_mfma_f32_16x16x32_bf16 v[106:109], v[142:145], v[158:161], v[106:109]
	v_mfma_f32_16x16x32_bf16 v[94:97], v[134:137], v[166:169], v[94:97]
	v_mfma_f32_16x16x32_bf16 v[90:93], v[142:145], v[166:169], v[90:93]
	v_mfma_f32_16x16x32_bf16 v[78:81], v[134:137], v[174:177], v[78:81]
	v_mfma_f32_16x16x32_bf16 v[74:77], v[142:145], v[174:177], v[74:77]
	s_barrier
	ds_read_b128 v[178:181], v189 offset:16384
	ds_read_b128 v[182:185], v189 offset:17408
	ds_read_b128 v[200:203], v189 offset:18432
	ds_read_b128 v[204:207], v189 offset:19456
	s_add_i32 m0, s38, 0x10000
	s_nop 0
	global_load_lds_dwordx4 v0, s[90:91]
	s_add_i32 m0, s38, 0x12000
	s_nop 0
	global_load_lds_dwordx4 v194, s[90:91]
	s_barrier
	s_waitcnt lgkmcnt(0)
	v_mfma_f32_16x16x32_bf16 v[118:121], v[178:181], v[146:149], 0
	v_mfma_f32_16x16x32_bf16 v[114:117], v[200:203], v[146:149], 0
	v_mfma_f32_16x16x32_bf16 v[102:105], v[178:181], v[154:157], 0
	v_mfma_f32_16x16x32_bf16 v[98:101], v[200:203], v[154:157], 0
	v_mfma_f32_16x16x32_bf16 v[86:89], v[178:181], v[162:165], 0
	v_mfma_f32_16x16x32_bf16 v[82:85], v[200:203], v[162:165], 0
	v_mfma_f32_16x16x32_bf16 v[70:73], v[178:181], v[170:173], 0
	v_mfma_f32_16x16x32_bf16 v[66:69], v[200:203], v[170:173], 0
	v_mfma_f32_16x16x32_bf16 v[118:121], v[182:185], v[150:153], v[118:121]
	v_mfma_f32_16x16x32_bf16 v[114:117], v[204:207], v[150:153], v[114:117]
	v_mfma_f32_16x16x32_bf16 v[102:105], v[182:185], v[158:161], v[102:105]
	v_mfma_f32_16x16x32_bf16 v[98:101], v[204:207], v[158:161], v[98:101]
	v_mfma_f32_16x16x32_bf16 v[86:89], v[182:185], v[166:169], v[86:89]
	v_mfma_f32_16x16x32_bf16 v[82:85], v[204:207], v[166:169], v[82:85]
	v_mfma_f32_16x16x32_bf16 v[70:73], v[182:185], v[174:177], v[70:73]
	v_mfma_f32_16x16x32_bf16 v[66:69], v[204:207], v[174:177], v[66:69]
	s_mov_b32 m0, s39
	s_barrier
	ds_read_b128 v[146:149], v213 offset:16384
	ds_read_b128 v[150:153], v213 offset:17408
	ds_read_b128 v[154:157], v213 offset:18432
	ds_read_b128 v[158:161], v213 offset:19456
	ds_read_b128 v[162:165], v213 offset:20480
	ds_read_b128 v[166:169], v213 offset:21504
	ds_read_b128 v[170:173], v213 offset:22528
	global_load_lds_dwordx4 v190, s[92:93]
	s_mov_b32 m0, s42
	ds_read_b128 v[174:177], v213 offset:23552
	global_load_lds_dwordx4 v192, s[92:93]
	s_waitcnt vmcnt(10)
	s_barrier
	s_waitcnt lgkmcnt(0)
	v_mfma_f32_16x16x32_bf16 v[62:65], v[130:133], v[146:149], 0
	v_mfma_f32_16x16x32_bf16 v[58:61], v[138:141], v[146:149], 0
	v_mfma_f32_16x16x32_bf16 v[46:49], v[130:133], v[154:157], 0
	v_mfma_f32_16x16x32_bf16 v[42:45], v[138:141], v[154:157], 0
	v_mfma_f32_16x16x32_bf16 v[30:33], v[130:133], v[162:165], 0
	v_mfma_f32_16x16x32_bf16 v[26:29], v[138:141], v[162:165], 0
	v_mfma_f32_16x16x32_bf16 v[14:17], v[130:133], v[170:173], 0
	v_mfma_f32_16x16x32_bf16 v[10:13], v[138:141], v[170:173], 0
	v_mfma_f32_16x16x32_bf16 v[62:65], v[134:137], v[150:153], v[62:65]
	s_add_u32 s88, s90, 0x40000
	s_addc_u32 s89, s91, 0
	v_mfma_f32_16x16x32_bf16 v[58:61], v[142:145], v[150:153], v[58:61]
	s_add_i32 m0, s38, 0x14000
	v_mfma_f32_16x16x32_bf16 v[46:49], v[134:137], v[158:161], v[46:49]
	v_mfma_f32_16x16x32_bf16 v[42:45], v[142:145], v[158:161], v[42:45]
	v_mfma_f32_16x16x32_bf16 v[30:33], v[134:137], v[166:169], v[30:33]
	v_mfma_f32_16x16x32_bf16 v[26:29], v[142:145], v[166:169], v[26:29]
	v_mfma_f32_16x16x32_bf16 v[14:17], v[134:137], v[174:177], v[14:17]
	v_mfma_f32_16x16x32_bf16 v[10:13], v[142:145], v[174:177], v[10:13]
	s_barrier
	s_nop 0
	global_load_lds_dwordx4 v0, s[88:89]
	s_add_i32 m0, s38, 0x16000
	s_nop 0
	global_load_lds_dwordx4 v194, s[88:89]
	s_add_i32 s79, 0, 0x18000
	v_add_u32_e32 v142, s79, v212
	ds_read_b128 v[130:133], v142
	ds_read_b128 v[134:137], v142 offset:1024
	ds_read_b128 v[138:141], v142 offset:2048
	ds_read_b128 v[142:145], v142 offset:3072
	s_waitcnt vmcnt(6)
	s_barrier
	v_mfma_f32_16x16x32_bf16 v[54:57], v[178:181], v[146:149], 0
	v_mfma_f32_16x16x32_bf16 v[50:53], v[200:203], v[146:149], 0
	v_mfma_f32_16x16x32_bf16 v[38:41], v[178:181], v[154:157], 0
	v_mfma_f32_16x16x32_bf16 v[34:37], v[200:203], v[154:157], 0
	v_mfma_f32_16x16x32_bf16 v[22:25], v[178:181], v[162:165], 0
	v_mfma_f32_16x16x32_bf16 v[18:21], v[200:203], v[162:165], 0
	v_mfma_f32_16x16x32_bf16 v[6:9], v[178:181], v[170:173], 0
	v_mfma_f32_16x16x32_bf16 v[2:5], v[200:203], v[170:173], 0
	v_mfma_f32_16x16x32_bf16 v[54:57], v[182:185], v[150:153], v[54:57]
	s_add_u32 s88, s92, 0xc0000
	s_addc_u32 s89, s93, 0
	v_mfma_f32_16x16x32_bf16 v[50:53], v[204:207], v[150:153], v[50:53]
	s_mov_b32 m0, s43
	v_mfma_f32_16x16x32_bf16 v[38:41], v[182:185], v[158:161], v[38:41]
	v_mfma_f32_16x16x32_bf16 v[34:37], v[204:207], v[158:161], v[34:37]
	v_mfma_f32_16x16x32_bf16 v[22:25], v[182:185], v[166:169], v[22:25]
	v_mfma_f32_16x16x32_bf16 v[18:21], v[204:207], v[166:169], v[18:21]
	v_mfma_f32_16x16x32_bf16 v[6:9], v[182:185], v[174:177], v[6:9]
	v_mfma_f32_16x16x32_bf16 v[2:5], v[204:207], v[174:177], v[2:5]
	s_barrier
	ds_read_b128 v[146:149], v213 offset:32768
	ds_read_b128 v[150:153], v213 offset:33792
	ds_read_b128 v[154:157], v213 offset:34816
	ds_read_b128 v[158:161], v213 offset:35840
	ds_read_b128 v[162:165], v213 offset:36864
	ds_read_b128 v[166:169], v213 offset:37888
	ds_read_b128 v[170:173], v213 offset:38912
	global_load_lds_dwordx4 v190, s[88:89]
	s_mov_b32 m0, s44
	ds_read_b128 v[174:177], v213 offset:39936
	global_load_lds_dwordx4 v192, s[88:89]
	s_waitcnt lgkmcnt(8)
	s_barrier
	s_waitcnt lgkmcnt(0)
	v_mfma_f32_16x16x32_bf16 v[126:129], v[130:133], v[146:149], v[126:129]
	v_mfma_f32_16x16x32_bf16 v[122:125], v[138:141], v[146:149], v[122:125]
	v_mfma_f32_16x16x32_bf16 v[110:113], v[130:133], v[154:157], v[110:113]
	v_mfma_f32_16x16x32_bf16 v[106:109], v[138:141], v[154:157], v[106:109]
	v_mfma_f32_16x16x32_bf16 v[94:97], v[130:133], v[162:165], v[94:97]
	v_mfma_f32_16x16x32_bf16 v[90:93], v[138:141], v[162:165], v[90:93]
	v_mfma_f32_16x16x32_bf16 v[78:81], v[130:133], v[170:173], v[78:81]
	v_mfma_f32_16x16x32_bf16 v[74:77], v[138:141], v[170:173], v[74:77]
	v_mfma_f32_16x16x32_bf16 v[126:129], v[134:137], v[150:153], v[126:129]
	s_add_i32 s87, 0, 0x1c000
	v_mfma_f32_16x16x32_bf16 v[122:125], v[142:145], v[150:153], v[122:125]
	v_mfma_f32_16x16x32_bf16 v[110:113], v[134:137], v[158:161], v[110:113]
	v_mfma_f32_16x16x32_bf16 v[106:109], v[142:145], v[158:161], v[106:109]
	v_mfma_f32_16x16x32_bf16 v[94:97], v[134:137], v[166:169], v[94:97]
	v_mfma_f32_16x16x32_bf16 v[90:93], v[142:145], v[166:169], v[90:93]
	v_mfma_f32_16x16x32_bf16 v[78:81], v[134:137], v[174:177], v[78:81]
	v_mfma_f32_16x16x32_bf16 v[74:77], v[142:145], v[174:177], v[74:77]
	s_barrier
	v_add_u32_e32 v204, s87, v212
	s_add_i32 m0, s38, 0x18000
	ds_read_b128 v[178:181], v204
	ds_read_b128 v[182:185], v204 offset:1024
	ds_read_b128 v[200:203], v204 offset:2048
	ds_read_b128 v[204:207], v204 offset:3072
	s_add_u32 s98, s90, s40
	s_addc_u32 s99, s91, s41
	global_load_lds_dwordx4 v0, s[98:99]
	s_add_i32 m0, s38, 0x1a000
	s_nop 0
	global_load_lds_dwordx4 v194, s[98:99]
	s_barrier
	s_waitcnt lgkmcnt(0)
	v_mfma_f32_16x16x32_bf16 v[118:121], v[178:181], v[146:149], v[118:121]
	v_mfma_f32_16x16x32_bf16 v[114:117], v[200:203], v[146:149], v[114:117]
	v_mfma_f32_16x16x32_bf16 v[102:105], v[178:181], v[154:157], v[102:105]
	v_mfma_f32_16x16x32_bf16 v[98:101], v[200:203], v[154:157], v[98:101]
	v_mfma_f32_16x16x32_bf16 v[86:89], v[178:181], v[162:165], v[86:89]
	v_mfma_f32_16x16x32_bf16 v[82:85], v[200:203], v[162:165], v[82:85]
	v_mfma_f32_16x16x32_bf16 v[70:73], v[178:181], v[170:173], v[70:73]
	v_mfma_f32_16x16x32_bf16 v[66:69], v[200:203], v[170:173], v[66:69]
	v_mfma_f32_16x16x32_bf16 v[118:121], v[182:185], v[150:153], v[118:121]
	v_mfma_f32_16x16x32_bf16 v[114:117], v[204:207], v[150:153], v[114:117]
	v_mfma_f32_16x16x32_bf16 v[102:105], v[182:185], v[158:161], v[102:105]
	v_mfma_f32_16x16x32_bf16 v[98:101], v[204:207], v[158:161], v[98:101]
	v_mfma_f32_16x16x32_bf16 v[86:89], v[182:185], v[166:169], v[86:89]
	v_mfma_f32_16x16x32_bf16 v[82:85], v[204:207], v[166:169], v[82:85]
	v_mfma_f32_16x16x32_bf16 v[70:73], v[182:185], v[174:177], v[70:73]
	v_mfma_f32_16x16x32_bf16 v[66:69], v[204:207], v[174:177], v[66:69]
	s_mov_b32 m0, s60
	s_barrier
	ds_read_b128 v[146:149], v213 offset:49152
	ds_read_b128 v[150:153], v213 offset:50176
	ds_read_b128 v[154:157], v213 offset:51200
	ds_read_b128 v[158:161], v213 offset:52224
	ds_read_b128 v[162:165], v213 offset:53248
	ds_read_b128 v[166:169], v213 offset:54272
	ds_read_b128 v[170:173], v213 offset:55296
	ds_read_b128 v[174:177], v213 offset:56320
	s_add_u32 s98, s92, s40
	s_addc_u32 s99, s93, s41
	global_load_lds_dwordx4 v190, s[98:99]
	s_mov_b32 m0, s61
	s_nop 0
	global_load_lds_dwordx4 v192, s[98:99]
	s_waitcnt vmcnt(10)
	s_barrier
	s_waitcnt lgkmcnt(0)
	v_mfma_f32_16x16x32_bf16 v[62:65], v[130:133], v[146:149], v[62:65]
	v_mfma_f32_16x16x32_bf16 v[58:61], v[138:141], v[146:149], v[58:61]
	v_mfma_f32_16x16x32_bf16 v[46:49], v[130:133], v[154:157], v[46:49]
	v_mfma_f32_16x16x32_bf16 v[42:45], v[138:141], v[154:157], v[42:45]
	v_mfma_f32_16x16x32_bf16 v[30:33], v[130:133], v[162:165], v[30:33]
	v_mfma_f32_16x16x32_bf16 v[26:29], v[138:141], v[162:165], v[26:29]
	v_mfma_f32_16x16x32_bf16 v[14:17], v[130:133], v[170:173], v[14:17]
	v_mfma_f32_16x16x32_bf16 v[10:13], v[138:141], v[170:173], v[10:13]
	v_mfma_f32_16x16x32_bf16 v[62:65], v[134:137], v[150:153], v[62:65]
	s_add_u32 s88, s90, 0x40080
	s_addc_u32 s89, s91, 0
	v_mfma_f32_16x16x32_bf16 v[58:61], v[142:145], v[150:153], v[58:61]
	s_add_i32 m0, s38, 0x1c000
	v_mfma_f32_16x16x32_bf16 v[46:49], v[134:137], v[158:161], v[46:49]
	v_mfma_f32_16x16x32_bf16 v[42:45], v[142:145], v[158:161], v[42:45]
	v_mfma_f32_16x16x32_bf16 v[30:33], v[134:137], v[166:169], v[30:33]
	v_mfma_f32_16x16x32_bf16 v[26:29], v[142:145], v[166:169], v[26:29]
	v_mfma_f32_16x16x32_bf16 v[14:17], v[134:137], v[174:177], v[14:17]
	v_mfma_f32_16x16x32_bf16 v[10:13], v[142:145], v[174:177], v[10:13]
	s_barrier
	s_nop 0
	global_load_lds_dwordx4 v0, s[88:89]
	s_add_i32 m0, s38, 0x1e000
	s_nop 0
	global_load_lds_dwordx4 v194, s[88:89]
	ds_read_b128 v[130:133], v189
	ds_read_b128 v[134:137], v189 offset:1024
	ds_read_b128 v[138:141], v189 offset:2048
	ds_read_b128 v[142:145], v189 offset:3072
	s_waitcnt vmcnt(6)
	s_barrier
	v_mfma_f32_16x16x32_bf16 v[54:57], v[178:181], v[146:149], v[54:57]
	v_mfma_f32_16x16x32_bf16 v[50:53], v[200:203], v[146:149], v[50:53]
	v_mfma_f32_16x16x32_bf16 v[38:41], v[178:181], v[154:157], v[38:41]
	v_mfma_f32_16x16x32_bf16 v[34:37], v[200:203], v[154:157], v[34:37]
	v_mfma_f32_16x16x32_bf16 v[22:25], v[178:181], v[162:165], v[22:25]
	v_mfma_f32_16x16x32_bf16 v[18:21], v[200:203], v[162:165], v[18:21]
	v_mfma_f32_16x16x32_bf16 v[6:9], v[178:181], v[170:173], v[6:9]
	v_mfma_f32_16x16x32_bf16 v[2:5], v[200:203], v[170:173], v[2:5]
	v_mfma_f32_16x16x32_bf16 v[54:57], v[182:185], v[150:153], v[54:57]
	s_add_i32 s78, s78, 2
	s_add_u32 s34, s34, 0x100
	v_mfma_f32_16x16x32_bf16 v[50:53], v[204:207], v[150:153], v[50:53]
	s_addc_u32 s75, s75, 0
	s_mov_b64 s[88:89], s[4:5]
	v_mfma_f32_16x16x32_bf16 v[38:41], v[182:185], v[158:161], v[38:41]
	s_add_u32 s4, s88, 0x100
	s_addc_u32 s5, s89, 0
	v_mfma_f32_16x16x32_bf16 v[34:37], v[204:207], v[158:161], v[34:37]
	s_cmp_eq_u32 s78, 12
	s_cselect_b32 s93, s17, s5
	v_mfma_f32_16x16x32_bf16 v[22:25], v[182:185], v[166:169], v[22:25]
	s_cselect_b32 s92, s16, s4
	s_cselect_b32 s91, s15, s75
	v_mfma_f32_16x16x32_bf16 v[18:21], v[204:207], v[166:169], v[18:21]
	s_cselect_b32 s90, s23, s34
	s_cmp_gt_u32 s78, 13
	v_mfma_f32_16x16x32_bf16 v[6:9], v[182:185], v[174:177], v[6:9]
	v_mfma_f32_16x16x32_bf16 v[2:5], v[204:207], v[174:177], v[2:5]
	s_barrier
	.p2align 3
.LBB0_838:
	v_lshl_add_u64 v[178:179], s[88:89], 0, v[196:197]
	s_add_i32 m0, s39, 0xc000
	ds_read_b128 v[146:149], v213
	ds_read_b128 v[150:153], v213 offset:1024
	ds_read_b128 v[154:157], v213 offset:2048
	ds_read_b128 v[158:161], v213 offset:3072
	ds_read_b128 v[162:165], v213 offset:4096
	ds_read_b128 v[166:169], v213 offset:5120
	ds_read_b128 v[170:173], v213 offset:6144
	ds_read_b128 v[174:177], v213 offset:7168
	global_load_lds_dwordx4 v[178:179], off
	s_add_i32 m0, s39, 0xe000
	v_lshl_add_u64 v[178:179], s[88:89], 0, v[198:199]
	global_load_lds_dwordx4 v[178:179], off
	s_waitcnt lgkmcnt(8)
	s_barrier
	s_waitcnt lgkmcnt(0)
	v_mfma_f32_16x16x32_bf16 v[126:129], v[130:133], v[146:149], v[126:129]
	v_mfma_f32_16x16x32_bf16 v[122:125], v[138:141], v[146:149], v[122:125]
	v_mfma_f32_16x16x32_bf16 v[110:113], v[130:133], v[154:157], v[110:113]
	v_mfma_f32_16x16x32_bf16 v[106:109], v[138:141], v[154:157], v[106:109]
	v_mfma_f32_16x16x32_bf16 v[94:97], v[130:133], v[162:165], v[94:97]
	v_mfma_f32_16x16x32_bf16 v[90:93], v[138:141], v[162:165], v[90:93]
	v_mfma_f32_16x16x32_bf16 v[78:81], v[130:133], v[170:173], v[78:81]
	v_mfma_f32_16x16x32_bf16 v[74:77], v[138:141], v[170:173], v[74:77]
	v_mfma_f32_16x16x32_bf16 v[126:129], v[134:137], v[150:153], v[126:129]
	v_mfma_f32_16x16x32_bf16 v[122:125], v[142:145], v[150:153], v[122:125]
	v_mfma_f32_16x16x32_bf16 v[110:113], v[134:137], v[158:161], v[110:113]
	v_mfma_f32_16x16x32_bf16 v[106:109], v[142:145], v[158:161], v[106:109]
	v_mfma_f32_16x16x32_bf16 v[94:97], v[134:137], v[166:169], v[94:97]
	v_mfma_f32_16x16x32_bf16 v[90:93], v[142:145], v[166:169], v[90:93]
	v_mfma_f32_16x16x32_bf16 v[78:81], v[134:137], v[174:177], v[78:81]
	v_mfma_f32_16x16x32_bf16 v[74:77], v[142:145], v[174:177], v[74:77]
	s_barrier
	ds_read_b128 v[178:181], v189 offset:16384
	ds_read_b128 v[182:185], v189 offset:17408
	ds_read_b128 v[200:203], v189 offset:18432
	ds_read_b128 v[204:207], v189 offset:19456
	s_add_i32 m0, s38, 0x10000
	s_nop 0
	global_load_lds_dwordx4 v0, s[90:91]
	s_add_i32 m0, s38, 0x12000
	s_nop 0
	global_load_lds_dwordx4 v194, s[90:91]
	s_barrier
	s_waitcnt lgkmcnt(0)
	v_mfma_f32_16x16x32_bf16 v[118:121], v[178:181], v[146:149], v[118:121]
	v_mfma_f32_16x16x32_bf16 v[114:117], v[200:203], v[146:149], v[114:117]
	v_mfma_f32_16x16x32_bf16 v[102:105], v[178:181], v[154:157], v[102:105]
	v_mfma_f32_16x16x32_bf16 v[98:101], v[200:203], v[154:157], v[98:101]
	v_mfma_f32_16x16x32_bf16 v[86:89], v[178:181], v[162:165], v[86:89]
	v_mfma_f32_16x16x32_bf16 v[82:85], v[200:203], v[162:165], v[82:85]
	v_mfma_f32_16x16x32_bf16 v[70:73], v[178:181], v[170:173], v[70:73]
	v_mfma_f32_16x16x32_bf16 v[66:69], v[200:203], v[170:173], v[66:69]
	v_mfma_f32_16x16x32_bf16 v[118:121], v[182:185], v[150:153], v[118:121]
	v_mfma_f32_16x16x32_bf16 v[114:117], v[204:207], v[150:153], v[114:117]
	v_mfma_f32_16x16x32_bf16 v[102:105], v[182:185], v[158:161], v[102:105]
	v_mfma_f32_16x16x32_bf16 v[98:101], v[204:207], v[158:161], v[98:101]
	v_mfma_f32_16x16x32_bf16 v[86:89], v[182:185], v[166:169], v[86:89]
	v_mfma_f32_16x16x32_bf16 v[82:85], v[204:207], v[166:169], v[82:85]
	v_mfma_f32_16x16x32_bf16 v[70:73], v[182:185], v[174:177], v[70:73]
	v_mfma_f32_16x16x32_bf16 v[66:69], v[204:207], v[174:177], v[66:69]
	s_mov_b32 m0, s39
	s_barrier
	ds_read_b128 v[146:149], v213 offset:16384
	ds_read_b128 v[150:153], v213 offset:17408
	ds_read_b128 v[154:157], v213 offset:18432
	ds_read_b128 v[158:161], v213 offset:19456
	ds_read_b128 v[162:165], v213 offset:20480
	ds_read_b128 v[166:169], v213 offset:21504
	ds_read_b128 v[170:173], v213 offset:22528
	global_load_lds_dwordx4 v190, s[92:93]
	s_mov_b32 m0, s42
	ds_read_b128 v[174:177], v213 offset:23552
	global_load_lds_dwordx4 v192, s[92:93]
	s_waitcnt vmcnt(10)
	s_barrier
	s_waitcnt lgkmcnt(0)
	v_mfma_f32_16x16x32_bf16 v[62:65], v[130:133], v[146:149], v[62:65]
	v_mfma_f32_16x16x32_bf16 v[58:61], v[138:141], v[146:149], v[58:61]
	v_mfma_f32_16x16x32_bf16 v[46:49], v[130:133], v[154:157], v[46:49]
	v_mfma_f32_16x16x32_bf16 v[42:45], v[138:141], v[154:157], v[42:45]
	v_mfma_f32_16x16x32_bf16 v[30:33], v[130:133], v[162:165], v[30:33]
	v_mfma_f32_16x16x32_bf16 v[26:29], v[138:141], v[162:165], v[26:29]
	v_mfma_f32_16x16x32_bf16 v[14:17], v[130:133], v[170:173], v[14:17]
	v_mfma_f32_16x16x32_bf16 v[10:13], v[138:141], v[170:173], v[10:13]
	v_mfma_f32_16x16x32_bf16 v[62:65], v[134:137], v[150:153], v[62:65]
	s_add_u32 s88, s90, 0x40000
	s_addc_u32 s89, s91, 0
	v_mfma_f32_16x16x32_bf16 v[58:61], v[142:145], v[150:153], v[58:61]
	s_add_i32 m0, s38, 0x14000
	v_mfma_f32_16x16x32_bf16 v[46:49], v[134:137], v[158:161], v[46:49]
	v_mfma_f32_16x16x32_bf16 v[42:45], v[142:145], v[158:161], v[42:45]
	v_mfma_f32_16x16x32_bf16 v[30:33], v[134:137], v[166:169], v[30:33]
	v_mfma_f32_16x16x32_bf16 v[26:29], v[142:145], v[166:169], v[26:29]
	v_mfma_f32_16x16x32_bf16 v[14:17], v[134:137], v[174:177], v[14:17]
	v_mfma_f32_16x16x32_bf16 v[10:13], v[142:145], v[174:177], v[10:13]
	s_barrier
	s_nop 0
	global_load_lds_dwordx4 v0, s[88:89]
	s_add_i32 m0, s38, 0x16000
	s_nop 0
	global_load_lds_dwordx4 v194, s[88:89]
	s_add_i32 s79, 0, 0x18000
	v_add_u32_e32 v142, s79, v212
	ds_read_b128 v[130:133], v142
	ds_read_b128 v[134:137], v142 offset:1024
	ds_read_b128 v[138:141], v142 offset:2048
	ds_read_b128 v[142:145], v142 offset:3072
	s_waitcnt vmcnt(6)
	s_barrier
	v_mfma_f32_16x16x32_bf16 v[54:57], v[178:181], v[146:149], v[54:57]
	v_mfma_f32_16x16x32_bf16 v[50:53], v[200:203], v[146:149], v[50:53]
	v_mfma_f32_16x16x32_bf16 v[38:41], v[178:181], v[154:157], v[38:41]
	v_mfma_f32_16x16x32_bf16 v[34:37], v[200:203], v[154:157], v[34:37]
	v_mfma_f32_16x16x32_bf16 v[22:25], v[178:181], v[162:165], v[22:25]
	v_mfma_f32_16x16x32_bf16 v[18:21], v[200:203], v[162:165], v[18:21]
	v_mfma_f32_16x16x32_bf16 v[6:9], v[178:181], v[170:173], v[6:9]
	v_mfma_f32_16x16x32_bf16 v[2:5], v[200:203], v[170:173], v[2:5]
	v_mfma_f32_16x16x32_bf16 v[54:57], v[182:185], v[150:153], v[54:57]
	s_add_u32 s88, s92, 0xc0000
	s_addc_u32 s89, s93, 0
	v_mfma_f32_16x16x32_bf16 v[50:53], v[204:207], v[150:153], v[50:53]
	s_mov_b32 m0, s43
	v_mfma_f32_16x16x32_bf16 v[38:41], v[182:185], v[158:161], v[38:41]
	v_mfma_f32_16x16x32_bf16 v[34:37], v[204:207], v[158:161], v[34:37]
	v_mfma_f32_16x16x32_bf16 v[22:25], v[182:185], v[166:169], v[22:25]
	v_mfma_f32_16x16x32_bf16 v[18:21], v[204:207], v[166:169], v[18:21]
	v_mfma_f32_16x16x32_bf16 v[6:9], v[182:185], v[174:177], v[6:9]
	v_mfma_f32_16x16x32_bf16 v[2:5], v[204:207], v[174:177], v[2:5]
	s_barrier
	ds_read_b128 v[146:149], v213 offset:32768
	ds_read_b128 v[150:153], v213 offset:33792
	ds_read_b128 v[154:157], v213 offset:34816
	ds_read_b128 v[158:161], v213 offset:35840
	ds_read_b128 v[162:165], v213 offset:36864
	ds_read_b128 v[166:169], v213 offset:37888
	ds_read_b128 v[170:173], v213 offset:38912
	global_load_lds_dwordx4 v190, s[88:89]
	s_mov_b32 m0, s44
	ds_read_b128 v[174:177], v213 offset:39936
	global_load_lds_dwordx4 v192, s[88:89]
	s_waitcnt lgkmcnt(8)
	s_barrier
	s_waitcnt lgkmcnt(0)
	v_mfma_f32_16x16x32_bf16 v[126:129], v[130:133], v[146:149], v[126:129]
	v_mfma_f32_16x16x32_bf16 v[122:125], v[138:141], v[146:149], v[122:125]
	v_mfma_f32_16x16x32_bf16 v[110:113], v[130:133], v[154:157], v[110:113]
	v_mfma_f32_16x16x32_bf16 v[106:109], v[138:141], v[154:157], v[106:109]
	v_mfma_f32_16x16x32_bf16 v[94:97], v[130:133], v[162:165], v[94:97]
	v_mfma_f32_16x16x32_bf16 v[90:93], v[138:141], v[162:165], v[90:93]
	v_mfma_f32_16x16x32_bf16 v[78:81], v[130:133], v[170:173], v[78:81]
	v_mfma_f32_16x16x32_bf16 v[74:77], v[138:141], v[170:173], v[74:77]
	v_mfma_f32_16x16x32_bf16 v[126:129], v[134:137], v[150:153], v[126:129]
	s_add_i32 s87, 0, 0x1c000
	v_mfma_f32_16x16x32_bf16 v[122:125], v[142:145], v[150:153], v[122:125]
	v_mfma_f32_16x16x32_bf16 v[110:113], v[134:137], v[158:161], v[110:113]
	v_mfma_f32_16x16x32_bf16 v[106:109], v[142:145], v[158:161], v[106:109]
	v_mfma_f32_16x16x32_bf16 v[94:97], v[134:137], v[166:169], v[94:97]
	v_mfma_f32_16x16x32_bf16 v[90:93], v[142:145], v[166:169], v[90:93]
	v_mfma_f32_16x16x32_bf16 v[78:81], v[134:137], v[174:177], v[78:81]
	v_mfma_f32_16x16x32_bf16 v[74:77], v[142:145], v[174:177], v[74:77]
	s_barrier
	v_add_u32_e32 v204, s87, v212
	s_add_i32 m0, s38, 0x18000
	ds_read_b128 v[178:181], v204
	ds_read_b128 v[182:185], v204 offset:1024
	ds_read_b128 v[200:203], v204 offset:2048
	ds_read_b128 v[204:207], v204 offset:3072
	s_add_u32 s98, s90, s40
	s_addc_u32 s99, s91, s41
	global_load_lds_dwordx4 v0, s[98:99]
	s_add_i32 m0, s38, 0x1a000
	s_nop 0
	global_load_lds_dwordx4 v194, s[98:99]
	s_barrier
	s_waitcnt lgkmcnt(0)
	v_mfma_f32_16x16x32_bf16 v[118:121], v[178:181], v[146:149], v[118:121]
	v_mfma_f32_16x16x32_bf16 v[114:117], v[200:203], v[146:149], v[114:117]
	v_mfma_f32_16x16x32_bf16 v[102:105], v[178:181], v[154:157], v[102:105]
	v_mfma_f32_16x16x32_bf16 v[98:101], v[200:203], v[154:157], v[98:101]
	v_mfma_f32_16x16x32_bf16 v[86:89], v[178:181], v[162:165], v[86:89]
	v_mfma_f32_16x16x32_bf16 v[82:85], v[200:203], v[162:165], v[82:85]
	v_mfma_f32_16x16x32_bf16 v[70:73], v[178:181], v[170:173], v[70:73]
	v_mfma_f32_16x16x32_bf16 v[66:69], v[200:203], v[170:173], v[66:69]
	v_mfma_f32_16x16x32_bf16 v[118:121], v[182:185], v[150:153], v[118:121]
	v_mfma_f32_16x16x32_bf16 v[114:117], v[204:207], v[150:153], v[114:117]
	v_mfma_f32_16x16x32_bf16 v[102:105], v[182:185], v[158:161], v[102:105]
	v_mfma_f32_16x16x32_bf16 v[98:101], v[204:207], v[158:161], v[98:101]
	v_mfma_f32_16x16x32_bf16 v[86:89], v[182:185], v[166:169], v[86:89]
	v_mfma_f32_16x16x32_bf16 v[82:85], v[204:207], v[166:169], v[82:85]
	v_mfma_f32_16x16x32_bf16 v[70:73], v[182:185], v[174:177], v[70:73]
	v_mfma_f32_16x16x32_bf16 v[66:69], v[204:207], v[174:177], v[66:69]
	s_mov_b32 m0, s60
	s_barrier
	ds_read_b128 v[146:149], v213 offset:49152
	ds_read_b128 v[150:153], v213 offset:50176
	ds_read_b128 v[154:157], v213 offset:51200
	ds_read_b128 v[158:161], v213 offset:52224
	ds_read_b128 v[162:165], v213 offset:53248
	ds_read_b128 v[166:169], v213 offset:54272
	ds_read_b128 v[170:173], v213 offset:55296
	ds_read_b128 v[174:177], v213 offset:56320
	s_add_u32 s98, s92, s40
	s_addc_u32 s99, s93, s41
	global_load_lds_dwordx4 v190, s[98:99]
	s_mov_b32 m0, s61
	s_nop 0
	global_load_lds_dwordx4 v192, s[98:99]
	s_waitcnt vmcnt(10)
	s_barrier
	s_waitcnt lgkmcnt(0)
	v_mfma_f32_16x16x32_bf16 v[62:65], v[130:133], v[146:149], v[62:65]
	v_mfma_f32_16x16x32_bf16 v[58:61], v[138:141], v[146:149], v[58:61]
	v_mfma_f32_16x16x32_bf16 v[46:49], v[130:133], v[154:157], v[46:49]
	v_mfma_f32_16x16x32_bf16 v[42:45], v[138:141], v[154:157], v[42:45]
	v_mfma_f32_16x16x32_bf16 v[30:33], v[130:133], v[162:165], v[30:33]
	v_mfma_f32_16x16x32_bf16 v[26:29], v[138:141], v[162:165], v[26:29]
	v_mfma_f32_16x16x32_bf16 v[14:17], v[130:133], v[170:173], v[14:17]
	v_mfma_f32_16x16x32_bf16 v[10:13], v[138:141], v[170:173], v[10:13]
	v_mfma_f32_16x16x32_bf16 v[62:65], v[134:137], v[150:153], v[62:65]
	s_add_u32 s88, s90, 0x40080
	s_addc_u32 s89, s91, 0
	v_mfma_f32_16x16x32_bf16 v[58:61], v[142:145], v[150:153], v[58:61]
	s_add_i32 m0, s38, 0x1c000
	v_mfma_f32_16x16x32_bf16 v[46:49], v[134:137], v[158:161], v[46:49]
	v_mfma_f32_16x16x32_bf16 v[42:45], v[142:145], v[158:161], v[42:45]
	v_mfma_f32_16x16x32_bf16 v[30:33], v[134:137], v[166:169], v[30:33]
	v_mfma_f32_16x16x32_bf16 v[26:29], v[142:145], v[166:169], v[26:29]
	v_mfma_f32_16x16x32_bf16 v[14:17], v[134:137], v[174:177], v[14:17]
	v_mfma_f32_16x16x32_bf16 v[10:13], v[142:145], v[174:177], v[10:13]
	s_barrier
	s_nop 0
	global_load_lds_dwordx4 v0, s[88:89]
	s_add_i32 m0, s38, 0x1e000
	s_nop 0
	global_load_lds_dwordx4 v194, s[88:89]
	ds_read_b128 v[130:133], v189
	ds_read_b128 v[134:137], v189 offset:1024
	ds_read_b128 v[138:141], v189 offset:2048
	ds_read_b128 v[142:145], v189 offset:3072
	s_waitcnt vmcnt(6)
	s_barrier
	v_mfma_f32_16x16x32_bf16 v[54:57], v[178:181], v[146:149], v[54:57]
	v_mfma_f32_16x16x32_bf16 v[50:53], v[200:203], v[146:149], v[50:53]
	v_mfma_f32_16x16x32_bf16 v[38:41], v[178:181], v[154:157], v[38:41]
	v_mfma_f32_16x16x32_bf16 v[34:37], v[200:203], v[154:157], v[34:37]
	v_mfma_f32_16x16x32_bf16 v[22:25], v[178:181], v[162:165], v[22:25]
	v_mfma_f32_16x16x32_bf16 v[18:21], v[200:203], v[162:165], v[18:21]
	v_mfma_f32_16x16x32_bf16 v[6:9], v[178:181], v[170:173], v[6:9]
	v_mfma_f32_16x16x32_bf16 v[2:5], v[200:203], v[170:173], v[2:5]
	v_mfma_f32_16x16x32_bf16 v[54:57], v[182:185], v[150:153], v[54:57]
	s_add_i32 s78, s78, 2
	s_add_u32 s34, s34, 0x100
	v_mfma_f32_16x16x32_bf16 v[50:53], v[204:207], v[150:153], v[50:53]
	s_addc_u32 s75, s75, 0
	s_mov_b64 s[88:89], s[4:5]
	v_mfma_f32_16x16x32_bf16 v[38:41], v[182:185], v[158:161], v[38:41]
	s_add_u32 s4, s88, 0x100
	s_addc_u32 s5, s89, 0
	v_mfma_f32_16x16x32_bf16 v[34:37], v[204:207], v[158:161], v[34:37]
	s_cmp_eq_u32 s78, 12
	s_cselect_b32 s93, s17, s5
	v_mfma_f32_16x16x32_bf16 v[22:25], v[182:185], v[166:169], v[22:25]
	s_cselect_b32 s92, s16, s4
	s_cselect_b32 s91, s15, s75
	v_mfma_f32_16x16x32_bf16 v[18:21], v[204:207], v[166:169], v[18:21]
	s_cselect_b32 s90, s23, s34
	s_cmp_gt_u32 s78, 13
	v_mfma_f32_16x16x32_bf16 v[6:9], v[182:185], v[174:177], v[6:9]
	v_mfma_f32_16x16x32_bf16 v[2:5], v[204:207], v[174:177], v[2:5]
	s_barrier
	s_cbranch_scc0 .LBB0_838
	s_waitcnt lgkmcnt(0)
	s_lshl_b32 s4, s22, 8
	v_mov_b32_e32 v186, v252
	s_add_i32 s4, s4, s47
	s_nop 0
	v_and_or_b32 v202, v186, 15, s4
	s_lshl_b32 s4, s86, 8
	s_or_b32 s4, s4, s55
	v_lshrrev_b32_e32 v130, 1, v186
	v_and_or_b32 v200, v130, 24, s4
	v_ashrrev_i32_e32 v201, 31, v200
	v_ashrrev_i32_e32 v203, 31, v202
	v_lshl_add_u64 v[204:205], v[200:201], 2, s[6:7]
	v_lshlrev_b64 v[130:131], 12, v[202:203]
	v_lshl_add_u64 v[130:131], v[204:205], 0, v[130:131]
	global_load_dwordx4 v[216:219], v[130:131], off offset:16
	global_load_dwordx4 v[220:223], v[130:131], off
	global_load_dwordx4 v[178:181], v[130:131], off offset:528
	global_load_dwordx4 v[182:185], v[130:131], off offset:512
	v_or_b32_e32 v210, 16, v202
	v_ashrrev_i32_e32 v211, 31, v210
	v_lshlrev_b64 v[130:131], 12, v[210:211]
	v_or_b32_e32 v208, 32, v202
	v_lshl_add_u64 v[130:131], v[204:205], 0, v[130:131]
	v_ashrrev_i32_e32 v209, 31, v208
	global_load_dwordx4 v[170:173], v[130:131], off offset:16
	global_load_dwordx4 v[174:177], v[130:131], off
	global_load_dwordx4 v[162:165], v[130:131], off offset:528
	global_load_dwordx4 v[166:169], v[130:131], off offset:512
	v_lshlrev_b64 v[130:131], 12, v[208:209]
	v_or_b32_e32 v206, 48, v202
	v_lshl_add_u64 v[130:131], v[204:205], 0, v[130:131]
	v_ashrrev_i32_e32 v207, 31, v206
	global_load_dwordx4 v[154:157], v[130:131], off offset:16
	global_load_dwordx4 v[158:161], v[130:131], off
	global_load_dwordx4 v[138:141], v[130:131], off offset:528
	global_load_dwordx4 v[142:145], v[130:131], off offset:512
	v_lshlrev_b64 v[130:131], 12, v[206:207]
	v_lshl_add_u64 v[134:135], v[204:205], 0, v[130:131]
	global_load_dwordx4 v[146:149], v[134:135], off offset:16
	global_load_dwordx4 v[150:153], v[134:135], off
	global_load_dwordx4 v[130:133], v[134:135], off offset:528
	s_nop 0
	global_load_dwordx4 v[134:137], v[134:135], off offset:512
	v_and_b32_e32 v186, 63, v186
	v_lshlrev_b32_e32 v187, 2, v186
	v_xor_b32_e32 v215, 64, v187
	v_xor_b32_e32 v214, 0x80, v187
	v_cmp_gt_u32_e32 vcc, 16, v186
	v_lshlrev_b64 v[186:187], 10, v[202:203]
	v_lshl_add_u64 v[186:187], v[186:187], 0, v[200:201]
	s_lshl_b32 s4, s86, 2
	s_ashr_i32 s5, s4, 31
	s_waitcnt vmcnt(0)
	v_pk_add_f32 v[124:125], v[124:125], v[218:219]
	v_pk_add_f32 v[128:129], v[128:129], v[222:223]
	v_pk_add_f32 v[126:127], v[126:127], v[220:221]
	v_pk_mul_f32 v[218:219], v[128:129], v[128:129]
	v_pk_mul_f32 v[220:221], v[126:127], v[126:127]
	v_pk_add_f32 v[122:123], v[122:123], v[216:217]
	v_lshl_add_u64 v[216:217], v[186:187], 2, s[12:13]
	v_add_f32_e32 v220, v220, v221
	v_add_f32_e32 v218, v218, v219
	global_store_dwordx4 v[216:217], v[126:129], off
	global_store_dwordx4 v[216:217], v[122:125], off offset:16
	v_add_f32_e32 v222, v220, v218
	v_pk_mul_f32 v[220:221], v[122:123], v[122:123]
	v_cvt_pk_bf16_f32 v126, v126, v127
	v_cvt_pk_bf16_f32 v127, v128, v129
	v_cvt_pk_bf16_f32 v128, v122, v123
	v_cvt_pk_bf16_f32 v129, v124, v125
	v_lshl_add_u64 v[122:123], v[186:187], 1, s[8:9]
	v_pk_add_f32 v[120:121], v[120:121], v[184:185]
	v_pk_add_f32 v[118:119], v[118:119], v[182:183]
	v_pk_mul_f32 v[218:219], v[124:125], v[124:125]
	global_store_dwordx4 v[122:123], v[126:129], off
	v_pk_mul_f32 v[124:125], v[120:121], v[120:121]
	v_pk_add_f32 v[116:117], v[116:117], v[180:181]
	v_pk_mul_f32 v[126:127], v[118:119], v[118:119]
	v_pk_add_f32 v[114:115], v[114:115], v[178:179]
	v_add_f32_e32 v126, v126, v127
	v_add_f32_e32 v124, v124, v125
	v_add_f32_e32 v128, v126, v124
	v_pk_mul_f32 v[124:125], v[116:117], v[116:117]
	v_pk_mul_f32 v[126:127], v[114:115], v[114:115]
	v_add_f32_e32 v220, v220, v221
	v_add_f32_e32 v218, v218, v219
	v_add_f32_e32 v126, v126, v127
	v_add_f32_e32 v124, v124, v125
	v_add_f32_e32 v218, v220, v218
	v_add_f32_e32 v124, v126, v124
	v_add_f32_e32 v218, v222, v218
	v_add_f32_e32 v124, v128, v124
	v_add_f32_e32 v124, v218, v124
	global_store_dwordx4 v[216:217], v[118:121], off offset:512
	global_store_dwordx4 v[216:217], v[114:117], off offset:528
	s_nop 0
	v_cvt_pk_bf16_f32 v118, v118, v119
	v_cvt_pk_bf16_f32 v119, v120, v121
	v_cvt_pk_bf16_f32 v120, v114, v115
	ds_bpermute_b32 v114, v215, v124
	v_cvt_pk_bf16_f32 v121, v116, v117
	global_store_dwordx4 v[122:123], v[118:121], off offset:256
	s_waitcnt lgkmcnt(0)
	v_add_f32_e32 v114, v124, v114
	ds_bpermute_b32 v115, v214, v114
	s_and_saveexec_b64 s[22:23], vcc
	s_cbranch_execz .LBB0_841
	v_lshlrev_b64 v[116:117], 6, v[202:203]
	v_lshl_add_u64 v[116:117], s[10:11], 0, v[116:117]
	v_lshl_add_u64 v[116:117], s[4:5], 2, v[116:117]
	s_lshl_b32 s34, s45, 2
	v_lshl_add_u64 v[116:117], v[116:117], 0, s[34:35]
	s_waitcnt lgkmcnt(0)
	v_add_f32_e32 v114, v114, v115
	global_store_dword v[116:117], v114, off

.LBB0_918:
	s_ashr_i32 s17, s16, 31
	s_lshl_b64 s[22:23], s[16:17], 19
	v_mov_b64_e32 v[2:3], 0xb00
	s_add_u32 s84, s8, s22
	v_cmp_lt_i64_e32 vcc, s[28:29], v[2:3]
	s_addc_u32 s85, s9, s23
	s_and_b64 s[22:23], vcc, exec
	s_cselect_b32 s17, s85, s7
	s_cselect_b32 s22, s84, s6
	s_ashr_i32 s15, s14, 31
	s_lshl_b64 s[28:29], s[14:15], 19
	s_add_u32 s86, s37, s28
	s_addc_u32 s87, s38, s29
	s_and_b64 s[28:29], vcc, exec
	s_cselect_b32 s15, s87, s89
	s_cselect_b32 s23, s86, s88
	s_add_u32 s28, s88, 0x100
	s_addc_u32 s29, s89, 0
	s_mov_b32 s45, -2
	s_add_i32 vcc_lo, 0, 0x10000
	v_add_u32_e32 v0, vcc_lo, v254
	v_add_u32_e32 v189, 0x10000, v254
	ds_read_b128 v[130:133], v0
	ds_read_b128 v[134:137], v0 offset:1024
	ds_read_b128 v[138:141], v0 offset:2048
	ds_read_b128 v[142:145], v0 offset:3072
	s_add_u32 s88, s6, 0x100
	s_addc_u32 s89, s7, 0
	s_cmp_eq_u32 s45, 12
	s_cselect_b32 s93, s17, s89
	s_cselect_b32 s92, s22, s88
	s_cselect_b32 s91, s15, s29
	s_cselect_b32 s90, s23, s28
	s_add_i32 m0, s43, 0xc000
	ds_read_b128 v[146:149], v253
	ds_read_b128 v[150:153], v253 offset:1024
	ds_read_b128 v[168:171], v253 offset:2048
	ds_read_b128 v[172:175], v253 offset:3072
	ds_read_b128 v[176:179], v253 offset:4096
	ds_read_b128 v[180:183], v253 offset:5120
	ds_read_b128 v[184:187], v253 offset:6144
	ds_read_b128 v[190:193], v253 offset:7168
	global_load_lds_dwordx4 v164, s[6:7]
	s_add_i32 m0, s43, 0xe000
	v_lshl_add_u64 v[154:155], s[6:7], 0, v[166:167]
	global_load_lds_dwordx4 v[154:155], off
	s_waitcnt lgkmcnt(8)
	s_barrier
	s_waitcnt lgkmcnt(0)
	v_mfma_f32_16x16x32_bf16 v[126:129], v[130:133], v[146:149], 0
	v_mfma_f32_16x16x32_bf16 v[70:73], v[138:141], v[146:149], 0
	v_mfma_f32_16x16x32_bf16 v[122:125], v[130:133], v[168:171], 0
	v_mfma_f32_16x16x32_bf16 v[74:77], v[138:141], v[168:171], 0
	v_mfma_f32_16x16x32_bf16 v[114:117], v[130:133], v[176:179], 0
	v_mfma_f32_16x16x32_bf16 v[66:69], v[138:141], v[176:179], 0
	v_mfma_f32_16x16x32_bf16 v[110:113], v[130:133], v[184:187], 0
	v_mfma_f32_16x16x32_bf16 v[78:81], v[138:141], v[184:187], 0
	v_mfma_f32_16x16x32_bf16 v[126:129], v[134:137], v[150:153], v[126:129]
	s_add_i32 m0, s39, 0x10000
	v_mfma_f32_16x16x32_bf16 v[70:73], v[142:145], v[150:153], v[70:73]
	v_mfma_f32_16x16x32_bf16 v[122:125], v[134:137], v[172:175], v[122:125]
	v_mfma_f32_16x16x32_bf16 v[74:77], v[142:145], v[172:175], v[74:77]
	v_mfma_f32_16x16x32_bf16 v[114:117], v[134:137], v[180:183], v[114:117]
	v_mfma_f32_16x16x32_bf16 v[66:69], v[142:145], v[180:183], v[66:69]
	v_mfma_f32_16x16x32_bf16 v[110:113], v[134:137], v[190:193], v[110:113]
	v_mfma_f32_16x16x32_bf16 v[78:81], v[142:145], v[190:193], v[78:81]
	s_barrier
	ds_read_b128 v[194:197], v189 offset:16384
	ds_read_b128 v[198:201], v189 offset:17408
	ds_read_b128 v[202:205], v189 offset:18432
	global_load_lds_dwordx4 v160, s[90:91]
	s_add_i32 m0, s39, 0x12000
	ds_read_b128 v[206:209], v189 offset:19456
	global_load_lds_dwordx4 v156, s[90:91]
	s_barrier
	s_waitcnt lgkmcnt(0)
	v_mfma_f32_16x16x32_bf16 v[118:121], v[194:197], v[146:149], 0
	v_mfma_f32_16x16x32_bf16 v[94:97], v[202:205], v[146:149], 0
	v_mfma_f32_16x16x32_bf16 v[106:109], v[194:197], v[168:171], 0
	v_mfma_f32_16x16x32_bf16 v[90:93], v[202:205], v[168:171], 0
	v_mfma_f32_16x16x32_bf16 v[102:105], v[194:197], v[176:179], 0
	v_mfma_f32_16x16x32_bf16 v[82:85], v[202:205], v[176:179], 0
	v_mfma_f32_16x16x32_bf16 v[98:101], v[194:197], v[184:187], 0
	v_mfma_f32_16x16x32_bf16 v[86:89], v[202:205], v[184:187], 0
	v_mfma_f32_16x16x32_bf16 v[118:121], v[198:201], v[150:153], v[118:121]
	v_mfma_f32_16x16x32_bf16 v[94:97], v[206:209], v[150:153], v[94:97]
	v_mfma_f32_16x16x32_bf16 v[106:109], v[198:201], v[172:175], v[106:109]
	v_mfma_f32_16x16x32_bf16 v[90:93], v[206:209], v[172:175], v[90:93]
	v_mfma_f32_16x16x32_bf16 v[102:105], v[198:201], v[180:183], v[102:105]
	v_mfma_f32_16x16x32_bf16 v[82:85], v[206:209], v[180:183], v[82:85]
	v_mfma_f32_16x16x32_bf16 v[98:101], v[198:201], v[190:193], v[98:101]
	v_mfma_f32_16x16x32_bf16 v[86:89], v[206:209], v[190:193], v[86:89]
	s_mov_b32 m0, s43
	s_mov_b64 s[100:101], s[92:93]
	s_barrier
	ds_read_b128 v[146:149], v253 offset:16384
	ds_read_b128 v[150:153], v253 offset:17408
	ds_read_b128 v[168:171], v253 offset:18432
	ds_read_b128 v[172:175], v253 offset:19456
	ds_read_b128 v[176:179], v253 offset:20480
	ds_read_b128 v[180:183], v253 offset:21504
	ds_read_b128 v[184:187], v253 offset:22528
	global_load_lds_dwordx4 v162, s[100:101]
	s_mov_b32 m0, s60
	ds_read_b128 v[190:193], v253 offset:23552
	global_load_lds_dwordx4 v158, s[100:101]
	s_waitcnt vmcnt(10)
	s_barrier
	s_waitcnt lgkmcnt(0)
	v_mfma_f32_16x16x32_bf16 v[62:65], v[130:133], v[146:149], 0
	v_mfma_f32_16x16x32_bf16 v[10:13], v[138:141], v[146:149], 0
	v_mfma_f32_16x16x32_bf16 v[58:61], v[130:133], v[168:171], 0
	v_mfma_f32_16x16x32_bf16 v[14:17], v[138:141], v[168:171], 0
	v_mfma_f32_16x16x32_bf16 v[54:57], v[130:133], v[176:179], 0
	v_mfma_f32_16x16x32_bf16 v[6:9], v[138:141], v[176:179], 0
	v_mfma_f32_16x16x32_bf16 v[42:45], v[130:133], v[184:187], 0
	v_mfma_f32_16x16x32_bf16 v[2:5], v[138:141], v[184:187], 0
	v_mfma_f32_16x16x32_bf16 v[62:65], v[134:137], v[150:153], v[62:65]
	s_add_u32 s6, s90, 0x40000
	s_addc_u32 s7, s91, 0
	v_mfma_f32_16x16x32_bf16 v[10:13], v[142:145], v[150:153], v[10:13]
	s_add_i32 m0, s39, 0x14000
	v_mfma_f32_16x16x32_bf16 v[58:61], v[134:137], v[172:175], v[58:61]
	v_mfma_f32_16x16x32_bf16 v[14:17], v[142:145], v[172:175], v[14:17]
	v_mfma_f32_16x16x32_bf16 v[54:57], v[134:137], v[180:183], v[54:57]
	v_mfma_f32_16x16x32_bf16 v[6:9], v[142:145], v[180:183], v[6:9]
	v_mfma_f32_16x16x32_bf16 v[42:45], v[134:137], v[190:193], v[42:45]
	v_mfma_f32_16x16x32_bf16 v[2:5], v[142:145], v[190:193], v[2:5]
	s_barrier
	s_nop 0
	global_load_lds_dwordx4 v160, s[6:7]
	s_add_i32 m0, s39, 0x16000
	s_nop 0
	global_load_lds_dwordx4 v156, s[6:7]
	ds_read_b128 v[130:133], v189 offset:32768
	ds_read_b128 v[134:137], v189 offset:33792
	ds_read_b128 v[138:141], v189 offset:34816
	ds_read_b128 v[142:145], v189 offset:35840
	s_waitcnt vmcnt(6)
	s_barrier
	v_mfma_f32_16x16x32_bf16 v[50:53], v[194:197], v[146:149], 0
	v_mfma_f32_16x16x32_bf16 v[26:29], v[202:205], v[146:149], 0
	v_mfma_f32_16x16x32_bf16 v[46:49], v[194:197], v[168:171], 0
	v_mfma_f32_16x16x32_bf16 v[30:33], v[202:205], v[168:171], 0
	v_mfma_f32_16x16x32_bf16 v[38:41], v[194:197], v[176:179], 0
	v_mfma_f32_16x16x32_bf16 v[22:25], v[202:205], v[176:179], 0
	v_mfma_f32_16x16x32_bf16 v[34:37], v[194:197], v[184:187], 0
	v_mfma_f32_16x16x32_bf16 v[18:21], v[202:205], v[184:187], 0
	v_mfma_f32_16x16x32_bf16 v[50:53], v[198:201], v[150:153], v[50:53]
	s_add_u32 s6, s92, 0x40000
	s_addc_u32 s7, s93, 0
	v_mfma_f32_16x16x32_bf16 v[26:29], v[206:209], v[150:153], v[26:29]
	s_mov_b32 m0, s61
	v_mfma_f32_16x16x32_bf16 v[46:49], v[198:201], v[172:175], v[46:49]
	v_mfma_f32_16x16x32_bf16 v[30:33], v[206:209], v[172:175], v[30:33]
	v_mfma_f32_16x16x32_bf16 v[38:41], v[198:201], v[180:183], v[38:41]
	v_mfma_f32_16x16x32_bf16 v[22:25], v[206:209], v[180:183], v[22:25]
	v_mfma_f32_16x16x32_bf16 v[34:37], v[198:201], v[190:193], v[34:37]
	v_mfma_f32_16x16x32_bf16 v[18:21], v[206:209], v[190:193], v[18:21]
	s_barrier
	ds_read_b128 v[146:149], v253 offset:32768
	ds_read_b128 v[150:153], v253 offset:33792
	ds_read_b128 v[168:171], v253 offset:34816
	ds_read_b128 v[172:175], v253 offset:35840
	ds_read_b128 v[176:179], v253 offset:36864
	ds_read_b128 v[180:183], v253 offset:37888
	ds_read_b128 v[184:187], v253 offset:38912
	global_load_lds_dwordx4 v162, s[6:7]
	s_mov_b32 m0, s72
	ds_read_b128 v[190:193], v253 offset:39936
	global_load_lds_dwordx4 v158, s[6:7]
	s_waitcnt lgkmcnt(8)
	s_barrier
	s_waitcnt lgkmcnt(0)
	v_mfma_f32_16x16x32_bf16 v[126:129], v[130:133], v[146:149], v[126:129]
	v_mfma_f32_16x16x32_bf16 v[70:73], v[138:141], v[146:149], v[70:73]
	v_mfma_f32_16x16x32_bf16 v[122:125], v[130:133], v[168:171], v[122:125]
	v_mfma_f32_16x16x32_bf16 v[74:77], v[138:141], v[168:171], v[74:77]
	v_mfma_f32_16x16x32_bf16 v[114:117], v[130:133], v[176:179], v[114:117]
	v_mfma_f32_16x16x32_bf16 v[66:69], v[138:141], v[176:179], v[66:69]
	v_mfma_f32_16x16x32_bf16 v[110:113], v[130:133], v[184:187], v[110:113]
	v_mfma_f32_16x16x32_bf16 v[78:81], v[138:141], v[184:187], v[78:81]
	v_mfma_f32_16x16x32_bf16 v[126:129], v[134:137], v[150:153], v[126:129]
	s_add_i32 m0, s39, 0x18000
	v_mfma_f32_16x16x32_bf16 v[70:73], v[142:145], v[150:153], v[70:73]
	v_mfma_f32_16x16x32_bf16 v[122:125], v[134:137], v[172:175], v[122:125]
	v_mfma_f32_16x16x32_bf16 v[74:77], v[142:145], v[172:175], v[74:77]
	v_mfma_f32_16x16x32_bf16 v[114:117], v[134:137], v[180:183], v[114:117]
	v_mfma_f32_16x16x32_bf16 v[66:69], v[142:145], v[180:183], v[66:69]
	v_mfma_f32_16x16x32_bf16 v[110:113], v[134:137], v[190:193], v[110:113]
	v_mfma_f32_16x16x32_bf16 v[78:81], v[142:145], v[190:193], v[78:81]
	s_barrier
	ds_read_b128 v[194:197], v189 offset:49152
	ds_read_b128 v[198:201], v189 offset:50176
	ds_read_b128 v[202:205], v189 offset:51200
	ds_read_b128 v[206:209], v189 offset:52224
	s_add_u32 s98, s90, s40
	s_addc_u32 s99, s91, s41
	global_load_lds_dwordx4 v160, s[98:99]
	s_add_i32 m0, s39, 0x1a000
	s_nop 0
	global_load_lds_dwordx4 v156, s[98:99]
	s_barrier
	s_waitcnt lgkmcnt(0)
	v_mfma_f32_16x16x32_bf16 v[118:121], v[194:197], v[146:149], v[118:121]
	v_mfma_f32_16x16x32_bf16 v[94:97], v[202:205], v[146:149], v[94:97]
	v_mfma_f32_16x16x32_bf16 v[106:109], v[194:197], v[168:171], v[106:109]
	v_mfma_f32_16x16x32_bf16 v[90:93], v[202:205], v[168:171], v[90:93]
	v_mfma_f32_16x16x32_bf16 v[102:105], v[194:197], v[176:179], v[102:105]
	v_mfma_f32_16x16x32_bf16 v[82:85], v[202:205], v[176:179], v[82:85]
	v_mfma_f32_16x16x32_bf16 v[98:101], v[194:197], v[184:187], v[98:101]
	v_mfma_f32_16x16x32_bf16 v[86:89], v[202:205], v[184:187], v[86:89]
	v_mfma_f32_16x16x32_bf16 v[118:121], v[198:201], v[150:153], v[118:121]
	v_mfma_f32_16x16x32_bf16 v[94:97], v[206:209], v[150:153], v[94:97]
	v_mfma_f32_16x16x32_bf16 v[106:109], v[198:201], v[172:175], v[106:109]
	v_mfma_f32_16x16x32_bf16 v[90:93], v[206:209], v[172:175], v[90:93]
	v_mfma_f32_16x16x32_bf16 v[102:105], v[198:201], v[180:183], v[102:105]
	v_mfma_f32_16x16x32_bf16 v[82:85], v[206:209], v[180:183], v[82:85]
	v_mfma_f32_16x16x32_bf16 v[98:101], v[198:201], v[190:193], v[98:101]
	v_mfma_f32_16x16x32_bf16 v[86:89], v[206:209], v[190:193], v[86:89]
	s_mov_b32 m0, s95
	s_barrier
	ds_read_b128 v[146:149], v253 offset:49152
	ds_read_b128 v[150:153], v253 offset:50176
	ds_read_b128 v[168:171], v253 offset:51200
	ds_read_b128 v[172:175], v253 offset:52224
	ds_read_b128 v[176:179], v253 offset:53248
	ds_read_b128 v[180:183], v253 offset:54272
	ds_read_b128 v[184:187], v253 offset:55296
	ds_read_b128 v[190:193], v253 offset:56320
	s_add_u32 s98, s100, s40
	s_addc_u32 s99, s101, s41
	global_load_lds_dwordx4 v162, s[98:99]
	s_mov_b32 m0, s96
	s_nop 0
	global_load_lds_dwordx4 v158, s[98:99]
	s_waitcnt vmcnt(10)
	s_barrier
	s_waitcnt lgkmcnt(0)
	v_mfma_f32_16x16x32_bf16 v[62:65], v[130:133], v[146:149], v[62:65]
	v_mfma_f32_16x16x32_bf16 v[10:13], v[138:141], v[146:149], v[10:13]
	v_mfma_f32_16x16x32_bf16 v[58:61], v[130:133], v[168:171], v[58:61]
	v_mfma_f32_16x16x32_bf16 v[14:17], v[138:141], v[168:171], v[14:17]
	v_mfma_f32_16x16x32_bf16 v[54:57], v[130:133], v[176:179], v[54:57]
	v_mfma_f32_16x16x32_bf16 v[6:9], v[138:141], v[176:179], v[6:9]
	v_mfma_f32_16x16x32_bf16 v[42:45], v[130:133], v[184:187], v[42:45]
	v_mfma_f32_16x16x32_bf16 v[2:5], v[138:141], v[184:187], v[2:5]
	v_mfma_f32_16x16x32_bf16 v[62:65], v[134:137], v[150:153], v[62:65]
	s_add_u32 s6, s90, 0x40080
	s_addc_u32 s7, s91, 0
	v_mfma_f32_16x16x32_bf16 v[10:13], v[142:145], v[150:153], v[10:13]
	s_add_i32 m0, s39, 0x1c000
	v_mfma_f32_16x16x32_bf16 v[58:61], v[134:137], v[172:175], v[58:61]
	v_mfma_f32_16x16x32_bf16 v[14:17], v[142:145], v[172:175], v[14:17]
	v_mfma_f32_16x16x32_bf16 v[54:57], v[134:137], v[180:183], v[54:57]
	v_mfma_f32_16x16x32_bf16 v[6:9], v[142:145], v[180:183], v[6:9]
	v_mfma_f32_16x16x32_bf16 v[42:45], v[134:137], v[190:193], v[42:45]
	v_mfma_f32_16x16x32_bf16 v[2:5], v[142:145], v[190:193], v[2:5]
	s_barrier
	s_nop 0
	global_load_lds_dwordx4 v160, s[6:7]
	s_add_i32 m0, s39, 0x1e000
	s_nop 0
	global_load_lds_dwordx4 v156, s[6:7]
	ds_read_b128 v[130:133], v189
	ds_read_b128 v[134:137], v189 offset:1024
	ds_read_b128 v[138:141], v189 offset:2048
	ds_read_b128 v[142:145], v189 offset:3072
	s_waitcnt vmcnt(6)
	s_barrier
	v_mfma_f32_16x16x32_bf16 v[50:53], v[194:197], v[146:149], v[50:53]
	v_mfma_f32_16x16x32_bf16 v[26:29], v[202:205], v[146:149], v[26:29]
	v_mfma_f32_16x16x32_bf16 v[46:49], v[194:197], v[168:171], v[46:49]
	v_mfma_f32_16x16x32_bf16 v[30:33], v[202:205], v[168:171], v[30:33]
	v_mfma_f32_16x16x32_bf16 v[38:41], v[194:197], v[176:179], v[38:41]
	v_mfma_f32_16x16x32_bf16 v[22:25], v[202:205], v[176:179], v[22:25]
	v_mfma_f32_16x16x32_bf16 v[34:37], v[194:197], v[184:187], v[34:37]
	v_mfma_f32_16x16x32_bf16 v[18:21], v[202:205], v[184:187], v[18:21]
	v_mfma_f32_16x16x32_bf16 v[50:53], v[198:201], v[150:153], v[50:53]
	s_add_i32 s45, s45, 2
	s_add_u32 s28, s28, 0x100
	v_mfma_f32_16x16x32_bf16 v[26:29], v[206:209], v[150:153], v[26:29]
	s_addc_u32 s29, s29, 0
	s_mov_b64 s[6:7], s[88:89]
	v_mfma_f32_16x16x32_bf16 v[46:49], v[198:201], v[172:175], v[46:49]
	s_add_u32 s88, s6, 0x100
	s_addc_u32 s89, s7, 0
	v_mfma_f32_16x16x32_bf16 v[30:33], v[206:209], v[172:175], v[30:33]
	s_cmp_eq_u32 s45, 12
	s_cselect_b32 s93, s17, s89
	v_mfma_f32_16x16x32_bf16 v[38:41], v[198:201], v[180:183], v[38:41]
	s_cselect_b32 s92, s22, s88
	s_cselect_b32 s91, s15, s29
	v_mfma_f32_16x16x32_bf16 v[22:25], v[206:209], v[180:183], v[22:25]
	s_cselect_b32 s90, s23, s28
	s_cmp_gt_u32 s45, 13
	v_mfma_f32_16x16x32_bf16 v[34:37], v[198:201], v[190:193], v[34:37]
	v_mfma_f32_16x16x32_bf16 v[18:21], v[206:209], v[190:193], v[18:21]
	s_barrier
	.p2align 3
.LBB0_919:
	s_add_i32 m0, s43, 0xc000
	ds_read_b128 v[146:149], v253
	ds_read_b128 v[150:153], v253 offset:1024
	ds_read_b128 v[168:171], v253 offset:2048
	ds_read_b128 v[172:175], v253 offset:3072
	ds_read_b128 v[176:179], v253 offset:4096
	ds_read_b128 v[180:183], v253 offset:5120
	ds_read_b128 v[184:187], v253 offset:6144
	ds_read_b128 v[190:193], v253 offset:7168
	global_load_lds_dwordx4 v164, s[6:7]
	s_add_i32 m0, s43, 0xe000
	v_lshl_add_u64 v[154:155], s[6:7], 0, v[166:167]
	global_load_lds_dwordx4 v[154:155], off
	s_waitcnt lgkmcnt(8)
	s_barrier
	s_waitcnt lgkmcnt(0)
	v_mfma_f32_16x16x32_bf16 v[126:129], v[130:133], v[146:149], v[126:129]
	v_mfma_f32_16x16x32_bf16 v[70:73], v[138:141], v[146:149], v[70:73]
	v_mfma_f32_16x16x32_bf16 v[122:125], v[130:133], v[168:171], v[122:125]
	v_mfma_f32_16x16x32_bf16 v[74:77], v[138:141], v[168:171], v[74:77]
	v_mfma_f32_16x16x32_bf16 v[114:117], v[130:133], v[176:179], v[114:117]
	v_mfma_f32_16x16x32_bf16 v[66:69], v[138:141], v[176:179], v[66:69]
	v_mfma_f32_16x16x32_bf16 v[110:113], v[130:133], v[184:187], v[110:113]
	v_mfma_f32_16x16x32_bf16 v[78:81], v[138:141], v[184:187], v[78:81]
	v_mfma_f32_16x16x32_bf16 v[126:129], v[134:137], v[150:153], v[126:129]
	s_add_i32 m0, s39, 0x10000
	v_mfma_f32_16x16x32_bf16 v[70:73], v[142:145], v[150:153], v[70:73]
	v_mfma_f32_16x16x32_bf16 v[122:125], v[134:137], v[172:175], v[122:125]
	v_mfma_f32_16x16x32_bf16 v[74:77], v[142:145], v[172:175], v[74:77]
	v_mfma_f32_16x16x32_bf16 v[114:117], v[134:137], v[180:183], v[114:117]
	v_mfma_f32_16x16x32_bf16 v[66:69], v[142:145], v[180:183], v[66:69]
	v_mfma_f32_16x16x32_bf16 v[110:113], v[134:137], v[190:193], v[110:113]
	v_mfma_f32_16x16x32_bf16 v[78:81], v[142:145], v[190:193], v[78:81]
	s_barrier
	ds_read_b128 v[194:197], v189 offset:16384
	ds_read_b128 v[198:201], v189 offset:17408
	ds_read_b128 v[202:205], v189 offset:18432
	global_load_lds_dwordx4 v160, s[90:91]
	s_add_i32 m0, s39, 0x12000
	ds_read_b128 v[206:209], v189 offset:19456
	global_load_lds_dwordx4 v156, s[90:91]
	s_barrier
	s_waitcnt lgkmcnt(0)
	v_mfma_f32_16x16x32_bf16 v[118:121], v[194:197], v[146:149], v[118:121]
	v_mfma_f32_16x16x32_bf16 v[94:97], v[202:205], v[146:149], v[94:97]
	v_mfma_f32_16x16x32_bf16 v[106:109], v[194:197], v[168:171], v[106:109]
	v_mfma_f32_16x16x32_bf16 v[90:93], v[202:205], v[168:171], v[90:93]
	v_mfma_f32_16x16x32_bf16 v[102:105], v[194:197], v[176:179], v[102:105]
	v_mfma_f32_16x16x32_bf16 v[82:85], v[202:205], v[176:179], v[82:85]
	v_mfma_f32_16x16x32_bf16 v[98:101], v[194:197], v[184:187], v[98:101]
	v_mfma_f32_16x16x32_bf16 v[86:89], v[202:205], v[184:187], v[86:89]
	v_mfma_f32_16x16x32_bf16 v[118:121], v[198:201], v[150:153], v[118:121]
	v_mfma_f32_16x16x32_bf16 v[94:97], v[206:209], v[150:153], v[94:97]
	v_mfma_f32_16x16x32_bf16 v[106:109], v[198:201], v[172:175], v[106:109]
	v_mfma_f32_16x16x32_bf16 v[90:93], v[206:209], v[172:175], v[90:93]
	v_mfma_f32_16x16x32_bf16 v[102:105], v[198:201], v[180:183], v[102:105]
	v_mfma_f32_16x16x32_bf16 v[82:85], v[206:209], v[180:183], v[82:85]
	v_mfma_f32_16x16x32_bf16 v[98:101], v[198:201], v[190:193], v[98:101]
	v_mfma_f32_16x16x32_bf16 v[86:89], v[206:209], v[190:193], v[86:89]
	s_mov_b32 m0, s43
	s_mov_b64 s[100:101], s[92:93]
	s_barrier
	ds_read_b128 v[146:149], v253 offset:16384
	ds_read_b128 v[150:153], v253 offset:17408
	ds_read_b128 v[168:171], v253 offset:18432
	ds_read_b128 v[172:175], v253 offset:19456
	ds_read_b128 v[176:179], v253 offset:20480
	ds_read_b128 v[180:183], v253 offset:21504
	ds_read_b128 v[184:187], v253 offset:22528
	global_load_lds_dwordx4 v162, s[100:101]
	s_mov_b32 m0, s60
	ds_read_b128 v[190:193], v253 offset:23552
	global_load_lds_dwordx4 v158, s[100:101]
	s_waitcnt vmcnt(10)
	s_barrier
	s_waitcnt lgkmcnt(0)
	v_mfma_f32_16x16x32_bf16 v[62:65], v[130:133], v[146:149], v[62:65]
	v_mfma_f32_16x16x32_bf16 v[10:13], v[138:141], v[146:149], v[10:13]
	v_mfma_f32_16x16x32_bf16 v[58:61], v[130:133], v[168:171], v[58:61]
	v_mfma_f32_16x16x32_bf16 v[14:17], v[138:141], v[168:171], v[14:17]
	v_mfma_f32_16x16x32_bf16 v[54:57], v[130:133], v[176:179], v[54:57]
	v_mfma_f32_16x16x32_bf16 v[6:9], v[138:141], v[176:179], v[6:9]
	v_mfma_f32_16x16x32_bf16 v[42:45], v[130:133], v[184:187], v[42:45]
	v_mfma_f32_16x16x32_bf16 v[2:5], v[138:141], v[184:187], v[2:5]
	v_mfma_f32_16x16x32_bf16 v[62:65], v[134:137], v[150:153], v[62:65]
	s_add_u32 s6, s90, 0x40000
	s_addc_u32 s7, s91, 0
	v_mfma_f32_16x16x32_bf16 v[10:13], v[142:145], v[150:153], v[10:13]
	s_add_i32 m0, s39, 0x14000
	v_mfma_f32_16x16x32_bf16 v[58:61], v[134:137], v[172:175], v[58:61]
	v_mfma_f32_16x16x32_bf16 v[14:17], v[142:145], v[172:175], v[14:17]
	v_mfma_f32_16x16x32_bf16 v[54:57], v[134:137], v[180:183], v[54:57]
	v_mfma_f32_16x16x32_bf16 v[6:9], v[142:145], v[180:183], v[6:9]
	v_mfma_f32_16x16x32_bf16 v[42:45], v[134:137], v[190:193], v[42:45]
	v_mfma_f32_16x16x32_bf16 v[2:5], v[142:145], v[190:193], v[2:5]
	s_barrier
	s_nop 0
	global_load_lds_dwordx4 v160, s[6:7]
	s_add_i32 m0, s39, 0x16000
	s_nop 0
	global_load_lds_dwordx4 v156, s[6:7]
	ds_read_b128 v[130:133], v189 offset:32768
	ds_read_b128 v[134:137], v189 offset:33792
	ds_read_b128 v[138:141], v189 offset:34816
	ds_read_b128 v[142:145], v189 offset:35840
	s_waitcnt vmcnt(6)
	s_barrier
	v_mfma_f32_16x16x32_bf16 v[50:53], v[194:197], v[146:149], v[50:53]
	v_mfma_f32_16x16x32_bf16 v[26:29], v[202:205], v[146:149], v[26:29]
	v_mfma_f32_16x16x32_bf16 v[46:49], v[194:197], v[168:171], v[46:49]
	v_mfma_f32_16x16x32_bf16 v[30:33], v[202:205], v[168:171], v[30:33]
	v_mfma_f32_16x16x32_bf16 v[38:41], v[194:197], v[176:179], v[38:41]
	v_mfma_f32_16x16x32_bf16 v[22:25], v[202:205], v[176:179], v[22:25]
	v_mfma_f32_16x16x32_bf16 v[34:37], v[194:197], v[184:187], v[34:37]
	v_mfma_f32_16x16x32_bf16 v[18:21], v[202:205], v[184:187], v[18:21]
	v_mfma_f32_16x16x32_bf16 v[50:53], v[198:201], v[150:153], v[50:53]
	s_add_u32 s6, s92, 0x40000
	s_addc_u32 s7, s93, 0
	v_mfma_f32_16x16x32_bf16 v[26:29], v[206:209], v[150:153], v[26:29]
	s_mov_b32 m0, s61
	v_mfma_f32_16x16x32_bf16 v[46:49], v[198:201], v[172:175], v[46:49]
	v_mfma_f32_16x16x32_bf16 v[30:33], v[206:209], v[172:175], v[30:33]
	v_mfma_f32_16x16x32_bf16 v[38:41], v[198:201], v[180:183], v[38:41]
	v_mfma_f32_16x16x32_bf16 v[22:25], v[206:209], v[180:183], v[22:25]
	v_mfma_f32_16x16x32_bf16 v[34:37], v[198:201], v[190:193], v[34:37]
	v_mfma_f32_16x16x32_bf16 v[18:21], v[206:209], v[190:193], v[18:21]
	s_barrier
	ds_read_b128 v[146:149], v253 offset:32768
	ds_read_b128 v[150:153], v253 offset:33792
	ds_read_b128 v[168:171], v253 offset:34816
	ds_read_b128 v[172:175], v253 offset:35840
	ds_read_b128 v[176:179], v253 offset:36864
	ds_read_b128 v[180:183], v253 offset:37888
	ds_read_b128 v[184:187], v253 offset:38912
	global_load_lds_dwordx4 v162, s[6:7]
	s_mov_b32 m0, s72
	ds_read_b128 v[190:193], v253 offset:39936
	global_load_lds_dwordx4 v158, s[6:7]
	s_waitcnt lgkmcnt(8)
	s_barrier
	s_waitcnt lgkmcnt(0)
	v_mfma_f32_16x16x32_bf16 v[126:129], v[130:133], v[146:149], v[126:129]
	v_mfma_f32_16x16x32_bf16 v[70:73], v[138:141], v[146:149], v[70:73]
	v_mfma_f32_16x16x32_bf16 v[122:125], v[130:133], v[168:171], v[122:125]
	v_mfma_f32_16x16x32_bf16 v[74:77], v[138:141], v[168:171], v[74:77]
	v_mfma_f32_16x16x32_bf16 v[114:117], v[130:133], v[176:179], v[114:117]
	v_mfma_f32_16x16x32_bf16 v[66:69], v[138:141], v[176:179], v[66:69]
	v_mfma_f32_16x16x32_bf16 v[110:113], v[130:133], v[184:187], v[110:113]
	v_mfma_f32_16x16x32_bf16 v[78:81], v[138:141], v[184:187], v[78:81]
	v_mfma_f32_16x16x32_bf16 v[126:129], v[134:137], v[150:153], v[126:129]
	s_add_i32 m0, s39, 0x18000
	v_mfma_f32_16x16x32_bf16 v[70:73], v[142:145], v[150:153], v[70:73]
	v_mfma_f32_16x16x32_bf16 v[122:125], v[134:137], v[172:175], v[122:125]
	v_mfma_f32_16x16x32_bf16 v[74:77], v[142:145], v[172:175], v[74:77]
	v_mfma_f32_16x16x32_bf16 v[114:117], v[134:137], v[180:183], v[114:117]
	v_mfma_f32_16x16x32_bf16 v[66:69], v[142:145], v[180:183], v[66:69]
	v_mfma_f32_16x16x32_bf16 v[110:113], v[134:137], v[190:193], v[110:113]
	v_mfma_f32_16x16x32_bf16 v[78:81], v[142:145], v[190:193], v[78:81]
	s_barrier
	ds_read_b128 v[194:197], v189 offset:49152
	ds_read_b128 v[198:201], v189 offset:50176
	ds_read_b128 v[202:205], v189 offset:51200
	ds_read_b128 v[206:209], v189 offset:52224
	s_add_u32 s98, s90, s40
	s_addc_u32 s99, s91, s41
	global_load_lds_dwordx4 v160, s[98:99]
	s_add_i32 m0, s39, 0x1a000
	s_nop 0
	global_load_lds_dwordx4 v156, s[98:99]
	s_barrier
	s_waitcnt lgkmcnt(0)
	v_mfma_f32_16x16x32_bf16 v[118:121], v[194:197], v[146:149], v[118:121]
	v_mfma_f32_16x16x32_bf16 v[94:97], v[202:205], v[146:149], v[94:97]
	v_mfma_f32_16x16x32_bf16 v[106:109], v[194:197], v[168:171], v[106:109]
	v_mfma_f32_16x16x32_bf16 v[90:93], v[202:205], v[168:171], v[90:93]
	v_mfma_f32_16x16x32_bf16 v[102:105], v[194:197], v[176:179], v[102:105]
	v_mfma_f32_16x16x32_bf16 v[82:85], v[202:205], v[176:179], v[82:85]
	v_mfma_f32_16x16x32_bf16 v[98:101], v[194:197], v[184:187], v[98:101]
	v_mfma_f32_16x16x32_bf16 v[86:89], v[202:205], v[184:187], v[86:89]
	v_mfma_f32_16x16x32_bf16 v[118:121], v[198:201], v[150:153], v[118:121]
	v_mfma_f32_16x16x32_bf16 v[94:97], v[206:209], v[150:153], v[94:97]
	v_mfma_f32_16x16x32_bf16 v[106:109], v[198:201], v[172:175], v[106:109]
	v_mfma_f32_16x16x32_bf16 v[90:93], v[206:209], v[172:175], v[90:93]
	v_mfma_f32_16x16x32_bf16 v[102:105], v[198:201], v[180:183], v[102:105]
	v_mfma_f32_16x16x32_bf16 v[82:85], v[206:209], v[180:183], v[82:85]
	v_mfma_f32_16x16x32_bf16 v[98:101], v[198:201], v[190:193], v[98:101]
	v_mfma_f32_16x16x32_bf16 v[86:89], v[206:209], v[190:193], v[86:89]
	s_mov_b32 m0, s95
	s_barrier
	ds_read_b128 v[146:149], v253 offset:49152
	ds_read_b128 v[150:153], v253 offset:50176
	ds_read_b128 v[168:171], v253 offset:51200
	ds_read_b128 v[172:175], v253 offset:52224
	ds_read_b128 v[176:179], v253 offset:53248
	ds_read_b128 v[180:183], v253 offset:54272
	ds_read_b128 v[184:187], v253 offset:55296
	ds_read_b128 v[190:193], v253 offset:56320
	s_add_u32 s98, s100, s40
	s_addc_u32 s99, s101, s41
	global_load_lds_dwordx4 v162, s[98:99]
	s_mov_b32 m0, s96
	s_nop 0
	global_load_lds_dwordx4 v158, s[98:99]
	s_waitcnt vmcnt(10)
	s_barrier
	s_waitcnt lgkmcnt(0)
	v_mfma_f32_16x16x32_bf16 v[62:65], v[130:133], v[146:149], v[62:65]
	v_mfma_f32_16x16x32_bf16 v[10:13], v[138:141], v[146:149], v[10:13]
	v_mfma_f32_16x16x32_bf16 v[58:61], v[130:133], v[168:171], v[58:61]
	v_mfma_f32_16x16x32_bf16 v[14:17], v[138:141], v[168:171], v[14:17]
	v_mfma_f32_16x16x32_bf16 v[54:57], v[130:133], v[176:179], v[54:57]
	v_mfma_f32_16x16x32_bf16 v[6:9], v[138:141], v[176:179], v[6:9]
	v_mfma_f32_16x16x32_bf16 v[42:45], v[130:133], v[184:187], v[42:45]
	v_mfma_f32_16x16x32_bf16 v[2:5], v[138:141], v[184:187], v[2:5]
	v_mfma_f32_16x16x32_bf16 v[62:65], v[134:137], v[150:153], v[62:65]
	s_add_u32 s6, s90, 0x40080
	s_addc_u32 s7, s91, 0
	v_mfma_f32_16x16x32_bf16 v[10:13], v[142:145], v[150:153], v[10:13]
	s_add_i32 m0, s39, 0x1c000
	v_mfma_f32_16x16x32_bf16 v[58:61], v[134:137], v[172:175], v[58:61]
	v_mfma_f32_16x16x32_bf16 v[14:17], v[142:145], v[172:175], v[14:17]
	v_mfma_f32_16x16x32_bf16 v[54:57], v[134:137], v[180:183], v[54:57]
	v_mfma_f32_16x16x32_bf16 v[6:9], v[142:145], v[180:183], v[6:9]
	v_mfma_f32_16x16x32_bf16 v[42:45], v[134:137], v[190:193], v[42:45]
	v_mfma_f32_16x16x32_bf16 v[2:5], v[142:145], v[190:193], v[2:5]
	s_barrier
	s_nop 0
	global_load_lds_dwordx4 v160, s[6:7]
	s_add_i32 m0, s39, 0x1e000
	s_nop 0
	global_load_lds_dwordx4 v156, s[6:7]
	ds_read_b128 v[130:133], v189
	ds_read_b128 v[134:137], v189 offset:1024
	ds_read_b128 v[138:141], v189 offset:2048
	ds_read_b128 v[142:145], v189 offset:3072
	s_waitcnt vmcnt(6)
	s_barrier
	v_mfma_f32_16x16x32_bf16 v[50:53], v[194:197], v[146:149], v[50:53]
	v_mfma_f32_16x16x32_bf16 v[26:29], v[202:205], v[146:149], v[26:29]
	v_mfma_f32_16x16x32_bf16 v[46:49], v[194:197], v[168:171], v[46:49]
	v_mfma_f32_16x16x32_bf16 v[30:33], v[202:205], v[168:171], v[30:33]
	v_mfma_f32_16x16x32_bf16 v[38:41], v[194:197], v[176:179], v[38:41]
	v_mfma_f32_16x16x32_bf16 v[22:25], v[202:205], v[176:179], v[22:25]
	v_mfma_f32_16x16x32_bf16 v[34:37], v[194:197], v[184:187], v[34:37]
	v_mfma_f32_16x16x32_bf16 v[18:21], v[202:205], v[184:187], v[18:21]
	v_mfma_f32_16x16x32_bf16 v[50:53], v[198:201], v[150:153], v[50:53]
	s_add_i32 s45, s45, 2
	s_add_u32 s28, s28, 0x100
	v_mfma_f32_16x16x32_bf16 v[26:29], v[206:209], v[150:153], v[26:29]
	s_addc_u32 s29, s29, 0
	s_mov_b64 s[6:7], s[88:89]
	v_mfma_f32_16x16x32_bf16 v[46:49], v[198:201], v[172:175], v[46:49]
	s_add_u32 s88, s6, 0x100
	s_addc_u32 s89, s7, 0
	v_mfma_f32_16x16x32_bf16 v[30:33], v[206:209], v[172:175], v[30:33]
	s_cmp_eq_u32 s45, 12
	s_cselect_b32 s93, s17, s89
	v_mfma_f32_16x16x32_bf16 v[38:41], v[198:201], v[180:183], v[38:41]
	s_cselect_b32 s92, s22, s88
	s_cselect_b32 s91, s15, s29
	v_mfma_f32_16x16x32_bf16 v[22:25], v[206:209], v[180:183], v[22:25]
	s_cselect_b32 s90, s23, s28
	s_cmp_gt_u32 s45, 13
	v_mfma_f32_16x16x32_bf16 v[34:37], v[198:201], v[190:193], v[34:37]
	v_mfma_f32_16x16x32_bf16 v[18:21], v[206:209], v[190:193], v[18:21]
	s_barrier
	s_cbranch_scc0 .LBB0_919
	s_waitcnt lgkmcnt(0)
	v_mov_b32_e32 v131, v252
	s_lshl_b32 s88, s5, 7
	v_bfe_u32 v130, v131, 4, 2
	v_and_b32_e32 v134, 15, v131
	v_lshlrev_b32_e32 v0, 4, v130
	s_ashr_i32 s89, s88, 31
	s_lshl_b32 s15, s4, 8
	v_or3_b32 v135, v0, s97, v134
	s_lshl_b64 s[4:5], s[88:89], 2
	v_lshrrev_b32_e32 v140, 1, v135
	s_add_u32 s4, s73, s4
	s_addc_u32 s5, s74, s5
	v_lshlrev_b32_e32 v0, 2, v140
	v_and_b32_e32 v144, 1, v131
	v_lshl_add_u64 v[132:133], s[4:5], 0, v[0:1]
	v_cmp_eq_u32_e32 vcc, 1, v144
	v_mov_b32_e32 v0, 0xb00
	s_movk_i32 s4, 0x5000
	v_cndmask_b32_e32 v141, 0, v0, vcc
	v_lshlrev_b32_e32 v0, 2, v141
	v_lshl_add_u64 v[132:133], v[132:133], 0, v[0:1]
	v_add_co_u32_e32 v138, vcc, s4, v132
	s_mov_b32 s4, 0xb000
	s_nop 0
	v_addc_co_u32_e32 v139, vcc, 0, v133, vcc
	global_load_dword v136, v[132:133], off
	global_load_dword v137, v[138:139], off offset:2048
	v_add_co_u32_e32 v132, vcc, s4, v132
	v_add_u32_e32 v0, s88, v141
	s_nop 0
	v_addc_co_u32_e32 v133, vcc, 0, v133, vcc
	global_load_dword v138, v[132:133], off
	v_or_b32_e32 v132, v140, v0
	v_ashrrev_i32_e32 v133, 31, v132
	v_lshl_add_u64 v[132:133], v[132:133], 2, s[12:13]
	global_load_dword v139, v[132:133], off
	v_lshl_add_u32 v152, v135, 4, s78
	v_and_b32_e32 v135, 63, v131
	v_cmp_eq_u32_e32 vcc, 0, v144
	v_or_b32_e32 v0, s97, v135
	v_lshrrev_b32_e32 v0, 1, v0
	v_and_or_b32 v131, v0, 63, s55
	v_add_u32_e32 v132, s15, v131
	v_ashrrev_i32_e32 v133, 31, v132
	v_lshlrev_b64 v[132:133], 6, v[132:133]
	v_lshl_add_u64 v[132:133], s[10:11], 0, v[132:133]
	v_lshlrev_b32_e32 v0, 5, v144
	v_lshl_add_u64 v[132:133], v[132:133], 0, v[0:1]
	global_load_dwordx4 v[148:151], v[132:133], off offset:16
	global_load_dwordx4 v[140:143], v[132:133], off
	s_waitcnt vmcnt(2)
	ds_write_b128 v152, v[136:139]
	s_waitcnt vmcnt(0)
	v_add_f32_e32 v133, v150, v151
	v_add_f32_e32 v0, v140, v141
	v_add_f32_e32 v132, v142, v143
	v_add_f32_e32 v0, v0, v132
	v_add_f32_e32 v132, v148, v149
	v_add_f32_e32 v132, v132, v133
	v_add_f32_e32 v0, v0, v132
	v_lshlrev_b32_e32 v132, 2, v135
	v_xor_b32_e32 v132, 4, v132
	ds_bpermute_b32 v132, v132, v0
	s_and_saveexec_b64 s[4:5], vcc
	s_cbranch_execz .LBB0_922
	s_waitcnt lgkmcnt(0)
	v_add_f32_e32 v0, v0, v132
	v_mov_b32_e32 v132, 0x358637bd
	v_fmamk_f32 v0, v0, 0x3a800000, v132
	s_mov_b32 s6, 0x800000
	v_mul_f32_e32 v132, 0x4b800000, v0
	v_cmp_gt_f32_e32 vcc, s6, v0
	v_lshl_add_u32 v131, v131, 2, 0
	v_add_u32_e32 v131, 0x20000, v131
	v_cndmask_b32_e32 v0, v0, v132, vcc
	v_rsq_f32_e32 v0, v0
	s_nop 0
	v_mul_f32_e32 v132, 0x45800000, v0
	v_cndmask_b32_e32 v0, v0, v132, vcc
	ds_write_b32 v131, v0

.LBB0_1089:
	s_add_u32 s34, s84, 0x100
	s_addc_u32 s78, s85, 0
	s_mov_b32 s79, -2
	s_waitcnt lgkmcnt(0)
	s_add_i32 s90, 0, 0x10000
	v_add_u32_e32 v142, s90, v212
	v_add_u32_e32 v189, 0x10000, v212
	ds_read_b128 v[130:133], v142
	ds_read_b128 v[134:137], v142 offset:1024
	ds_read_b128 v[138:141], v142 offset:2048
	ds_read_b128 v[142:145], v142 offset:3072
	s_add_u32 s84, s16, 0x100
	s_addc_u32 s85, s17, 0
	s_cmp_eq_u32 s79, 40
	s_cselect_b32 s89, s5, s85
	s_cselect_b32 s88, s4, s84
	s_cselect_b32 s87, s7, s78
	s_cselect_b32 s86, s6, s34
	v_lshl_add_u64 v[178:179], s[16:17], 0, v[196:197]
	s_add_i32 m0, s39, 0xc000
	ds_read_b128 v[146:149], v213
	ds_read_b128 v[150:153], v213 offset:1024
	ds_read_b128 v[154:157], v213 offset:2048
	ds_read_b128 v[158:161], v213 offset:3072
	ds_read_b128 v[162:165], v213 offset:4096
	ds_read_b128 v[166:169], v213 offset:5120
	ds_read_b128 v[170:173], v213 offset:6144
	ds_read_b128 v[174:177], v213 offset:7168
	global_load_lds_dwordx4 v[178:179], off
	s_add_i32 m0, s39, 0xe000
	v_lshl_add_u64 v[178:179], s[16:17], 0, v[198:199]
	global_load_lds_dwordx4 v[178:179], off
	s_waitcnt lgkmcnt(8)
	s_barrier
	s_waitcnt lgkmcnt(0)
	v_mfma_f32_16x16x32_bf16 v[126:129], v[130:133], v[146:149], 0
	v_mfma_f32_16x16x32_bf16 v[122:125], v[138:141], v[146:149], 0
	v_mfma_f32_16x16x32_bf16 v[110:113], v[130:133], v[154:157], 0
	v_mfma_f32_16x16x32_bf16 v[106:109], v[138:141], v[154:157], 0
	v_mfma_f32_16x16x32_bf16 v[94:97], v[130:133], v[162:165], 0
	v_mfma_f32_16x16x32_bf16 v[90:93], v[138:141], v[162:165], 0
	v_mfma_f32_16x16x32_bf16 v[78:81], v[130:133], v[170:173], 0
	v_mfma_f32_16x16x32_bf16 v[74:77], v[138:141], v[170:173], 0
	v_mfma_f32_16x16x32_bf16 v[126:129], v[134:137], v[150:153], v[126:129]
	v_mfma_f32_16x16x32_bf16 v[122:125], v[142:145], v[150:153], v[122:125]
	v_mfma_f32_16x16x32_bf16 v[110:113], v[134:137], v[158:161], v[110:113]
	v_mfma_f32_16x16x32_bf16 v[106:109], v[142:145], v[158:161], v[106:109]
	v_mfma_f32_16x16x32_bf16 v[94:97], v[134:137], v[166:169], v[94:97]
	v_mfma_f32_16x16x32_bf16 v[90:93], v[142:145], v[166:169], v[90:93]
	v_mfma_f32_16x16x32_bf16 v[78:81], v[134:137], v[174:177], v[78:81]
	v_mfma_f32_16x16x32_bf16 v[74:77], v[142:145], v[174:177], v[74:77]
	s_barrier
	ds_read_b128 v[178:181], v189 offset:16384
	ds_read_b128 v[182:185], v189 offset:17408
	ds_read_b128 v[200:203], v189 offset:18432
	ds_read_b128 v[204:207], v189 offset:19456
	s_add_i32 m0, s38, 0x10000
	s_nop 0
	global_load_lds_dwordx4 v0, s[86:87]
	s_add_i32 m0, s38, 0x12000
	s_nop 0
	global_load_lds_dwordx4 v194, s[86:87]
	s_barrier
	s_waitcnt lgkmcnt(0)
	v_mfma_f32_16x16x32_bf16 v[118:121], v[178:181], v[146:149], 0
	v_mfma_f32_16x16x32_bf16 v[114:117], v[200:203], v[146:149], 0
	v_mfma_f32_16x16x32_bf16 v[102:105], v[178:181], v[154:157], 0
	v_mfma_f32_16x16x32_bf16 v[98:101], v[200:203], v[154:157], 0
	v_mfma_f32_16x16x32_bf16 v[86:89], v[178:181], v[162:165], 0
	v_mfma_f32_16x16x32_bf16 v[82:85], v[200:203], v[162:165], 0
	v_mfma_f32_16x16x32_bf16 v[70:73], v[178:181], v[170:173], 0
	v_mfma_f32_16x16x32_bf16 v[66:69], v[200:203], v[170:173], 0
	v_mfma_f32_16x16x32_bf16 v[118:121], v[182:185], v[150:153], v[118:121]
	v_mfma_f32_16x16x32_bf16 v[114:117], v[204:207], v[150:153], v[114:117]
	v_mfma_f32_16x16x32_bf16 v[102:105], v[182:185], v[158:161], v[102:105]
	v_mfma_f32_16x16x32_bf16 v[98:101], v[204:207], v[158:161], v[98:101]
	v_mfma_f32_16x16x32_bf16 v[86:89], v[182:185], v[166:169], v[86:89]
	v_mfma_f32_16x16x32_bf16 v[82:85], v[204:207], v[166:169], v[82:85]
	v_mfma_f32_16x16x32_bf16 v[70:73], v[182:185], v[174:177], v[70:73]
	v_mfma_f32_16x16x32_bf16 v[66:69], v[204:207], v[174:177], v[66:69]
	s_mov_b32 m0, s39
	s_mov_b64 s[100:101], s[88:89]
	s_barrier
	ds_read_b128 v[146:149], v213 offset:16384
	ds_read_b128 v[150:153], v213 offset:17408
	ds_read_b128 v[154:157], v213 offset:18432
	ds_read_b128 v[158:161], v213 offset:19456
	ds_read_b128 v[162:165], v213 offset:20480
	ds_read_b128 v[166:169], v213 offset:21504
	ds_read_b128 v[170:173], v213 offset:22528
	global_load_lds_dwordx4 v190, s[100:101]
	s_mov_b32 m0, s42
	ds_read_b128 v[174:177], v213 offset:23552
	global_load_lds_dwordx4 v192, s[100:101]
	s_waitcnt vmcnt(10)
	s_barrier
	s_waitcnt lgkmcnt(0)
	v_mfma_f32_16x16x32_bf16 v[62:65], v[130:133], v[146:149], 0
	v_mfma_f32_16x16x32_bf16 v[58:61], v[138:141], v[146:149], 0
	v_mfma_f32_16x16x32_bf16 v[46:49], v[130:133], v[154:157], 0
	v_mfma_f32_16x16x32_bf16 v[42:45], v[138:141], v[154:157], 0
	v_mfma_f32_16x16x32_bf16 v[30:33], v[130:133], v[162:165], 0
	v_mfma_f32_16x16x32_bf16 v[26:29], v[138:141], v[162:165], 0
	v_mfma_f32_16x16x32_bf16 v[14:17], v[130:133], v[170:173], 0
	v_mfma_f32_16x16x32_bf16 v[10:13], v[138:141], v[170:173], 0
	v_mfma_f32_16x16x32_bf16 v[62:65], v[134:137], v[150:153], v[62:65]
	s_add_u32 s16, s86, 0xb0000
	s_addc_u32 s17, s87, 0
	v_mfma_f32_16x16x32_bf16 v[58:61], v[142:145], v[150:153], v[58:61]
	s_add_i32 m0, s38, 0x14000
	v_mfma_f32_16x16x32_bf16 v[46:49], v[134:137], v[158:161], v[46:49]
	v_mfma_f32_16x16x32_bf16 v[42:45], v[142:145], v[158:161], v[42:45]
	v_mfma_f32_16x16x32_bf16 v[30:33], v[134:137], v[166:169], v[30:33]
	v_mfma_f32_16x16x32_bf16 v[26:29], v[142:145], v[166:169], v[26:29]
	v_mfma_f32_16x16x32_bf16 v[14:17], v[134:137], v[174:177], v[14:17]
	v_mfma_f32_16x16x32_bf16 v[10:13], v[142:145], v[174:177], v[10:13]
	s_barrier
	s_nop 0
	global_load_lds_dwordx4 v0, s[16:17]
	s_add_i32 m0, s38, 0x16000
	s_nop 0
	global_load_lds_dwordx4 v194, s[16:17]
	s_add_i32 s90, 0, 0x18000
	v_add_u32_e32 v142, s90, v212
	ds_read_b128 v[130:133], v142
	ds_read_b128 v[134:137], v142 offset:1024
	ds_read_b128 v[138:141], v142 offset:2048
	ds_read_b128 v[142:145], v142 offset:3072
	s_waitcnt vmcnt(6)
	s_barrier
	v_mfma_f32_16x16x32_bf16 v[54:57], v[178:181], v[146:149], 0
	v_mfma_f32_16x16x32_bf16 v[50:53], v[200:203], v[146:149], 0
	v_mfma_f32_16x16x32_bf16 v[38:41], v[178:181], v[154:157], 0
	v_mfma_f32_16x16x32_bf16 v[34:37], v[200:203], v[154:157], 0
	v_mfma_f32_16x16x32_bf16 v[22:25], v[178:181], v[162:165], 0
	v_mfma_f32_16x16x32_bf16 v[18:21], v[200:203], v[162:165], 0
	v_mfma_f32_16x16x32_bf16 v[6:9], v[178:181], v[170:173], 0
	v_mfma_f32_16x16x32_bf16 v[2:5], v[200:203], v[170:173], 0
	v_mfma_f32_16x16x32_bf16 v[54:57], v[182:185], v[150:153], v[54:57]
	s_add_u32 s16, s88, 0xb0000
	s_addc_u32 s17, s89, 0
	v_mfma_f32_16x16x32_bf16 v[50:53], v[204:207], v[150:153], v[50:53]
	s_mov_b32 m0, s43
	v_mfma_f32_16x16x32_bf16 v[38:41], v[182:185], v[158:161], v[38:41]
	v_mfma_f32_16x16x32_bf16 v[34:37], v[204:207], v[158:161], v[34:37]
	v_mfma_f32_16x16x32_bf16 v[22:25], v[182:185], v[166:169], v[22:25]
	v_mfma_f32_16x16x32_bf16 v[18:21], v[204:207], v[166:169], v[18:21]
	v_mfma_f32_16x16x32_bf16 v[6:9], v[182:185], v[174:177], v[6:9]
	v_mfma_f32_16x16x32_bf16 v[2:5], v[204:207], v[174:177], v[2:5]
	s_barrier
	ds_read_b128 v[146:149], v213 offset:32768
	ds_read_b128 v[150:153], v213 offset:33792
	ds_read_b128 v[154:157], v213 offset:34816
	ds_read_b128 v[158:161], v213 offset:35840
	ds_read_b128 v[162:165], v213 offset:36864
	ds_read_b128 v[166:169], v213 offset:37888
	ds_read_b128 v[170:173], v213 offset:38912
	global_load_lds_dwordx4 v190, s[16:17]
	s_mov_b32 m0, s44
	ds_read_b128 v[174:177], v213 offset:39936
	global_load_lds_dwordx4 v192, s[16:17]
	s_waitcnt lgkmcnt(8)
	s_barrier
	s_waitcnt lgkmcnt(0)
	v_mfma_f32_16x16x32_bf16 v[126:129], v[130:133], v[146:149], v[126:129]
	v_mfma_f32_16x16x32_bf16 v[122:125], v[138:141], v[146:149], v[122:125]
	v_mfma_f32_16x16x32_bf16 v[110:113], v[130:133], v[154:157], v[110:113]
	v_mfma_f32_16x16x32_bf16 v[106:109], v[138:141], v[154:157], v[106:109]
	v_mfma_f32_16x16x32_bf16 v[94:97], v[130:133], v[162:165], v[94:97]
	v_mfma_f32_16x16x32_bf16 v[90:93], v[138:141], v[162:165], v[90:93]
	v_mfma_f32_16x16x32_bf16 v[78:81], v[130:133], v[170:173], v[78:81]
	v_mfma_f32_16x16x32_bf16 v[74:77], v[138:141], v[170:173], v[74:77]
	v_mfma_f32_16x16x32_bf16 v[126:129], v[134:137], v[150:153], v[126:129]
	s_add_i32 s88, 0, 0x1c000
	v_mfma_f32_16x16x32_bf16 v[122:125], v[142:145], v[150:153], v[122:125]
	v_mfma_f32_16x16x32_bf16 v[110:113], v[134:137], v[158:161], v[110:113]
	v_mfma_f32_16x16x32_bf16 v[106:109], v[142:145], v[158:161], v[106:109]
	v_mfma_f32_16x16x32_bf16 v[94:97], v[134:137], v[166:169], v[94:97]
	v_mfma_f32_16x16x32_bf16 v[90:93], v[142:145], v[166:169], v[90:93]
	v_mfma_f32_16x16x32_bf16 v[78:81], v[134:137], v[174:177], v[78:81]
	v_mfma_f32_16x16x32_bf16 v[74:77], v[142:145], v[174:177], v[74:77]
	s_barrier
	v_add_u32_e32 v204, s88, v212
	s_add_i32 m0, s38, 0x18000
	ds_read_b128 v[178:181], v204
	ds_read_b128 v[182:185], v204 offset:1024
	ds_read_b128 v[200:203], v204 offset:2048
	ds_read_b128 v[204:207], v204 offset:3072
	s_add_u32 s98, s86, s40
	s_addc_u32 s99, s87, s41
	global_load_lds_dwordx4 v0, s[98:99]
	s_add_i32 m0, s38, 0x1a000
	s_nop 0
	global_load_lds_dwordx4 v194, s[98:99]
	s_barrier
	s_waitcnt lgkmcnt(0)
	v_mfma_f32_16x16x32_bf16 v[118:121], v[178:181], v[146:149], v[118:121]
	v_mfma_f32_16x16x32_bf16 v[114:117], v[200:203], v[146:149], v[114:117]
	v_mfma_f32_16x16x32_bf16 v[102:105], v[178:181], v[154:157], v[102:105]
	v_mfma_f32_16x16x32_bf16 v[98:101], v[200:203], v[154:157], v[98:101]
	v_mfma_f32_16x16x32_bf16 v[86:89], v[178:181], v[162:165], v[86:89]
	v_mfma_f32_16x16x32_bf16 v[82:85], v[200:203], v[162:165], v[82:85]
	v_mfma_f32_16x16x32_bf16 v[70:73], v[178:181], v[170:173], v[70:73]
	v_mfma_f32_16x16x32_bf16 v[66:69], v[200:203], v[170:173], v[66:69]
	v_mfma_f32_16x16x32_bf16 v[118:121], v[182:185], v[150:153], v[118:121]
	v_mfma_f32_16x16x32_bf16 v[114:117], v[204:207], v[150:153], v[114:117]
	v_mfma_f32_16x16x32_bf16 v[102:105], v[182:185], v[158:161], v[102:105]
	v_mfma_f32_16x16x32_bf16 v[98:101], v[204:207], v[158:161], v[98:101]
	v_mfma_f32_16x16x32_bf16 v[86:89], v[182:185], v[166:169], v[86:89]
	v_mfma_f32_16x16x32_bf16 v[82:85], v[204:207], v[166:169], v[82:85]
	v_mfma_f32_16x16x32_bf16 v[70:73], v[182:185], v[174:177], v[70:73]
	v_mfma_f32_16x16x32_bf16 v[66:69], v[204:207], v[174:177], v[66:69]
	s_mov_b32 m0, s60
	s_barrier
	ds_read_b128 v[146:149], v213 offset:49152
	ds_read_b128 v[150:153], v213 offset:50176
	ds_read_b128 v[154:157], v213 offset:51200
	ds_read_b128 v[158:161], v213 offset:52224
	ds_read_b128 v[162:165], v213 offset:53248
	ds_read_b128 v[166:169], v213 offset:54272
	ds_read_b128 v[170:173], v213 offset:55296
	ds_read_b128 v[174:177], v213 offset:56320
	s_add_u32 s98, s100, s40
	s_addc_u32 s99, s101, s41
	global_load_lds_dwordx4 v190, s[98:99]
	s_mov_b32 m0, s61
	s_nop 0
	global_load_lds_dwordx4 v192, s[98:99]
	s_waitcnt vmcnt(10)
	s_barrier
	s_waitcnt lgkmcnt(0)
	v_mfma_f32_16x16x32_bf16 v[62:65], v[130:133], v[146:149], v[62:65]
	v_mfma_f32_16x16x32_bf16 v[58:61], v[138:141], v[146:149], v[58:61]
	v_mfma_f32_16x16x32_bf16 v[46:49], v[130:133], v[154:157], v[46:49]
	v_mfma_f32_16x16x32_bf16 v[42:45], v[138:141], v[154:157], v[42:45]
	v_mfma_f32_16x16x32_bf16 v[30:33], v[130:133], v[162:165], v[30:33]
	v_mfma_f32_16x16x32_bf16 v[26:29], v[138:141], v[162:165], v[26:29]
	v_mfma_f32_16x16x32_bf16 v[14:17], v[130:133], v[170:173], v[14:17]
	v_mfma_f32_16x16x32_bf16 v[10:13], v[138:141], v[170:173], v[10:13]
	v_mfma_f32_16x16x32_bf16 v[62:65], v[134:137], v[150:153], v[62:65]
	s_add_u32 s16, s86, 0xb0080
	s_addc_u32 s17, s87, 0
	v_mfma_f32_16x16x32_bf16 v[58:61], v[142:145], v[150:153], v[58:61]
	s_add_i32 m0, s38, 0x1c000
	v_mfma_f32_16x16x32_bf16 v[46:49], v[134:137], v[158:161], v[46:49]
	v_mfma_f32_16x16x32_bf16 v[42:45], v[142:145], v[158:161], v[42:45]
	v_mfma_f32_16x16x32_bf16 v[30:33], v[134:137], v[166:169], v[30:33]
	v_mfma_f32_16x16x32_bf16 v[26:29], v[142:145], v[166:169], v[26:29]
	v_mfma_f32_16x16x32_bf16 v[14:17], v[134:137], v[174:177], v[14:17]
	v_mfma_f32_16x16x32_bf16 v[10:13], v[142:145], v[174:177], v[10:13]
	s_barrier
	s_nop 0
	global_load_lds_dwordx4 v0, s[16:17]
	s_add_i32 m0, s38, 0x1e000
	s_nop 0
	global_load_lds_dwordx4 v194, s[16:17]
	ds_read_b128 v[130:133], v189
	ds_read_b128 v[134:137], v189 offset:1024
	ds_read_b128 v[138:141], v189 offset:2048
	ds_read_b128 v[142:145], v189 offset:3072
	s_waitcnt vmcnt(6)
	s_barrier
	v_mfma_f32_16x16x32_bf16 v[54:57], v[178:181], v[146:149], v[54:57]
	v_mfma_f32_16x16x32_bf16 v[50:53], v[200:203], v[146:149], v[50:53]
	v_mfma_f32_16x16x32_bf16 v[38:41], v[178:181], v[154:157], v[38:41]
	v_mfma_f32_16x16x32_bf16 v[34:37], v[200:203], v[154:157], v[34:37]
	v_mfma_f32_16x16x32_bf16 v[22:25], v[178:181], v[162:165], v[22:25]
	v_mfma_f32_16x16x32_bf16 v[18:21], v[200:203], v[162:165], v[18:21]
	v_mfma_f32_16x16x32_bf16 v[6:9], v[178:181], v[170:173], v[6:9]
	v_mfma_f32_16x16x32_bf16 v[2:5], v[200:203], v[170:173], v[2:5]
	v_mfma_f32_16x16x32_bf16 v[54:57], v[182:185], v[150:153], v[54:57]
	s_add_i32 s79, s79, 2
	s_add_u32 s34, s34, 0x100
	v_mfma_f32_16x16x32_bf16 v[50:53], v[204:207], v[150:153], v[50:53]
	s_addc_u32 s78, s78, 0
	s_mov_b64 s[16:17], s[84:85]
	v_mfma_f32_16x16x32_bf16 v[38:41], v[182:185], v[158:161], v[38:41]
	s_add_u32 s84, s16, 0x100
	s_addc_u32 s85, s17, 0
	v_mfma_f32_16x16x32_bf16 v[34:37], v[204:207], v[158:161], v[34:37]
	s_cmp_eq_u32 s79, 40
	s_cselect_b32 s89, s5, s85
	v_mfma_f32_16x16x32_bf16 v[22:25], v[182:185], v[166:169], v[22:25]
	s_cselect_b32 s88, s4, s84
	s_cselect_b32 s87, s7, s78
	v_mfma_f32_16x16x32_bf16 v[18:21], v[204:207], v[166:169], v[18:21]
	s_cselect_b32 s86, s6, s34
	s_cmp_gt_u32 s79, 41
	v_mfma_f32_16x16x32_bf16 v[6:9], v[182:185], v[174:177], v[6:9]
	v_mfma_f32_16x16x32_bf16 v[2:5], v[204:207], v[174:177], v[2:5]
	s_barrier
	.p2align 3
.LBB0_1090:
	v_lshl_add_u64 v[178:179], s[16:17], 0, v[196:197]
	s_add_i32 m0, s39, 0xc000
	ds_read_b128 v[146:149], v213
	ds_read_b128 v[150:153], v213 offset:1024
	ds_read_b128 v[154:157], v213 offset:2048
	ds_read_b128 v[158:161], v213 offset:3072
	ds_read_b128 v[162:165], v213 offset:4096
	ds_read_b128 v[166:169], v213 offset:5120
	ds_read_b128 v[170:173], v213 offset:6144
	ds_read_b128 v[174:177], v213 offset:7168
	global_load_lds_dwordx4 v[178:179], off
	s_add_i32 m0, s39, 0xe000
	v_lshl_add_u64 v[178:179], s[16:17], 0, v[198:199]
	global_load_lds_dwordx4 v[178:179], off
	s_waitcnt lgkmcnt(8)
	s_barrier
	s_waitcnt lgkmcnt(0)
	v_mfma_f32_16x16x32_bf16 v[126:129], v[130:133], v[146:149], v[126:129]
	v_mfma_f32_16x16x32_bf16 v[122:125], v[138:141], v[146:149], v[122:125]
	v_mfma_f32_16x16x32_bf16 v[110:113], v[130:133], v[154:157], v[110:113]
	v_mfma_f32_16x16x32_bf16 v[106:109], v[138:141], v[154:157], v[106:109]
	v_mfma_f32_16x16x32_bf16 v[94:97], v[130:133], v[162:165], v[94:97]
	v_mfma_f32_16x16x32_bf16 v[90:93], v[138:141], v[162:165], v[90:93]
	v_mfma_f32_16x16x32_bf16 v[78:81], v[130:133], v[170:173], v[78:81]
	v_mfma_f32_16x16x32_bf16 v[74:77], v[138:141], v[170:173], v[74:77]
	v_mfma_f32_16x16x32_bf16 v[126:129], v[134:137], v[150:153], v[126:129]
	v_mfma_f32_16x16x32_bf16 v[122:125], v[142:145], v[150:153], v[122:125]
	v_mfma_f32_16x16x32_bf16 v[110:113], v[134:137], v[158:161], v[110:113]
	v_mfma_f32_16x16x32_bf16 v[106:109], v[142:145], v[158:161], v[106:109]
	v_mfma_f32_16x16x32_bf16 v[94:97], v[134:137], v[166:169], v[94:97]
	v_mfma_f32_16x16x32_bf16 v[90:93], v[142:145], v[166:169], v[90:93]
	v_mfma_f32_16x16x32_bf16 v[78:81], v[134:137], v[174:177], v[78:81]
	v_mfma_f32_16x16x32_bf16 v[74:77], v[142:145], v[174:177], v[74:77]
	s_barrier
	ds_read_b128 v[178:181], v189 offset:16384
	ds_read_b128 v[182:185], v189 offset:17408
	ds_read_b128 v[200:203], v189 offset:18432
	ds_read_b128 v[204:207], v189 offset:19456
	s_add_i32 m0, s38, 0x10000
	s_nop 0
	global_load_lds_dwordx4 v0, s[86:87]
	s_add_i32 m0, s38, 0x12000
	s_nop 0
	global_load_lds_dwordx4 v194, s[86:87]
	s_barrier
	s_waitcnt lgkmcnt(0)
	v_mfma_f32_16x16x32_bf16 v[118:121], v[178:181], v[146:149], v[118:121]
	v_mfma_f32_16x16x32_bf16 v[114:117], v[200:203], v[146:149], v[114:117]
	v_mfma_f32_16x16x32_bf16 v[102:105], v[178:181], v[154:157], v[102:105]
	v_mfma_f32_16x16x32_bf16 v[98:101], v[200:203], v[154:157], v[98:101]
	v_mfma_f32_16x16x32_bf16 v[86:89], v[178:181], v[162:165], v[86:89]
	v_mfma_f32_16x16x32_bf16 v[82:85], v[200:203], v[162:165], v[82:85]
	v_mfma_f32_16x16x32_bf16 v[70:73], v[178:181], v[170:173], v[70:73]
	v_mfma_f32_16x16x32_bf16 v[66:69], v[200:203], v[170:173], v[66:69]
	v_mfma_f32_16x16x32_bf16 v[118:121], v[182:185], v[150:153], v[118:121]
	v_mfma_f32_16x16x32_bf16 v[114:117], v[204:207], v[150:153], v[114:117]
	v_mfma_f32_16x16x32_bf16 v[102:105], v[182:185], v[158:161], v[102:105]
	v_mfma_f32_16x16x32_bf16 v[98:101], v[204:207], v[158:161], v[98:101]
	v_mfma_f32_16x16x32_bf16 v[86:89], v[182:185], v[166:169], v[86:89]
	v_mfma_f32_16x16x32_bf16 v[82:85], v[204:207], v[166:169], v[82:85]
	v_mfma_f32_16x16x32_bf16 v[70:73], v[182:185], v[174:177], v[70:73]
	v_mfma_f32_16x16x32_bf16 v[66:69], v[204:207], v[174:177], v[66:69]
	s_mov_b32 m0, s39
	s_mov_b64 s[100:101], s[88:89]
	s_barrier
	ds_read_b128 v[146:149], v213 offset:16384
	ds_read_b128 v[150:153], v213 offset:17408
	ds_read_b128 v[154:157], v213 offset:18432
	ds_read_b128 v[158:161], v213 offset:19456
	ds_read_b128 v[162:165], v213 offset:20480
	ds_read_b128 v[166:169], v213 offset:21504
	ds_read_b128 v[170:173], v213 offset:22528
	global_load_lds_dwordx4 v190, s[100:101]
	s_mov_b32 m0, s42
	ds_read_b128 v[174:177], v213 offset:23552
	global_load_lds_dwordx4 v192, s[100:101]
	s_waitcnt vmcnt(10)
	s_barrier
	s_waitcnt lgkmcnt(0)
	v_mfma_f32_16x16x32_bf16 v[62:65], v[130:133], v[146:149], v[62:65]
	v_mfma_f32_16x16x32_bf16 v[58:61], v[138:141], v[146:149], v[58:61]
	v_mfma_f32_16x16x32_bf16 v[46:49], v[130:133], v[154:157], v[46:49]
	v_mfma_f32_16x16x32_bf16 v[42:45], v[138:141], v[154:157], v[42:45]
	v_mfma_f32_16x16x32_bf16 v[30:33], v[130:133], v[162:165], v[30:33]
	v_mfma_f32_16x16x32_bf16 v[26:29], v[138:141], v[162:165], v[26:29]
	v_mfma_f32_16x16x32_bf16 v[14:17], v[130:133], v[170:173], v[14:17]
	v_mfma_f32_16x16x32_bf16 v[10:13], v[138:141], v[170:173], v[10:13]
	v_mfma_f32_16x16x32_bf16 v[62:65], v[134:137], v[150:153], v[62:65]
	s_add_u32 s16, s86, 0xb0000
	s_addc_u32 s17, s87, 0
	v_mfma_f32_16x16x32_bf16 v[58:61], v[142:145], v[150:153], v[58:61]
	s_add_i32 m0, s38, 0x14000
	v_mfma_f32_16x16x32_bf16 v[46:49], v[134:137], v[158:161], v[46:49]
	v_mfma_f32_16x16x32_bf16 v[42:45], v[142:145], v[158:161], v[42:45]
	v_mfma_f32_16x16x32_bf16 v[30:33], v[134:137], v[166:169], v[30:33]
	v_mfma_f32_16x16x32_bf16 v[26:29], v[142:145], v[166:169], v[26:29]
	v_mfma_f32_16x16x32_bf16 v[14:17], v[134:137], v[174:177], v[14:17]
	v_mfma_f32_16x16x32_bf16 v[10:13], v[142:145], v[174:177], v[10:13]
	s_barrier
	s_nop 0
	global_load_lds_dwordx4 v0, s[16:17]
	s_add_i32 m0, s38, 0x16000
	s_nop 0
	global_load_lds_dwordx4 v194, s[16:17]
	s_add_i32 s90, 0, 0x18000
	v_add_u32_e32 v142, s90, v212
	ds_read_b128 v[130:133], v142
	ds_read_b128 v[134:137], v142 offset:1024
	ds_read_b128 v[138:141], v142 offset:2048
	ds_read_b128 v[142:145], v142 offset:3072
	s_waitcnt vmcnt(6)
	s_barrier
	v_mfma_f32_16x16x32_bf16 v[54:57], v[178:181], v[146:149], v[54:57]
	v_mfma_f32_16x16x32_bf16 v[50:53], v[200:203], v[146:149], v[50:53]
	v_mfma_f32_16x16x32_bf16 v[38:41], v[178:181], v[154:157], v[38:41]
	v_mfma_f32_16x16x32_bf16 v[34:37], v[200:203], v[154:157], v[34:37]
	v_mfma_f32_16x16x32_bf16 v[22:25], v[178:181], v[162:165], v[22:25]
	v_mfma_f32_16x16x32_bf16 v[18:21], v[200:203], v[162:165], v[18:21]
	v_mfma_f32_16x16x32_bf16 v[6:9], v[178:181], v[170:173], v[6:9]
	v_mfma_f32_16x16x32_bf16 v[2:5], v[200:203], v[170:173], v[2:5]
	v_mfma_f32_16x16x32_bf16 v[54:57], v[182:185], v[150:153], v[54:57]
	s_add_u32 s16, s88, 0xb0000
	s_addc_u32 s17, s89, 0
	v_mfma_f32_16x16x32_bf16 v[50:53], v[204:207], v[150:153], v[50:53]
	s_mov_b32 m0, s43
	v_mfma_f32_16x16x32_bf16 v[38:41], v[182:185], v[158:161], v[38:41]
	v_mfma_f32_16x16x32_bf16 v[34:37], v[204:207], v[158:161], v[34:37]
	v_mfma_f32_16x16x32_bf16 v[22:25], v[182:185], v[166:169], v[22:25]
	v_mfma_f32_16x16x32_bf16 v[18:21], v[204:207], v[166:169], v[18:21]
	v_mfma_f32_16x16x32_bf16 v[6:9], v[182:185], v[174:177], v[6:9]
	v_mfma_f32_16x16x32_bf16 v[2:5], v[204:207], v[174:177], v[2:5]
	s_barrier
	ds_read_b128 v[146:149], v213 offset:32768
	ds_read_b128 v[150:153], v213 offset:33792
	ds_read_b128 v[154:157], v213 offset:34816
	ds_read_b128 v[158:161], v213 offset:35840
	ds_read_b128 v[162:165], v213 offset:36864
	ds_read_b128 v[166:169], v213 offset:37888
	ds_read_b128 v[170:173], v213 offset:38912
	global_load_lds_dwordx4 v190, s[16:17]
	s_mov_b32 m0, s44
	ds_read_b128 v[174:177], v213 offset:39936
	global_load_lds_dwordx4 v192, s[16:17]
	s_waitcnt lgkmcnt(8)
	s_barrier
	s_waitcnt lgkmcnt(0)
	v_mfma_f32_16x16x32_bf16 v[126:129], v[130:133], v[146:149], v[126:129]
	v_mfma_f32_16x16x32_bf16 v[122:125], v[138:141], v[146:149], v[122:125]
	v_mfma_f32_16x16x32_bf16 v[110:113], v[130:133], v[154:157], v[110:113]
	v_mfma_f32_16x16x32_bf16 v[106:109], v[138:141], v[154:157], v[106:109]
	v_mfma_f32_16x16x32_bf16 v[94:97], v[130:133], v[162:165], v[94:97]
	v_mfma_f32_16x16x32_bf16 v[90:93], v[138:141], v[162:165], v[90:93]
	v_mfma_f32_16x16x32_bf16 v[78:81], v[130:133], v[170:173], v[78:81]
	v_mfma_f32_16x16x32_bf16 v[74:77], v[138:141], v[170:173], v[74:77]
	v_mfma_f32_16x16x32_bf16 v[126:129], v[134:137], v[150:153], v[126:129]
	s_add_i32 s88, 0, 0x1c000
	v_mfma_f32_16x16x32_bf16 v[122:125], v[142:145], v[150:153], v[122:125]
	v_mfma_f32_16x16x32_bf16 v[110:113], v[134:137], v[158:161], v[110:113]
	v_mfma_f32_16x16x32_bf16 v[106:109], v[142:145], v[158:161], v[106:109]
	v_mfma_f32_16x16x32_bf16 v[94:97], v[134:137], v[166:169], v[94:97]
	v_mfma_f32_16x16x32_bf16 v[90:93], v[142:145], v[166:169], v[90:93]
	v_mfma_f32_16x16x32_bf16 v[78:81], v[134:137], v[174:177], v[78:81]
	v_mfma_f32_16x16x32_bf16 v[74:77], v[142:145], v[174:177], v[74:77]
	s_barrier
	v_add_u32_e32 v204, s88, v212
	s_add_i32 m0, s38, 0x18000
	ds_read_b128 v[178:181], v204
	ds_read_b128 v[182:185], v204 offset:1024
	ds_read_b128 v[200:203], v204 offset:2048
	ds_read_b128 v[204:207], v204 offset:3072
	s_add_u32 s98, s86, s40
	s_addc_u32 s99, s87, s41
	global_load_lds_dwordx4 v0, s[98:99]
	s_add_i32 m0, s38, 0x1a000
	s_nop 0
	global_load_lds_dwordx4 v194, s[98:99]
	s_barrier
	s_waitcnt lgkmcnt(0)
	v_mfma_f32_16x16x32_bf16 v[118:121], v[178:181], v[146:149], v[118:121]
	v_mfma_f32_16x16x32_bf16 v[114:117], v[200:203], v[146:149], v[114:117]
	v_mfma_f32_16x16x32_bf16 v[102:105], v[178:181], v[154:157], v[102:105]
	v_mfma_f32_16x16x32_bf16 v[98:101], v[200:203], v[154:157], v[98:101]
	v_mfma_f32_16x16x32_bf16 v[86:89], v[178:181], v[162:165], v[86:89]
	v_mfma_f32_16x16x32_bf16 v[82:85], v[200:203], v[162:165], v[82:85]
	v_mfma_f32_16x16x32_bf16 v[70:73], v[178:181], v[170:173], v[70:73]
	v_mfma_f32_16x16x32_bf16 v[66:69], v[200:203], v[170:173], v[66:69]
	v_mfma_f32_16x16x32_bf16 v[118:121], v[182:185], v[150:153], v[118:121]
	v_mfma_f32_16x16x32_bf16 v[114:117], v[204:207], v[150:153], v[114:117]
	v_mfma_f32_16x16x32_bf16 v[102:105], v[182:185], v[158:161], v[102:105]
	v_mfma_f32_16x16x32_bf16 v[98:101], v[204:207], v[158:161], v[98:101]
	v_mfma_f32_16x16x32_bf16 v[86:89], v[182:185], v[166:169], v[86:89]
	v_mfma_f32_16x16x32_bf16 v[82:85], v[204:207], v[166:169], v[82:85]
	v_mfma_f32_16x16x32_bf16 v[70:73], v[182:185], v[174:177], v[70:73]
	v_mfma_f32_16x16x32_bf16 v[66:69], v[204:207], v[174:177], v[66:69]
	s_mov_b32 m0, s60
	s_barrier
	ds_read_b128 v[146:149], v213 offset:49152
	ds_read_b128 v[150:153], v213 offset:50176
	ds_read_b128 v[154:157], v213 offset:51200
	ds_read_b128 v[158:161], v213 offset:52224
	ds_read_b128 v[162:165], v213 offset:53248
	ds_read_b128 v[166:169], v213 offset:54272
	ds_read_b128 v[170:173], v213 offset:55296
	ds_read_b128 v[174:177], v213 offset:56320
	s_add_u32 s98, s100, s40
	s_addc_u32 s99, s101, s41
	global_load_lds_dwordx4 v190, s[98:99]
	s_mov_b32 m0, s61
	s_nop 0
	global_load_lds_dwordx4 v192, s[98:99]
	s_waitcnt vmcnt(10)
	s_barrier
	s_waitcnt lgkmcnt(0)
	v_mfma_f32_16x16x32_bf16 v[62:65], v[130:133], v[146:149], v[62:65]
	v_mfma_f32_16x16x32_bf16 v[58:61], v[138:141], v[146:149], v[58:61]
	v_mfma_f32_16x16x32_bf16 v[46:49], v[130:133], v[154:157], v[46:49]
	v_mfma_f32_16x16x32_bf16 v[42:45], v[138:141], v[154:157], v[42:45]
	v_mfma_f32_16x16x32_bf16 v[30:33], v[130:133], v[162:165], v[30:33]
	v_mfma_f32_16x16x32_bf16 v[26:29], v[138:141], v[162:165], v[26:29]
	v_mfma_f32_16x16x32_bf16 v[14:17], v[130:133], v[170:173], v[14:17]
	v_mfma_f32_16x16x32_bf16 v[10:13], v[138:141], v[170:173], v[10:13]
	v_mfma_f32_16x16x32_bf16 v[62:65], v[134:137], v[150:153], v[62:65]
	s_add_u32 s16, s86, 0xb0080
	s_addc_u32 s17, s87, 0
	v_mfma_f32_16x16x32_bf16 v[58:61], v[142:145], v[150:153], v[58:61]
	s_add_i32 m0, s38, 0x1c000
	v_mfma_f32_16x16x32_bf16 v[46:49], v[134:137], v[158:161], v[46:49]
	v_mfma_f32_16x16x32_bf16 v[42:45], v[142:145], v[158:161], v[42:45]
	v_mfma_f32_16x16x32_bf16 v[30:33], v[134:137], v[166:169], v[30:33]
	v_mfma_f32_16x16x32_bf16 v[26:29], v[142:145], v[166:169], v[26:29]
	v_mfma_f32_16x16x32_bf16 v[14:17], v[134:137], v[174:177], v[14:17]
	v_mfma_f32_16x16x32_bf16 v[10:13], v[142:145], v[174:177], v[10:13]
	s_barrier
	s_nop 0
	global_load_lds_dwordx4 v0, s[16:17]
	s_add_i32 m0, s38, 0x1e000
	s_nop 0
	global_load_lds_dwordx4 v194, s[16:17]
	ds_read_b128 v[130:133], v189
	ds_read_b128 v[134:137], v189 offset:1024
	ds_read_b128 v[138:141], v189 offset:2048
	ds_read_b128 v[142:145], v189 offset:3072
	s_waitcnt vmcnt(6)
	s_barrier
	v_mfma_f32_16x16x32_bf16 v[54:57], v[178:181], v[146:149], v[54:57]
	v_mfma_f32_16x16x32_bf16 v[50:53], v[200:203], v[146:149], v[50:53]
	v_mfma_f32_16x16x32_bf16 v[38:41], v[178:181], v[154:157], v[38:41]
	v_mfma_f32_16x16x32_bf16 v[34:37], v[200:203], v[154:157], v[34:37]
	v_mfma_f32_16x16x32_bf16 v[22:25], v[178:181], v[162:165], v[22:25]
	v_mfma_f32_16x16x32_bf16 v[18:21], v[200:203], v[162:165], v[18:21]
	v_mfma_f32_16x16x32_bf16 v[6:9], v[178:181], v[170:173], v[6:9]
	v_mfma_f32_16x16x32_bf16 v[2:5], v[200:203], v[170:173], v[2:5]
	v_mfma_f32_16x16x32_bf16 v[54:57], v[182:185], v[150:153], v[54:57]
	s_add_i32 s79, s79, 2
	s_add_u32 s34, s34, 0x100
	v_mfma_f32_16x16x32_bf16 v[50:53], v[204:207], v[150:153], v[50:53]
	s_addc_u32 s78, s78, 0
	s_mov_b64 s[16:17], s[84:85]
	v_mfma_f32_16x16x32_bf16 v[38:41], v[182:185], v[158:161], v[38:41]
	s_add_u32 s84, s16, 0x100
	s_addc_u32 s85, s17, 0
	v_mfma_f32_16x16x32_bf16 v[34:37], v[204:207], v[158:161], v[34:37]
	s_cmp_eq_u32 s79, 40
	s_cselect_b32 s89, s5, s85
	v_mfma_f32_16x16x32_bf16 v[22:25], v[182:185], v[166:169], v[22:25]
	s_cselect_b32 s88, s4, s84
	s_cselect_b32 s87, s7, s78
	v_mfma_f32_16x16x32_bf16 v[18:21], v[204:207], v[166:169], v[18:21]
	s_cselect_b32 s86, s6, s34
	s_cmp_gt_u32 s79, 41
	v_mfma_f32_16x16x32_bf16 v[6:9], v[182:185], v[174:177], v[6:9]
	v_mfma_f32_16x16x32_bf16 v[2:5], v[204:207], v[174:177], v[2:5]
	s_barrier
	s_cbranch_scc0 .LBB0_1090
	s_waitcnt lgkmcnt(0)
	s_lshl_b32 s16, s23, 8
	v_mov_b32_e32 v186, v252
	s_add_i32 s16, s16, s47
	s_nop 0
	v_and_or_b32 v202, v186, 15, s16
	s_lshl_b32 s16, s22, 8
	s_or_b32 s16, s16, s55
	v_lshrrev_b32_e32 v130, 1, v186
	v_and_or_b32 v200, v130, 24, s16
	v_ashrrev_i32_e32 v201, 31, v200
	v_ashrrev_i32_e32 v203, 31, v202
	v_lshl_add_u64 v[204:205], v[200:201], 2, s[12:13]
	v_lshlrev_b64 v[130:131], 12, v[202:203]
	v_lshl_add_u64 v[130:131], v[204:205], 0, v[130:131]
	global_load_dwordx4 v[216:219], v[130:131], off offset:16
	global_load_dwordx4 v[220:223], v[130:131], off
	global_load_dwordx4 v[178:181], v[130:131], off offset:528
	global_load_dwordx4 v[182:185], v[130:131], off offset:512
	v_or_b32_e32 v210, 16, v202
	v_ashrrev_i32_e32 v211, 31, v210
	v_lshlrev_b64 v[130:131], 12, v[210:211]
	v_or_b32_e32 v208, 32, v202
	v_lshl_add_u64 v[130:131], v[204:205], 0, v[130:131]
	v_ashrrev_i32_e32 v209, 31, v208
	global_load_dwordx4 v[170:173], v[130:131], off offset:16
	global_load_dwordx4 v[174:177], v[130:131], off
	global_load_dwordx4 v[162:165], v[130:131], off offset:528
	global_load_dwordx4 v[166:169], v[130:131], off offset:512
	v_lshlrev_b64 v[130:131], 12, v[208:209]
	v_or_b32_e32 v206, 48, v202
	v_lshl_add_u64 v[130:131], v[204:205], 0, v[130:131]
	v_ashrrev_i32_e32 v207, 31, v206
	global_load_dwordx4 v[154:157], v[130:131], off offset:16
	global_load_dwordx4 v[158:161], v[130:131], off
	global_load_dwordx4 v[138:141], v[130:131], off offset:528
	global_load_dwordx4 v[142:145], v[130:131], off offset:512
	v_lshlrev_b64 v[130:131], 12, v[206:207]
	v_lshl_add_u64 v[134:135], v[204:205], 0, v[130:131]
	global_load_dwordx4 v[146:149], v[134:135], off offset:16
	global_load_dwordx4 v[150:153], v[134:135], off
	global_load_dwordx4 v[130:133], v[134:135], off offset:528
	s_nop 0
	global_load_dwordx4 v[134:137], v[134:135], off offset:512
	v_and_b32_e32 v186, 63, v186
	v_lshlrev_b32_e32 v187, 2, v186
	v_xor_b32_e32 v215, 64, v187
	v_xor_b32_e32 v214, 0x80, v187
	v_cmp_gt_u32_e32 vcc, 16, v186
	v_lshlrev_b64 v[186:187], 10, v[202:203]
	v_lshl_add_u64 v[186:187], v[186:187], 0, v[200:201]
	s_lshl_b32 s16, s22, 2
	s_ashr_i32 s17, s16, 31
	s_waitcnt vmcnt(0)
	v_pk_add_f32 v[124:125], v[124:125], v[218:219]
	v_pk_add_f32 v[128:129], v[128:129], v[222:223]
	v_pk_add_f32 v[126:127], v[126:127], v[220:221]
	v_pk_mul_f32 v[218:219], v[128:129], v[128:129]
	v_pk_mul_f32 v[220:221], v[126:127], v[126:127]
	v_pk_add_f32 v[122:123], v[122:123], v[216:217]
	v_lshl_add_u64 v[216:217], v[186:187], 2, s[14:15]
	v_add_f32_e32 v220, v220, v221
	v_add_f32_e32 v218, v218, v219
	global_store_dwordx4 v[216:217], v[126:129], off
	global_store_dwordx4 v[216:217], v[122:125], off offset:16
	v_add_f32_e32 v222, v220, v218
	v_pk_mul_f32 v[220:221], v[122:123], v[122:123]
	v_cvt_pk_bf16_f32 v126, v126, v127
	v_cvt_pk_bf16_f32 v127, v128, v129
	v_cvt_pk_bf16_f32 v128, v122, v123
	v_cvt_pk_bf16_f32 v129, v124, v125
	v_lshl_add_u64 v[122:123], v[186:187], 1, s[80:81]
	v_pk_add_f32 v[120:121], v[120:121], v[184:185]
	v_pk_add_f32 v[118:119], v[118:119], v[182:183]
	v_pk_mul_f32 v[218:219], v[124:125], v[124:125]
	global_store_dwordx4 v[122:123], v[126:129], off
	v_pk_mul_f32 v[124:125], v[120:121], v[120:121]
	v_pk_add_f32 v[116:117], v[116:117], v[180:181]
	v_pk_mul_f32 v[126:127], v[118:119], v[118:119]
	v_pk_add_f32 v[114:115], v[114:115], v[178:179]
	v_add_f32_e32 v126, v126, v127
	v_add_f32_e32 v124, v124, v125
	v_add_f32_e32 v128, v126, v124
	v_pk_mul_f32 v[124:125], v[116:117], v[116:117]
	v_pk_mul_f32 v[126:127], v[114:115], v[114:115]
	v_add_f32_e32 v220, v220, v221
	v_add_f32_e32 v218, v218, v219
	v_add_f32_e32 v126, v126, v127
	v_add_f32_e32 v124, v124, v125
	v_add_f32_e32 v218, v220, v218
	v_add_f32_e32 v124, v126, v124
	v_add_f32_e32 v218, v222, v218
	v_add_f32_e32 v124, v128, v124
	v_add_f32_e32 v124, v218, v124
	global_store_dwordx4 v[216:217], v[118:121], off offset:512
	global_store_dwordx4 v[216:217], v[114:117], off offset:528
	s_nop 0
	v_cvt_pk_bf16_f32 v118, v118, v119
	v_cvt_pk_bf16_f32 v119, v120, v121
	v_cvt_pk_bf16_f32 v120, v114, v115
	ds_bpermute_b32 v114, v215, v124
	v_cvt_pk_bf16_f32 v121, v116, v117
	global_store_dwordx4 v[122:123], v[118:121], off offset:256
	s_waitcnt lgkmcnt(0)
	v_add_f32_e32 v114, v124, v114
	ds_bpermute_b32 v115, v214, v114
	s_and_saveexec_b64 s[22:23], vcc
	s_cbranch_execz .LBB0_1093
	v_lshlrev_b64 v[116:117], 6, v[202:203]
	v_lshl_add_u64 v[116:117], s[82:83], 0, v[116:117]
	v_lshl_add_u64 v[116:117], s[16:17], 2, v[116:117]
	s_lshl_b32 s34, s45, 2
	v_lshl_add_u64 v[116:117], v[116:117], 0, s[34:35]
	s_waitcnt lgkmcnt(0)
	v_add_f32_e32 v114, v114, v115
	global_store_dword v[116:117], v114, off

.LBB0_1208:
	s_ashr_i32 s13, s12, 31
	v_cmp_lt_i64_e32 vcc, s[14:15], v[230:231]
	s_lshl_b64 s[14:15], s[12:13], 19
	s_add_u32 s14, s80, s14
	s_addc_u32 s15, s81, s15
	s_and_b64 s[16:17], vcc, exec
	s_cselect_b32 s13, s15, s89
	s_cselect_b32 s22, s14, s88
	s_ashr_i32 s7, s6, 31
	s_lshl_b64 s[16:17], s[6:7], 19
	s_add_u32 s16, s36, s16
	s_addc_u32 s17, s37, s17
	s_and_b64 s[92:93], vcc, exec
	s_cselect_b32 s7, s17, s91
	s_cselect_b32 s23, s16, s90
	s_add_u32 s88, s88, 0x40080
	s_addc_u32 s89, s89, 0
	s_add_u32 s34, s90, 0x100
	s_addc_u32 s79, s91, 0
	s_mov_b32 s85, -2
	s_waitcnt lgkmcnt(0)
	s_add_i32 s94, 0, 0x10000
	v_add_u32_e32 v0, s94, v170
	v_add_u32_e32 v189, 0x10000, v170
	ds_read_b128 v[130:133], v0
	ds_read_b128 v[134:137], v0 offset:1024
	ds_read_b128 v[138:141], v0 offset:2048
	ds_read_b128 v[142:145], v0 offset:3072
	s_add_u32 s87, s88, 0xfffc0080
	s_addc_u32 s90, s89, -1
	s_cmp_eq_u32 s85, 12
	s_cselect_b32 s93, s13, s90
	s_cselect_b32 s92, s22, s87
	s_cselect_b32 s91, s7, s79
	s_cselect_b32 s90, s23, s34
	s_waitcnt lgkmcnt(0)
	s_add_i32 m0, s39, 0xc000
	ds_read_b128 v[158:161], v171
	ds_read_b128 v[162:165], v171 offset:1024
	ds_read_b128 v[166:169], v171 offset:2048
	ds_read_b128 v[172:175], v171 offset:3072
	ds_read_b128 v[176:179], v171 offset:4096
	ds_read_b128 v[180:183], v171 offset:5120
	ds_read_b128 v[184:187], v171 offset:6144
	global_load_lds_dwordx4 v154, s[88:89]
	s_add_i32 m0, s39, 0xe000
	ds_read_b128 v[190:193], v171 offset:7168
	global_load_lds_dwordx4 v156, s[88:89]
	s_waitcnt lgkmcnt(8)
	s_barrier
	s_waitcnt lgkmcnt(0)
	v_mfma_f32_16x16x32_bf16 v[126:129], v[130:133], v[158:161], 0
	v_mfma_f32_16x16x32_bf16 v[122:125], v[138:141], v[158:161], 0
	v_mfma_f32_16x16x32_bf16 v[110:113], v[130:133], v[166:169], 0
	v_mfma_f32_16x16x32_bf16 v[106:109], v[138:141], v[166:169], 0
	v_mfma_f32_16x16x32_bf16 v[94:97], v[130:133], v[176:179], 0
	v_mfma_f32_16x16x32_bf16 v[90:93], v[138:141], v[176:179], 0
	v_mfma_f32_16x16x32_bf16 v[78:81], v[130:133], v[184:187], 0
	v_mfma_f32_16x16x32_bf16 v[74:77], v[138:141], v[184:187], 0
	v_mfma_f32_16x16x32_bf16 v[126:129], v[134:137], v[162:165], v[126:129]
	s_add_i32 m0, s38, 0x10000
	v_mfma_f32_16x16x32_bf16 v[122:125], v[142:145], v[162:165], v[122:125]
	v_mfma_f32_16x16x32_bf16 v[110:113], v[134:137], v[172:175], v[110:113]
	v_mfma_f32_16x16x32_bf16 v[106:109], v[142:145], v[172:175], v[106:109]
	v_mfma_f32_16x16x32_bf16 v[94:97], v[134:137], v[180:183], v[94:97]
	v_mfma_f32_16x16x32_bf16 v[90:93], v[142:145], v[180:183], v[90:93]
	v_mfma_f32_16x16x32_bf16 v[78:81], v[134:137], v[190:193], v[78:81]
	v_mfma_f32_16x16x32_bf16 v[74:77], v[142:145], v[190:193], v[74:77]
	s_barrier
	ds_read_b128 v[194:197], v189 offset:16384
	ds_read_b128 v[198:201], v189 offset:17408
	ds_read_b128 v[202:205], v189 offset:18432
	global_load_lds_dwordx4 v148, s[90:91]
	s_add_i32 m0, s38, 0x12000
	ds_read_b128 v[206:209], v189 offset:19456
	global_load_lds_dwordx4 v152, s[90:91]
	s_barrier
	s_waitcnt lgkmcnt(0)
	v_mfma_f32_16x16x32_bf16 v[118:121], v[194:197], v[158:161], 0
	v_mfma_f32_16x16x32_bf16 v[114:117], v[202:205], v[158:161], 0
	v_mfma_f32_16x16x32_bf16 v[102:105], v[194:197], v[166:169], 0
	v_mfma_f32_16x16x32_bf16 v[98:101], v[202:205], v[166:169], 0
	v_mfma_f32_16x16x32_bf16 v[86:89], v[194:197], v[176:179], 0
	v_mfma_f32_16x16x32_bf16 v[82:85], v[202:205], v[176:179], 0
	v_mfma_f32_16x16x32_bf16 v[70:73], v[194:197], v[184:187], 0
	v_mfma_f32_16x16x32_bf16 v[66:69], v[202:205], v[184:187], 0
	v_mfma_f32_16x16x32_bf16 v[118:121], v[198:201], v[162:165], v[118:121]
	v_mfma_f32_16x16x32_bf16 v[114:117], v[206:209], v[162:165], v[114:117]
	v_mfma_f32_16x16x32_bf16 v[102:105], v[198:201], v[172:175], v[102:105]
	v_mfma_f32_16x16x32_bf16 v[98:101], v[206:209], v[172:175], v[98:101]
	v_mfma_f32_16x16x32_bf16 v[86:89], v[198:201], v[180:183], v[86:89]
	v_mfma_f32_16x16x32_bf16 v[82:85], v[206:209], v[180:183], v[82:85]
	v_mfma_f32_16x16x32_bf16 v[70:73], v[198:201], v[190:193], v[70:73]
	v_mfma_f32_16x16x32_bf16 v[66:69], v[206:209], v[190:193], v[66:69]
	s_mov_b32 m0, s39
	s_mov_b64 s[100:101], s[92:93]
	s_barrier
	ds_read_b128 v[158:161], v171 offset:16384
	ds_read_b128 v[162:165], v171 offset:17408
	ds_read_b128 v[166:169], v171 offset:18432
	ds_read_b128 v[172:175], v171 offset:19456
	ds_read_b128 v[176:179], v171 offset:20480
	ds_read_b128 v[180:183], v171 offset:21504
	ds_read_b128 v[184:187], v171 offset:22528
	global_load_lds_dwordx4 v146, s[100:101]
	s_mov_b32 m0, s42
	ds_read_b128 v[190:193], v171 offset:23552
	global_load_lds_dwordx4 v150, s[100:101]
	s_waitcnt vmcnt(10)
	s_barrier
	s_waitcnt lgkmcnt(0)
	v_mfma_f32_16x16x32_bf16 v[62:65], v[130:133], v[158:161], 0
	v_mfma_f32_16x16x32_bf16 v[58:61], v[138:141], v[158:161], 0
	v_mfma_f32_16x16x32_bf16 v[46:49], v[130:133], v[166:169], 0
	v_mfma_f32_16x16x32_bf16 v[42:45], v[138:141], v[166:169], 0
	v_mfma_f32_16x16x32_bf16 v[30:33], v[130:133], v[176:179], 0
	v_mfma_f32_16x16x32_bf16 v[26:29], v[138:141], v[176:179], 0
	v_mfma_f32_16x16x32_bf16 v[14:17], v[130:133], v[184:187], 0
	v_mfma_f32_16x16x32_bf16 v[10:13], v[138:141], v[184:187], 0
	v_mfma_f32_16x16x32_bf16 v[62:65], v[134:137], v[162:165], v[62:65]
	s_add_u32 s94, s90, 0x40000
	s_addc_u32 s95, s91, 0
	v_mfma_f32_16x16x32_bf16 v[58:61], v[142:145], v[162:165], v[58:61]
	s_add_i32 m0, s38, 0x14000
	v_mfma_f32_16x16x32_bf16 v[46:49], v[134:137], v[172:175], v[46:49]
	v_mfma_f32_16x16x32_bf16 v[42:45], v[142:145], v[172:175], v[42:45]
	v_mfma_f32_16x16x32_bf16 v[30:33], v[134:137], v[180:183], v[30:33]
	v_mfma_f32_16x16x32_bf16 v[26:29], v[142:145], v[180:183], v[26:29]
	v_mfma_f32_16x16x32_bf16 v[14:17], v[134:137], v[190:193], v[14:17]
	v_mfma_f32_16x16x32_bf16 v[10:13], v[142:145], v[190:193], v[10:13]
	s_barrier
	s_nop 0
	global_load_lds_dwordx4 v148, s[94:95]
	s_add_i32 m0, s38, 0x16000
	s_nop 0
	global_load_lds_dwordx4 v152, s[94:95]
	ds_read_b128 v[130:133], v189 offset:32768
	ds_read_b128 v[134:137], v189 offset:33792
	ds_read_b128 v[138:141], v189 offset:34816
	ds_read_b128 v[142:145], v189 offset:35840
	s_waitcnt vmcnt(6)
	s_barrier
	v_mfma_f32_16x16x32_bf16 v[54:57], v[194:197], v[158:161], 0
	v_mfma_f32_16x16x32_bf16 v[50:53], v[202:205], v[158:161], 0
	v_mfma_f32_16x16x32_bf16 v[38:41], v[194:197], v[166:169], 0
	v_mfma_f32_16x16x32_bf16 v[34:37], v[202:205], v[166:169], 0
	v_mfma_f32_16x16x32_bf16 v[22:25], v[194:197], v[176:179], 0
	v_mfma_f32_16x16x32_bf16 v[18:21], v[202:205], v[176:179], 0
	v_mfma_f32_16x16x32_bf16 v[6:9], v[194:197], v[184:187], 0
	v_mfma_f32_16x16x32_bf16 v[2:5], v[202:205], v[184:187], 0
	v_mfma_f32_16x16x32_bf16 v[54:57], v[198:201], v[162:165], v[54:57]
	s_add_u32 s92, s92, 0x40000
	s_addc_u32 s93, s93, 0
	v_mfma_f32_16x16x32_bf16 v[50:53], v[206:209], v[162:165], v[50:53]
	s_mov_b32 m0, s43
	v_mfma_f32_16x16x32_bf16 v[38:41], v[198:201], v[172:175], v[38:41]
	v_mfma_f32_16x16x32_bf16 v[34:37], v[206:209], v[172:175], v[34:37]
	v_mfma_f32_16x16x32_bf16 v[22:25], v[198:201], v[180:183], v[22:25]
	v_mfma_f32_16x16x32_bf16 v[18:21], v[206:209], v[180:183], v[18:21]
	v_mfma_f32_16x16x32_bf16 v[6:9], v[198:201], v[190:193], v[6:9]
	v_mfma_f32_16x16x32_bf16 v[2:5], v[206:209], v[190:193], v[2:5]
	s_barrier
	ds_read_b128 v[158:161], v171 offset:32768
	ds_read_b128 v[162:165], v171 offset:33792
	ds_read_b128 v[166:169], v171 offset:34816
	ds_read_b128 v[172:175], v171 offset:35840
	ds_read_b128 v[176:179], v171 offset:36864
	ds_read_b128 v[180:183], v171 offset:37888
	ds_read_b128 v[184:187], v171 offset:38912
	global_load_lds_dwordx4 v146, s[92:93]
	s_mov_b32 m0, s44
	ds_read_b128 v[190:193], v171 offset:39936
	global_load_lds_dwordx4 v150, s[92:93]
	s_waitcnt lgkmcnt(8)
	s_barrier
	s_waitcnt lgkmcnt(0)
	v_mfma_f32_16x16x32_bf16 v[126:129], v[130:133], v[158:161], v[126:129]
	v_mfma_f32_16x16x32_bf16 v[122:125], v[138:141], v[158:161], v[122:125]
	v_mfma_f32_16x16x32_bf16 v[110:113], v[130:133], v[166:169], v[110:113]
	v_mfma_f32_16x16x32_bf16 v[106:109], v[138:141], v[166:169], v[106:109]
	v_mfma_f32_16x16x32_bf16 v[94:97], v[130:133], v[176:179], v[94:97]
	v_mfma_f32_16x16x32_bf16 v[90:93], v[138:141], v[176:179], v[90:93]
	v_mfma_f32_16x16x32_bf16 v[78:81], v[130:133], v[184:187], v[78:81]
	v_mfma_f32_16x16x32_bf16 v[74:77], v[138:141], v[184:187], v[74:77]
	v_mfma_f32_16x16x32_bf16 v[126:129], v[134:137], v[162:165], v[126:129]
	s_add_i32 m0, s38, 0x18000
	v_mfma_f32_16x16x32_bf16 v[122:125], v[142:145], v[162:165], v[122:125]
	v_mfma_f32_16x16x32_bf16 v[110:113], v[134:137], v[172:175], v[110:113]
	v_mfma_f32_16x16x32_bf16 v[106:109], v[142:145], v[172:175], v[106:109]
	v_mfma_f32_16x16x32_bf16 v[94:97], v[134:137], v[180:183], v[94:97]
	v_mfma_f32_16x16x32_bf16 v[90:93], v[142:145], v[180:183], v[90:93]
	v_mfma_f32_16x16x32_bf16 v[78:81], v[134:137], v[190:193], v[78:81]
	v_mfma_f32_16x16x32_bf16 v[74:77], v[142:145], v[190:193], v[74:77]
	s_barrier
	ds_read_b128 v[194:197], v189 offset:49152
	ds_read_b128 v[198:201], v189 offset:50176
	ds_read_b128 v[202:205], v189 offset:51200
	ds_read_b128 v[206:209], v189 offset:52224
	s_add_u32 s98, s90, s40
	s_addc_u32 s99, s91, s41
	global_load_lds_dwordx4 v148, s[98:99]
	s_add_i32 m0, s38, 0x1a000
	s_nop 0
	global_load_lds_dwordx4 v152, s[98:99]
	s_barrier
	s_waitcnt lgkmcnt(0)
	v_mfma_f32_16x16x32_bf16 v[118:121], v[194:197], v[158:161], v[118:121]
	v_mfma_f32_16x16x32_bf16 v[114:117], v[202:205], v[158:161], v[114:117]
	v_mfma_f32_16x16x32_bf16 v[102:105], v[194:197], v[166:169], v[102:105]
	v_mfma_f32_16x16x32_bf16 v[98:101], v[202:205], v[166:169], v[98:101]
	v_mfma_f32_16x16x32_bf16 v[86:89], v[194:197], v[176:179], v[86:89]
	v_mfma_f32_16x16x32_bf16 v[82:85], v[202:205], v[176:179], v[82:85]
	v_mfma_f32_16x16x32_bf16 v[70:73], v[194:197], v[184:187], v[70:73]
	v_mfma_f32_16x16x32_bf16 v[66:69], v[202:205], v[184:187], v[66:69]
	v_mfma_f32_16x16x32_bf16 v[118:121], v[198:201], v[162:165], v[118:121]
	v_mfma_f32_16x16x32_bf16 v[114:117], v[206:209], v[162:165], v[114:117]
	v_mfma_f32_16x16x32_bf16 v[102:105], v[198:201], v[172:175], v[102:105]
	v_mfma_f32_16x16x32_bf16 v[98:101], v[206:209], v[172:175], v[98:101]
	v_mfma_f32_16x16x32_bf16 v[86:89], v[198:201], v[180:183], v[86:89]
	v_mfma_f32_16x16x32_bf16 v[82:85], v[206:209], v[180:183], v[82:85]
	v_mfma_f32_16x16x32_bf16 v[70:73], v[198:201], v[190:193], v[70:73]
	v_mfma_f32_16x16x32_bf16 v[66:69], v[206:209], v[190:193], v[66:69]
	s_mov_b32 m0, s60
	s_barrier
	ds_read_b128 v[158:161], v171 offset:49152
	ds_read_b128 v[162:165], v171 offset:50176
	ds_read_b128 v[166:169], v171 offset:51200
	ds_read_b128 v[172:175], v171 offset:52224
	ds_read_b128 v[176:179], v171 offset:53248
	ds_read_b128 v[180:183], v171 offset:54272
	ds_read_b128 v[184:187], v171 offset:55296
	ds_read_b128 v[190:193], v171 offset:56320
	s_add_u32 s98, s100, s40
	s_addc_u32 s99, s101, s41
	global_load_lds_dwordx4 v146, s[98:99]
	s_mov_b32 m0, s61
	s_nop 0
	global_load_lds_dwordx4 v150, s[98:99]
	s_waitcnt vmcnt(10)
	s_barrier
	s_waitcnt lgkmcnt(0)
	v_mfma_f32_16x16x32_bf16 v[62:65], v[130:133], v[158:161], v[62:65]
	v_mfma_f32_16x16x32_bf16 v[58:61], v[138:141], v[158:161], v[58:61]
	v_mfma_f32_16x16x32_bf16 v[46:49], v[130:133], v[166:169], v[46:49]
	v_mfma_f32_16x16x32_bf16 v[42:45], v[138:141], v[166:169], v[42:45]
	v_mfma_f32_16x16x32_bf16 v[30:33], v[130:133], v[176:179], v[30:33]
	v_mfma_f32_16x16x32_bf16 v[26:29], v[138:141], v[176:179], v[26:29]
	v_mfma_f32_16x16x32_bf16 v[14:17], v[130:133], v[184:187], v[14:17]
	v_mfma_f32_16x16x32_bf16 v[10:13], v[138:141], v[184:187], v[10:13]
	v_mfma_f32_16x16x32_bf16 v[62:65], v[134:137], v[162:165], v[62:65]
	s_add_u32 s90, s90, 0x40080
	s_addc_u32 s91, s91, 0
	v_mfma_f32_16x16x32_bf16 v[58:61], v[142:145], v[162:165], v[58:61]
	s_add_i32 m0, s38, 0x1c000
	v_mfma_f32_16x16x32_bf16 v[46:49], v[134:137], v[172:175], v[46:49]
	v_mfma_f32_16x16x32_bf16 v[42:45], v[142:145], v[172:175], v[42:45]
	v_mfma_f32_16x16x32_bf16 v[30:33], v[134:137], v[180:183], v[30:33]
	v_mfma_f32_16x16x32_bf16 v[26:29], v[142:145], v[180:183], v[26:29]
	v_mfma_f32_16x16x32_bf16 v[14:17], v[134:137], v[190:193], v[14:17]
	v_mfma_f32_16x16x32_bf16 v[10:13], v[142:145], v[190:193], v[10:13]
	s_barrier
	s_nop 0
	global_load_lds_dwordx4 v148, s[90:91]
	s_add_i32 m0, s38, 0x1e000
	s_nop 0
	global_load_lds_dwordx4 v152, s[90:91]
	ds_read_b128 v[130:133], v189
	ds_read_b128 v[134:137], v189 offset:1024
	ds_read_b128 v[138:141], v189 offset:2048
	ds_read_b128 v[142:145], v189 offset:3072
	s_waitcnt vmcnt(6)
	s_barrier
	v_mfma_f32_16x16x32_bf16 v[54:57], v[194:197], v[158:161], v[54:57]
	v_mfma_f32_16x16x32_bf16 v[50:53], v[202:205], v[158:161], v[50:53]
	v_mfma_f32_16x16x32_bf16 v[38:41], v[194:197], v[166:169], v[38:41]
	v_mfma_f32_16x16x32_bf16 v[34:37], v[202:205], v[166:169], v[34:37]
	v_mfma_f32_16x16x32_bf16 v[22:25], v[194:197], v[176:179], v[22:25]
	v_mfma_f32_16x16x32_bf16 v[18:21], v[202:205], v[176:179], v[18:21]
	v_mfma_f32_16x16x32_bf16 v[6:9], v[194:197], v[184:187], v[6:9]
	v_mfma_f32_16x16x32_bf16 v[2:5], v[202:205], v[184:187], v[2:5]
	v_mfma_f32_16x16x32_bf16 v[54:57], v[198:201], v[162:165], v[54:57]
	s_add_i32 s85, s85, 2
	s_add_u32 s88, s88, 0x100
	v_mfma_f32_16x16x32_bf16 v[50:53], v[206:209], v[162:165], v[50:53]
	s_addc_u32 s89, s89, 0
	s_add_u32 s34, s34, 0x100
	v_mfma_f32_16x16x32_bf16 v[38:41], v[198:201], v[172:175], v[38:41]
	s_addc_u32 s79, s79, 0
	s_add_u32 s87, s88, 0xfffc0080
	v_mfma_f32_16x16x32_bf16 v[34:37], v[206:209], v[172:175], v[34:37]
	s_addc_u32 s90, s89, -1
	s_cmp_eq_u32 s85, 12
	v_mfma_f32_16x16x32_bf16 v[22:25], v[198:201], v[180:183], v[22:25]
	s_cselect_b32 s93, s13, s90
	s_cselect_b32 s92, s22, s87
	v_mfma_f32_16x16x32_bf16 v[18:21], v[206:209], v[180:183], v[18:21]
	s_cselect_b32 s91, s7, s79
	s_cselect_b32 s90, s23, s34
	v_mfma_f32_16x16x32_bf16 v[6:9], v[198:201], v[190:193], v[6:9]
	s_cmp_gt_u32 s85, 13
	v_mfma_f32_16x16x32_bf16 v[2:5], v[206:209], v[190:193], v[2:5]
	s_barrier
	.p2align 3
.LBB0_1209:
	s_waitcnt lgkmcnt(0)
	s_add_i32 m0, s39, 0xc000
	ds_read_b128 v[158:161], v171
	ds_read_b128 v[162:165], v171 offset:1024
	ds_read_b128 v[166:169], v171 offset:2048
	ds_read_b128 v[172:175], v171 offset:3072
	ds_read_b128 v[176:179], v171 offset:4096
	ds_read_b128 v[180:183], v171 offset:5120
	ds_read_b128 v[184:187], v171 offset:6144
	global_load_lds_dwordx4 v154, s[88:89]
	s_add_i32 m0, s39, 0xe000
	ds_read_b128 v[190:193], v171 offset:7168
	global_load_lds_dwordx4 v156, s[88:89]
	s_waitcnt lgkmcnt(8)
	s_barrier
	s_waitcnt lgkmcnt(0)
	v_mfma_f32_16x16x32_bf16 v[126:129], v[130:133], v[158:161], v[126:129]
	v_mfma_f32_16x16x32_bf16 v[122:125], v[138:141], v[158:161], v[122:125]
	v_mfma_f32_16x16x32_bf16 v[110:113], v[130:133], v[166:169], v[110:113]
	v_mfma_f32_16x16x32_bf16 v[106:109], v[138:141], v[166:169], v[106:109]
	v_mfma_f32_16x16x32_bf16 v[94:97], v[130:133], v[176:179], v[94:97]
	v_mfma_f32_16x16x32_bf16 v[90:93], v[138:141], v[176:179], v[90:93]
	v_mfma_f32_16x16x32_bf16 v[78:81], v[130:133], v[184:187], v[78:81]
	v_mfma_f32_16x16x32_bf16 v[74:77], v[138:141], v[184:187], v[74:77]
	v_mfma_f32_16x16x32_bf16 v[126:129], v[134:137], v[162:165], v[126:129]
	s_add_i32 m0, s38, 0x10000
	v_mfma_f32_16x16x32_bf16 v[122:125], v[142:145], v[162:165], v[122:125]
	v_mfma_f32_16x16x32_bf16 v[110:113], v[134:137], v[172:175], v[110:113]
	v_mfma_f32_16x16x32_bf16 v[106:109], v[142:145], v[172:175], v[106:109]
	v_mfma_f32_16x16x32_bf16 v[94:97], v[134:137], v[180:183], v[94:97]
	v_mfma_f32_16x16x32_bf16 v[90:93], v[142:145], v[180:183], v[90:93]
	v_mfma_f32_16x16x32_bf16 v[78:81], v[134:137], v[190:193], v[78:81]
	v_mfma_f32_16x16x32_bf16 v[74:77], v[142:145], v[190:193], v[74:77]
	s_barrier
	ds_read_b128 v[194:197], v189 offset:16384
	ds_read_b128 v[198:201], v189 offset:17408
	ds_read_b128 v[202:205], v189 offset:18432
	global_load_lds_dwordx4 v148, s[90:91]
	s_add_i32 m0, s38, 0x12000
	ds_read_b128 v[206:209], v189 offset:19456
	global_load_lds_dwordx4 v152, s[90:91]
	s_barrier
	s_waitcnt lgkmcnt(0)
	v_mfma_f32_16x16x32_bf16 v[118:121], v[194:197], v[158:161], v[118:121]
	v_mfma_f32_16x16x32_bf16 v[114:117], v[202:205], v[158:161], v[114:117]
	v_mfma_f32_16x16x32_bf16 v[102:105], v[194:197], v[166:169], v[102:105]
	v_mfma_f32_16x16x32_bf16 v[98:101], v[202:205], v[166:169], v[98:101]
	v_mfma_f32_16x16x32_bf16 v[86:89], v[194:197], v[176:179], v[86:89]
	v_mfma_f32_16x16x32_bf16 v[82:85], v[202:205], v[176:179], v[82:85]
	v_mfma_f32_16x16x32_bf16 v[70:73], v[194:197], v[184:187], v[70:73]
	v_mfma_f32_16x16x32_bf16 v[66:69], v[202:205], v[184:187], v[66:69]
	v_mfma_f32_16x16x32_bf16 v[118:121], v[198:201], v[162:165], v[118:121]
	v_mfma_f32_16x16x32_bf16 v[114:117], v[206:209], v[162:165], v[114:117]
	v_mfma_f32_16x16x32_bf16 v[102:105], v[198:201], v[172:175], v[102:105]
	v_mfma_f32_16x16x32_bf16 v[98:101], v[206:209], v[172:175], v[98:101]
	v_mfma_f32_16x16x32_bf16 v[86:89], v[198:201], v[180:183], v[86:89]
	v_mfma_f32_16x16x32_bf16 v[82:85], v[206:209], v[180:183], v[82:85]
	v_mfma_f32_16x16x32_bf16 v[70:73], v[198:201], v[190:193], v[70:73]
	v_mfma_f32_16x16x32_bf16 v[66:69], v[206:209], v[190:193], v[66:69]
	s_mov_b32 m0, s39
	s_mov_b64 s[100:101], s[92:93]
	s_barrier
	ds_read_b128 v[158:161], v171 offset:16384
	ds_read_b128 v[162:165], v171 offset:17408
	ds_read_b128 v[166:169], v171 offset:18432
	ds_read_b128 v[172:175], v171 offset:19456
	ds_read_b128 v[176:179], v171 offset:20480
	ds_read_b128 v[180:183], v171 offset:21504
	ds_read_b128 v[184:187], v171 offset:22528
	global_load_lds_dwordx4 v146, s[100:101]
	s_mov_b32 m0, s42
	ds_read_b128 v[190:193], v171 offset:23552
	global_load_lds_dwordx4 v150, s[100:101]
	s_waitcnt vmcnt(10)
	s_barrier
	s_waitcnt lgkmcnt(0)
	v_mfma_f32_16x16x32_bf16 v[62:65], v[130:133], v[158:161], v[62:65]
	v_mfma_f32_16x16x32_bf16 v[58:61], v[138:141], v[158:161], v[58:61]
	v_mfma_f32_16x16x32_bf16 v[46:49], v[130:133], v[166:169], v[46:49]
	v_mfma_f32_16x16x32_bf16 v[42:45], v[138:141], v[166:169], v[42:45]
	v_mfma_f32_16x16x32_bf16 v[30:33], v[130:133], v[176:179], v[30:33]
	v_mfma_f32_16x16x32_bf16 v[26:29], v[138:141], v[176:179], v[26:29]
	v_mfma_f32_16x16x32_bf16 v[14:17], v[130:133], v[184:187], v[14:17]
	v_mfma_f32_16x16x32_bf16 v[10:13], v[138:141], v[184:187], v[10:13]
	v_mfma_f32_16x16x32_bf16 v[62:65], v[134:137], v[162:165], v[62:65]
	s_add_u32 s94, s90, 0x40000
	s_addc_u32 s95, s91, 0
	v_mfma_f32_16x16x32_bf16 v[58:61], v[142:145], v[162:165], v[58:61]
	s_add_i32 m0, s38, 0x14000
	v_mfma_f32_16x16x32_bf16 v[46:49], v[134:137], v[172:175], v[46:49]
	v_mfma_f32_16x16x32_bf16 v[42:45], v[142:145], v[172:175], v[42:45]
	v_mfma_f32_16x16x32_bf16 v[30:33], v[134:137], v[180:183], v[30:33]
	v_mfma_f32_16x16x32_bf16 v[26:29], v[142:145], v[180:183], v[26:29]
	v_mfma_f32_16x16x32_bf16 v[14:17], v[134:137], v[190:193], v[14:17]
	v_mfma_f32_16x16x32_bf16 v[10:13], v[142:145], v[190:193], v[10:13]
	s_barrier
	s_nop 0
	global_load_lds_dwordx4 v148, s[94:95]
	s_add_i32 m0, s38, 0x16000
	s_nop 0
	global_load_lds_dwordx4 v152, s[94:95]
	ds_read_b128 v[130:133], v189 offset:32768
	ds_read_b128 v[134:137], v189 offset:33792
	ds_read_b128 v[138:141], v189 offset:34816
	ds_read_b128 v[142:145], v189 offset:35840
	s_waitcnt vmcnt(6)
	s_barrier
	v_mfma_f32_16x16x32_bf16 v[54:57], v[194:197], v[158:161], v[54:57]
	v_mfma_f32_16x16x32_bf16 v[50:53], v[202:205], v[158:161], v[50:53]
	v_mfma_f32_16x16x32_bf16 v[38:41], v[194:197], v[166:169], v[38:41]
	v_mfma_f32_16x16x32_bf16 v[34:37], v[202:205], v[166:169], v[34:37]
	v_mfma_f32_16x16x32_bf16 v[22:25], v[194:197], v[176:179], v[22:25]
	v_mfma_f32_16x16x32_bf16 v[18:21], v[202:205], v[176:179], v[18:21]
	v_mfma_f32_16x16x32_bf16 v[6:9], v[194:197], v[184:187], v[6:9]
	v_mfma_f32_16x16x32_bf16 v[2:5], v[202:205], v[184:187], v[2:5]
	v_mfma_f32_16x16x32_bf16 v[54:57], v[198:201], v[162:165], v[54:57]
	s_add_u32 s92, s92, 0x40000
	s_addc_u32 s93, s93, 0
	v_mfma_f32_16x16x32_bf16 v[50:53], v[206:209], v[162:165], v[50:53]
	s_mov_b32 m0, s43
	v_mfma_f32_16x16x32_bf16 v[38:41], v[198:201], v[172:175], v[38:41]
	v_mfma_f32_16x16x32_bf16 v[34:37], v[206:209], v[172:175], v[34:37]
	v_mfma_f32_16x16x32_bf16 v[22:25], v[198:201], v[180:183], v[22:25]
	v_mfma_f32_16x16x32_bf16 v[18:21], v[206:209], v[180:183], v[18:21]
	v_mfma_f32_16x16x32_bf16 v[6:9], v[198:201], v[190:193], v[6:9]
	v_mfma_f32_16x16x32_bf16 v[2:5], v[206:209], v[190:193], v[2:5]
	s_barrier
	ds_read_b128 v[158:161], v171 offset:32768
	ds_read_b128 v[162:165], v171 offset:33792
	ds_read_b128 v[166:169], v171 offset:34816
	ds_read_b128 v[172:175], v171 offset:35840
	ds_read_b128 v[176:179], v171 offset:36864
	ds_read_b128 v[180:183], v171 offset:37888
	ds_read_b128 v[184:187], v171 offset:38912
	global_load_lds_dwordx4 v146, s[92:93]
	s_mov_b32 m0, s44
	ds_read_b128 v[190:193], v171 offset:39936
	global_load_lds_dwordx4 v150, s[92:93]
	s_waitcnt lgkmcnt(8)
	s_barrier
	s_waitcnt lgkmcnt(0)
	v_mfma_f32_16x16x32_bf16 v[126:129], v[130:133], v[158:161], v[126:129]
	v_mfma_f32_16x16x32_bf16 v[122:125], v[138:141], v[158:161], v[122:125]
	v_mfma_f32_16x16x32_bf16 v[110:113], v[130:133], v[166:169], v[110:113]
	v_mfma_f32_16x16x32_bf16 v[106:109], v[138:141], v[166:169], v[106:109]
	v_mfma_f32_16x16x32_bf16 v[94:97], v[130:133], v[176:179], v[94:97]
	v_mfma_f32_16x16x32_bf16 v[90:93], v[138:141], v[176:179], v[90:93]
	v_mfma_f32_16x16x32_bf16 v[78:81], v[130:133], v[184:187], v[78:81]
	v_mfma_f32_16x16x32_bf16 v[74:77], v[138:141], v[184:187], v[74:77]
	v_mfma_f32_16x16x32_bf16 v[126:129], v[134:137], v[162:165], v[126:129]
	s_add_i32 m0, s38, 0x18000
	v_mfma_f32_16x16x32_bf16 v[122:125], v[142:145], v[162:165], v[122:125]
	v_mfma_f32_16x16x32_bf16 v[110:113], v[134:137], v[172:175], v[110:113]
	v_mfma_f32_16x16x32_bf16 v[106:109], v[142:145], v[172:175], v[106:109]
	v_mfma_f32_16x16x32_bf16 v[94:97], v[134:137], v[180:183], v[94:97]
	v_mfma_f32_16x16x32_bf16 v[90:93], v[142:145], v[180:183], v[90:93]
	v_mfma_f32_16x16x32_bf16 v[78:81], v[134:137], v[190:193], v[78:81]
	v_mfma_f32_16x16x32_bf16 v[74:77], v[142:145], v[190:193], v[74:77]
	s_barrier
	ds_read_b128 v[194:197], v189 offset:49152
	ds_read_b128 v[198:201], v189 offset:50176
	ds_read_b128 v[202:205], v189 offset:51200
	ds_read_b128 v[206:209], v189 offset:52224
	s_add_u32 s98, s90, s40
	s_addc_u32 s99, s91, s41
	global_load_lds_dwordx4 v148, s[98:99]
	s_add_i32 m0, s38, 0x1a000
	s_nop 0
	global_load_lds_dwordx4 v152, s[98:99]
	s_barrier
	s_waitcnt lgkmcnt(0)
	v_mfma_f32_16x16x32_bf16 v[118:121], v[194:197], v[158:161], v[118:121]
	v_mfma_f32_16x16x32_bf16 v[114:117], v[202:205], v[158:161], v[114:117]
	v_mfma_f32_16x16x32_bf16 v[102:105], v[194:197], v[166:169], v[102:105]
	v_mfma_f32_16x16x32_bf16 v[98:101], v[202:205], v[166:169], v[98:101]
	v_mfma_f32_16x16x32_bf16 v[86:89], v[194:197], v[176:179], v[86:89]
	v_mfma_f32_16x16x32_bf16 v[82:85], v[202:205], v[176:179], v[82:85]
	v_mfma_f32_16x16x32_bf16 v[70:73], v[194:197], v[184:187], v[70:73]
	v_mfma_f32_16x16x32_bf16 v[66:69], v[202:205], v[184:187], v[66:69]
	v_mfma_f32_16x16x32_bf16 v[118:121], v[198:201], v[162:165], v[118:121]
	v_mfma_f32_16x16x32_bf16 v[114:117], v[206:209], v[162:165], v[114:117]
	v_mfma_f32_16x16x32_bf16 v[102:105], v[198:201], v[172:175], v[102:105]
	v_mfma_f32_16x16x32_bf16 v[98:101], v[206:209], v[172:175], v[98:101]
	v_mfma_f32_16x16x32_bf16 v[86:89], v[198:201], v[180:183], v[86:89]
	v_mfma_f32_16x16x32_bf16 v[82:85], v[206:209], v[180:183], v[82:85]
	v_mfma_f32_16x16x32_bf16 v[70:73], v[198:201], v[190:193], v[70:73]
	v_mfma_f32_16x16x32_bf16 v[66:69], v[206:209], v[190:193], v[66:69]
	s_mov_b32 m0, s60
	s_barrier
	ds_read_b128 v[158:161], v171 offset:49152
	ds_read_b128 v[162:165], v171 offset:50176
	ds_read_b128 v[166:169], v171 offset:51200
	ds_read_b128 v[172:175], v171 offset:52224
	ds_read_b128 v[176:179], v171 offset:53248
	ds_read_b128 v[180:183], v171 offset:54272
	ds_read_b128 v[184:187], v171 offset:55296
	ds_read_b128 v[190:193], v171 offset:56320
	s_add_u32 s98, s100, s40
	s_addc_u32 s99, s101, s41
	global_load_lds_dwordx4 v146, s[98:99]
	s_mov_b32 m0, s61
	s_nop 0
	global_load_lds_dwordx4 v150, s[98:99]
	s_waitcnt vmcnt(10)
	s_barrier
	s_waitcnt lgkmcnt(0)
	v_mfma_f32_16x16x32_bf16 v[62:65], v[130:133], v[158:161], v[62:65]
	v_mfma_f32_16x16x32_bf16 v[58:61], v[138:141], v[158:161], v[58:61]
	v_mfma_f32_16x16x32_bf16 v[46:49], v[130:133], v[166:169], v[46:49]
	v_mfma_f32_16x16x32_bf16 v[42:45], v[138:141], v[166:169], v[42:45]
	v_mfma_f32_16x16x32_bf16 v[30:33], v[130:133], v[176:179], v[30:33]
	v_mfma_f32_16x16x32_bf16 v[26:29], v[138:141], v[176:179], v[26:29]
	v_mfma_f32_16x16x32_bf16 v[14:17], v[130:133], v[184:187], v[14:17]
	v_mfma_f32_16x16x32_bf16 v[10:13], v[138:141], v[184:187], v[10:13]
	v_mfma_f32_16x16x32_bf16 v[62:65], v[134:137], v[162:165], v[62:65]
	s_add_u32 s90, s90, 0x40080
	s_addc_u32 s91, s91, 0
	v_mfma_f32_16x16x32_bf16 v[58:61], v[142:145], v[162:165], v[58:61]
	s_add_i32 m0, s38, 0x1c000
	v_mfma_f32_16x16x32_bf16 v[46:49], v[134:137], v[172:175], v[46:49]
	v_mfma_f32_16x16x32_bf16 v[42:45], v[142:145], v[172:175], v[42:45]
	v_mfma_f32_16x16x32_bf16 v[30:33], v[134:137], v[180:183], v[30:33]
	v_mfma_f32_16x16x32_bf16 v[26:29], v[142:145], v[180:183], v[26:29]
	v_mfma_f32_16x16x32_bf16 v[14:17], v[134:137], v[190:193], v[14:17]
	v_mfma_f32_16x16x32_bf16 v[10:13], v[142:145], v[190:193], v[10:13]
	s_barrier
	s_nop 0
	global_load_lds_dwordx4 v148, s[90:91]
	s_add_i32 m0, s38, 0x1e000
	s_nop 0
	global_load_lds_dwordx4 v152, s[90:91]
	ds_read_b128 v[130:133], v189
	ds_read_b128 v[134:137], v189 offset:1024
	ds_read_b128 v[138:141], v189 offset:2048
	ds_read_b128 v[142:145], v189 offset:3072
	s_waitcnt vmcnt(6)
	s_barrier
	v_mfma_f32_16x16x32_bf16 v[54:57], v[194:197], v[158:161], v[54:57]
	v_mfma_f32_16x16x32_bf16 v[50:53], v[202:205], v[158:161], v[50:53]
	v_mfma_f32_16x16x32_bf16 v[38:41], v[194:197], v[166:169], v[38:41]
	v_mfma_f32_16x16x32_bf16 v[34:37], v[202:205], v[166:169], v[34:37]
	v_mfma_f32_16x16x32_bf16 v[22:25], v[194:197], v[176:179], v[22:25]
	v_mfma_f32_16x16x32_bf16 v[18:21], v[202:205], v[176:179], v[18:21]
	v_mfma_f32_16x16x32_bf16 v[6:9], v[194:197], v[184:187], v[6:9]
	v_mfma_f32_16x16x32_bf16 v[2:5], v[202:205], v[184:187], v[2:5]
	v_mfma_f32_16x16x32_bf16 v[54:57], v[198:201], v[162:165], v[54:57]
	s_add_i32 s85, s85, 2
	s_add_u32 s88, s88, 0x100
	v_mfma_f32_16x16x32_bf16 v[50:53], v[206:209], v[162:165], v[50:53]
	s_addc_u32 s89, s89, 0
	s_add_u32 s34, s34, 0x100
	v_mfma_f32_16x16x32_bf16 v[38:41], v[198:201], v[172:175], v[38:41]
	s_addc_u32 s79, s79, 0
	s_add_u32 s87, s88, 0xfffc0080
	v_mfma_f32_16x16x32_bf16 v[34:37], v[206:209], v[172:175], v[34:37]
	s_addc_u32 s90, s89, -1
	s_cmp_eq_u32 s85, 12
	v_mfma_f32_16x16x32_bf16 v[22:25], v[198:201], v[180:183], v[22:25]
	s_cselect_b32 s93, s13, s90
	s_cselect_b32 s92, s22, s87
	v_mfma_f32_16x16x32_bf16 v[18:21], v[206:209], v[180:183], v[18:21]
	s_cselect_b32 s91, s7, s79
	s_cselect_b32 s90, s23, s34
	v_mfma_f32_16x16x32_bf16 v[6:9], v[198:201], v[190:193], v[6:9]
	s_cmp_gt_u32 s85, 13
	v_mfma_f32_16x16x32_bf16 v[2:5], v[206:209], v[190:193], v[2:5]
	s_barrier
	s_cbranch_scc0 .LBB0_1209
	s_waitcnt lgkmcnt(0)
	v_mov_b32_e32 v131, v252
	s_lshl_b32 s7, s86, 8
	v_and_b32_e32 v130, 63, v131
	v_or_b32_e32 v0, s72, v130
	v_lshrrev_b32_e32 v0, 1, v0
	v_and_or_b32 v132, v0, 63, s73
	v_add_u32_e32 v134, s7, v132
	v_ashrrev_i32_e32 v135, 31, v134
	v_and_b32_e32 v142, 1, v131
	v_lshlrev_b64 v[134:135], 6, v[134:135]
	v_lshl_add_u64 v[134:135], s[82:83], 0, v[134:135]
	v_lshlrev_b32_e32 v0, 5, v142
	v_lshl_add_u64 v[138:139], v[134:135], 0, v[0:1]
	global_load_dwordx4 v[134:137], v[138:139], off
	s_nop 0
	global_load_dwordx4 v[138:141], v[138:139], off offset:16
	v_lshlrev_b32_e32 v0, 2, v130
	v_cmp_eq_u32_e32 vcc, 0, v142
	s_waitcnt vmcnt(0)
	v_add_f32_e32 v133, v134, v135
	v_add_f32_e32 v134, v136, v137
	v_add_f32_e32 v135, v138, v139
	v_add_f32_e32 v136, v140, v141
	v_add_f32_e32 v133, v133, v134
	v_add_f32_e32 v134, v135, v136
	v_add_f32_e32 v133, v133, v134
	v_xor_b32_e32 v134, 4, v0
	ds_bpermute_b32 v134, v134, v133
	s_and_saveexec_b64 s[22:23], vcc
	s_cbranch_execz .LBB0_1212
	s_waitcnt lgkmcnt(0)
	v_add_f32_e32 v133, v133, v134
	v_fmamk_f32 v133, v133, 0x3a800000, v224
	s_mov_b32 s13, 0x800000
	v_mul_f32_e32 v134, 0x4b800000, v133
	v_cmp_gt_f32_e32 vcc, s13, v133
	v_lshl_add_u32 v132, v132, 2, 0
	v_add_u32_e32 v132, 0x20000, v132
	v_cndmask_b32_e32 v133, v133, v134, vcc
	v_rsq_f32_e32 v133, v133
	s_nop 0
	v_mul_f32_e32 v134, 0x45800000, v133
	v_cndmask_b32_e32 v133, v133, v134, vcc
	ds_write_b32 v132, v133
